# v9 + gridDim kept in s100 (no per-tile scalar load), win/kvq epilogue loads hoisted
# speedup vs baseline: 1.0425x; 1.0058x over previous
.LBB0_20:
	v_readlane_b32 s0, v251, 0
	v_readlane_b32 s1, v251, 1
	s_load_dword s81, s[0:1], 0x124
	s_waitcnt lgkmcnt(0)
	s_cmp_ge_i32 s33, s81
	s_cbranch_scc1 .LBB0_714
	s_cmpk_lt_i32 s14, 0xb00
	s_cselect_b64 s[0:1], -1, 0
	v_writelane_b32 v251, s0, 8
	s_mov_b32 s87, 0
	s_mov_b32 s15, s87
	v_writelane_b32 v251, s1, 9
	v_lshrrev_b32_e32 v1, 20, v0
	v_readlane_b32 s0, v251, 0
	v_readlane_b32 s1, v251, 1
	s_add_u32 s74, s0, 0x130
	s_addc_u32 s75, s1, 0
	s_load_dword s100, s[74:75], 0x0
	s_waitcnt lgkmcnt(0)
	s_cmp_lt_i32 s14, 44
	s_cselect_b64 s[2:3], -1, 0
	v_writelane_b32 v251, s2, 10
	v_lshrrev_b32_e32 v0, 10, v0
	v_or_b32_e32 v0, v0, v1
	v_writelane_b32 v251, s3, 11
	s_not_b32 s2, s14
	s_cmpk_lt_i32 s14, 0x400
	v_writelane_b32 v251, s2, 12
	s_cselect_b64 s[2:3], -1, 0
	v_writelane_b32 v251, s2, 13
	s_cmpk_lt_i32 s14, 0x200
	s_load_dwordx2 s[0:1], s[0:1], 0x110
	v_writelane_b32 v251, s3, 14
	s_cselect_b64 s[2:3], -1, 0
	v_writelane_b32 v251, s2, 15
	s_cmpk_lt_i32 s14, 0x800
	v_mov_b32_e32 v1, 0
	v_writelane_b32 v251, s3, 16
	s_cselect_b64 s[2:3], -1, 0
	v_writelane_b32 v251, s2, 17
	s_cmpk_lt_i32 s14, 0x100
	v_mbcnt_lo_u32_b32 v2, -1, 0
	v_writelane_b32 v251, s3, 18
	s_cselect_b64 s[2:3], -1, 0
	v_writelane_b32 v251, s2, 19
	s_ashr_i32 s31, s14, 31
	s_movk_i32 s82, 0xf000
	v_writelane_b32 v251, s3, 20
	s_lshr_b32 s2, s31, 28
	s_add_i32 s2, s14, s2
	s_and_b32 s3, s2, 0x3fffff0
	s_sub_i32 s3, s14, s3
	s_lshl_b32 s3, s3, 6
	s_lshl_b32 s2, s2, 2
	v_writelane_b32 v251, s3, 21
	s_andn2_b32 s2, s2, 63
	v_writelane_b32 v251, s2, 22
	s_lshl_b32 s2, s14, 9
	v_writelane_b32 v251, s2, 23
	s_lshl_b32 s2, s14, 3
	v_writelane_b32 v251, s2, 24
	s_lshl_b64 s[2:3], s[14:15], 9
	v_writelane_b32 v251, s2, 25
	s_cmp_eq_u32 s14, 0
	v_mov_b32_e32 v177, 0x358637bd
	v_writelane_b32 v251, s3, 26
	s_cselect_b64 s[2:3], -1, 0
	v_writelane_b32 v251, s2, 27
	s_cmp_lt_i32 s14, 64
	v_mov_b32_e32 v178, 0xc0135761
	v_writelane_b32 v251, s3, 28
	s_cselect_b64 s[2:3], -1, 0
	v_writelane_b32 v251, s2, 29
	s_cmp_eq_u32 s19, 2
	v_mbcnt_hi_u32_b32 v179, -1, v2
	v_writelane_b32 v251, s3, 30
	s_cselect_b64 s[2:3], -1, 0
	v_writelane_b32 v251, s2, 31
	v_mov_b32_e32 v180, 0x260
	v_mov_b32_e32 v181, 1.0
	v_writelane_b32 v251, s3, 32
	s_movk_i32 s2, 0x3ff
	v_readlane_b32 s4, v251, 4
	v_and_or_b32 v0, v0, s2, v176
	v_readlane_b32 s5, v251, 5
	s_add_u32 s2, s4, 0x2dc0200
	s_addc_u32 s3, s5, 0
	v_writelane_b32 v251, s2, 33
	v_mov_b32_e32 v182, 1
	v_mov_b32_e32 v183, 0x3f0e59d5
	v_writelane_b32 v251, s3, 34
	s_add_u32 s2, s4, 0x2dc0400
	s_addc_u32 s3, s5, 0
	v_writelane_b32 v251, s2, 35
	v_mov_b32_e32 v184, 0x3ef1014c
	v_mov_b32_e32 v185, 0x7f800000
	v_writelane_b32 v251, s3, 36
	s_add_u32 s2, s4, 0x2dc0500
	s_addc_u32 s3, s5, 0
	v_writelane_b32 v251, s2, 37
	v_mov_b32_e32 v186, 0x80
	v_mov_b32_e32 v187, 0x3e38aa3b
	v_writelane_b32 v251, s3, 38
	s_add_u32 s2, s4, 0x2dc0600
	s_addc_u32 s3, s5, 0
	v_writelane_b32 v251, s2, 39
	v_mov_b32_e32 v220, v1
	v_mov_b32_e32 v221, v1
	v_writelane_b32 v251, s3, 40
	s_add_u32 s2, s4, 0x2dc0700
	s_addc_u32 s3, s5, 0
	v_writelane_b32 v251, s2, 41
	v_mov_b32_e32 v188, 0x100000
	s_movk_i32 s69, 0x400
	v_writelane_b32 v251, s3, 42
	s_add_u32 s2, s4, 0x2dc0800
	s_addc_u32 s3, s5, 0
	v_writelane_b32 v251, s2, 43
	s_movk_i32 s26, 0x5800
	s_mov_b32 s34, 0x800000
	v_writelane_b32 v251, s3, 44
	s_add_u32 s2, s4, 0x2dc0900
	s_addc_u32 s3, s5, 0
	v_writelane_b32 v251, s2, 45
	s_mov_b32 s35, 0x4b800000
	s_movk_i32 s36, 0x7fff
	v_writelane_b32 v251, s3, 46
	s_add_u32 s2, s4, 0x2dc0a00
	s_addc_u32 s3, s5, 0
	v_writelane_b32 v251, s2, 47
	s_mov_b32 s37, 0x13e04000
	s_movk_i32 s38, 0x180
	v_writelane_b32 v251, s3, 48
	s_add_u32 s2, s4, 0x2dc0b00
	s_addc_u32 s3, s5, 0
	v_writelane_b32 v251, s2, 49
	s_mov_b32 s83, -1
	s_mov_b32 s64, 0x3f803f80
	v_writelane_b32 v251, s3, 50
	s_add_u32 s2, s4, 0x2dc0c00
	s_addc_u32 s3, s5, 0
	v_writelane_b32 v251, s2, 51
	s_nop 1
	v_writelane_b32 v251, s3, 52
	s_add_u32 s2, s4, 0x2dc0d00
	s_addc_u32 s3, s5, 0
	v_writelane_b32 v251, s2, 53
	s_nop 1
	v_writelane_b32 v251, s3, 54
	s_add_u32 s2, s4, 0x2dc0e00
	s_addc_u32 s3, s5, 0
	v_writelane_b32 v251, s2, 55
	s_nop 1
	v_writelane_b32 v251, s3, 56
	s_add_u32 s2, s4, 0x2dc0f00
	s_addc_u32 s3, s5, 0
	v_writelane_b32 v251, s2, 57
	s_nop 1
	v_writelane_b32 v251, s3, 58
	s_add_u32 s2, s4, 0x2dc1000
	s_addc_u32 s3, s5, 0
	v_writelane_b32 v251, s2, 59
	s_nop 1
	v_writelane_b32 v251, s3, 60
	s_add_u32 s2, s4, 0x2dc1100
	s_addc_u32 s3, s5, 0
	v_writelane_b32 v251, s2, 61
	s_nop 1
	v_writelane_b32 v251, s3, 62
	s_add_u32 s2, s4, 0x2dc1200
	s_addc_u32 s3, s5, 0
	v_writelane_b32 v251, s2, 63
	s_nop 1
	v_writelane_b32 v250, s3, 0
	s_add_u32 s2, s4, 0x2dc1300
	s_addc_u32 s3, s5, 0
	v_writelane_b32 v250, s2, 1
	s_cmp_eq_u32 s18, 15
	s_nop 0
	v_writelane_b32 v250, s3, 2
	s_cselect_b64 s[2:3], -1, 0
	v_writelane_b32 v250, s2, 3
	s_cmp_eq_u32 s18, 14
	s_nop 0
	v_writelane_b32 v250, s3, 4
	s_cselect_b64 s[2:3], -1, 0
	v_writelane_b32 v250, s2, 5
	s_cmp_eq_u32 s18, 13
	s_nop 0
	v_writelane_b32 v250, s3, 6
	s_cselect_b64 s[2:3], -1, 0
	v_writelane_b32 v250, s2, 7
	s_cmp_eq_u32 s18, 12
	s_nop 0
	v_writelane_b32 v250, s3, 8
	s_cselect_b64 s[2:3], -1, 0
	v_writelane_b32 v250, s2, 9
	s_cmp_eq_u32 s18, 11
	s_nop 0
	v_writelane_b32 v250, s3, 10
	s_cselect_b64 s[2:3], -1, 0
	v_writelane_b32 v250, s2, 11
	s_cmp_eq_u32 s18, 10
	s_nop 0
	v_writelane_b32 v250, s3, 12
	s_cselect_b64 s[2:3], -1, 0
	v_writelane_b32 v250, s2, 13
	s_cmp_eq_u32 s18, 9
	s_nop 0
	v_writelane_b32 v250, s3, 14
	s_cselect_b64 s[2:3], -1, 0
	v_writelane_b32 v250, s2, 15
	s_cmp_eq_u32 s18, 8
	s_nop 0
	v_writelane_b32 v250, s3, 16
	s_cselect_b64 s[2:3], -1, 0
	v_writelane_b32 v250, s2, 17
	s_cmp_eq_u32 s18, 7
	s_nop 0
	v_writelane_b32 v250, s3, 18
	s_cselect_b64 s[2:3], -1, 0
	v_writelane_b32 v250, s2, 19
	s_cmp_eq_u32 s18, 6
	s_nop 0
	v_writelane_b32 v250, s3, 20
	s_cselect_b64 s[2:3], -1, 0
	v_writelane_b32 v250, s2, 21
	s_cmp_eq_u32 s18, 5
	s_nop 0
	v_writelane_b32 v250, s3, 22
	s_cselect_b64 s[2:3], -1, 0
	v_writelane_b32 v250, s2, 23
	s_cmp_eq_u32 s18, 4
	s_nop 0
	v_writelane_b32 v250, s3, 24
	s_cselect_b64 s[2:3], -1, 0
	v_writelane_b32 v250, s2, 25
	s_cmp_eq_u32 s18, 3
	s_nop 0
	v_writelane_b32 v250, s3, 26
	s_cselect_b64 s[2:3], -1, 0
	v_writelane_b32 v250, s2, 27
	s_cmp_eq_u32 s18, 2
	s_nop 0
	v_writelane_b32 v250, s3, 28
	s_cselect_b64 s[2:3], -1, 0
	v_writelane_b32 v250, s2, 29
	s_cmp_eq_u32 s18, 1
	s_nop 0
	v_writelane_b32 v250, s3, 30
	s_cselect_b64 s[2:3], -1, 0
	v_writelane_b32 v250, s2, 31
	s_cmp_eq_u32 s18, 0
	s_nop 0
	v_writelane_b32 v250, s3, 32
	s_cselect_b64 s[2:3], -1, 0
	v_writelane_b32 v250, s2, 33
	s_nop 1
	v_writelane_b32 v250, s3, 34
	s_lshl_b32 s2, s18, 8
	s_add_u32 s2, s4, s2
	s_addc_u32 s3, s5, 0
	s_add_u32 s6, s2, 0x2dc1400
	s_addc_u32 s7, s3, 0
	v_writelane_b32 v250, s6, 35
	s_add_u32 s2, s2, 0x2dc2400
	s_addc_u32 s3, s3, 0
	v_writelane_b32 v250, s7, 36
	v_writelane_b32 v250, s2, 37
	s_nop 1
	v_writelane_b32 v250, s3, 38
	s_add_u32 s2, s4, 0x2dc3400
	s_addc_u32 s3, s5, 0
	v_writelane_b32 v250, s2, 39
	s_nop 1
	v_writelane_b32 v250, s3, 40
	s_add_u32 s2, s4, 0x2dc3500
	s_addc_u32 s3, s5, 0
	v_writelane_b32 v250, s2, 41
	s_abs_i32 s28, s14
	s_nop 0
	v_writelane_b32 v250, s3, 42
	s_add_u32 s2, s4, 0x13e00080
	v_writelane_b32 v250, s2, 43
	s_addc_u32 s2, s5, 0
	v_writelane_b32 v250, s2, 44
	s_lshl_b32 s2, s14, 6
	v_writelane_b32 v250, s2, 45
	s_lshl_b64 s[2:3], s[14:15], 13
	s_add_u32 s2, s4, s2
	s_addc_u32 s3, s5, s3
	s_add_u32 s2, s2, 0x2e00000
	v_writelane_b32 v250, s2, 46
	s_addc_u32 s2, s3, 0
	v_writelane_b32 v250, s2, 47
	s_lshl_b64 s[2:3], s[14:15], 14
	s_or_b32 s2, s2, 16
	v_writelane_b32 v250, s2, 48
	s_nop 1
	v_writelane_b32 v250, s3, 49
	s_add_u32 s2, s4, 0x2e00000
	v_writelane_b32 v250, s2, 50
	s_addc_u32 s2, s5, 0
	v_writelane_b32 v250, s2, 51
	s_lshl_b32 s2, s14, 10
	v_writelane_b32 v250, s2, 52
	s_add_i32 s2, 0, 0x21fc0
	v_writelane_b32 v250, s2, 53
	s_add_i32 s2, 0, 0x21fc4
	v_writelane_b32 v250, s2, 54
	s_waitcnt lgkmcnt(0)
	v_writelane_b32 v250, s0, 55
	s_nop 1
	v_writelane_b32 v250, s1, 56
	v_cmp_eq_u32_e64 s[0:1], 0, v0
	s_nop 1
	v_writelane_b32 v250, s0, 57
	s_nop 1
	v_writelane_b32 v250, s1, 58
	s_branch .LBB0_25

.LBB0_38:
	s_mov_b32 s99, s100
	v_lshl_or_b32 v202, s18, 7, v135
	v_ashrrev_i32_e32 v203, 31, v202
	v_lshlrev_b64 v[202:203], 2, v[202:203]
	v_lshl_add_u64 v[204:205], s[56:57], 0, v[202:203]
	v_lshl_add_u64 v[206:207], s[62:63], 0, v[202:203]
	global_load_dwordx4 v[156:159], v[204:205], off
	global_load_dwordx4 v[160:163], v[206:207], off
	v_lshl_add_u64 v[204:205], s[66:67], 0, v[202:203]
	v_lshl_add_u64 v[206:207], s[78:79], 0, v[202:203]
	global_load_dwordx4 v[164:167], v[204:205], off
	global_load_dwordx4 v[168:171], v[206:207], off
	v_lshl_add_u64 v[204:205], s[88:89], 0, v[202:203]
	v_lshl_add_u64 v[206:207], s[90:91], 0, v[202:203]
	global_load_dwordx4 v[172:175], v[204:205], off
	global_load_dwordx4 v[190:193], v[206:207], off
	v_lshl_add_u64 v[204:205], s[58:59], 0, v[202:203]
	v_lshl_add_u64 v[206:207], s[60:61], 0, v[202:203]
	global_load_dwordx4 v[194:197], v[204:205], off
	global_load_dwordx4 v[198:201], v[206:207], off
	v_mov_b32_e32 v140, v130
	v_mov_b32_e32 v141, v131
	s_cmp_eq_u32 s17, 0
	v_add_u32_e32 v141, v141, v132
	v_mov_b32_e32 v142, v224
	v_mov_b32_e32 v143, v225
	v_lshlrev_b32_e32 v140, 4, v140
	v_ffbh_u32_e32 v144, v143
	v_min_u32_e32 v144, 32, v144
	v_lshlrev_b64 v[142:143], v144, v[142:143]
	v_min_u32_e32 v142, 1, v142
	v_or_b32_e32 v142, v143, v142
	v_cvt_f32_u32_e32 v142, v142
	v_sub_u32_e32 v143, 32, v144
	v_ldexp_f32 v142, v142, v143
	v_fmamk_f32 v142, v142, 0x2e800000, v177
	v_cmp_gt_f32_e32 vcc, s34, v142
	v_mul_f32_e32 v143, 0x4b800000, v142
	s_nop 0
	v_cndmask_b32_e32 v142, v142, v143, vcc
	v_rsq_f32_e32 v142, v142
	s_nop 0
	v_mul_f32_e32 v143, 0x45800000, v142
	v_cndmask_b32_e32 v142, v142, v143, vcc
	v_mul_u32_u24_e32 v143, 0x210, v141
	v_add3_u32 v143, v138, v143, v140
	v_pk_mul_f32 v[128:129], v[128:129], v[142:143] op_sel_hi:[1,0]
	v_pk_mul_f32 v[126:127], v[126:127], v[142:143] op_sel_hi:[1,0]
	v_pk_mul_f32 v[144:145], v[124:125], v[142:143] op_sel_hi:[1,0]
	v_pk_mul_f32 v[124:125], v[122:123], v[142:143] op_sel_hi:[1,0]
	v_cvt_pk_bf16_f32 v122, v126, v127
	v_cvt_pk_bf16_f32 v123, v128, v129
	v_cvt_pk_bf16_f32 v124, v124, v125
	v_cvt_pk_bf16_f32 v125, v144, v145
	ds_write_b128 v143, v[122:125] offset:2080
	v_pk_mul_f32 v[120:121], v[120:121], v[142:143] op_sel_hi:[1,0]
	v_pk_mul_f32 v[118:119], v[118:119], v[142:143] op_sel_hi:[1,0]
	v_pk_mul_f32 v[122:123], v[116:117], v[142:143] op_sel_hi:[1,0]
	v_pk_mul_f32 v[116:117], v[114:115], v[142:143] op_sel_hi:[1,0]
	v_cvt_pk_bf16_f32 v114, v118, v119
	v_cvt_pk_bf16_f32 v115, v120, v121
	v_cvt_pk_bf16_f32 v116, v116, v117
	v_cvt_pk_bf16_f32 v117, v122, v123
	ds_write_b128 v143, v[114:117] offset:2144
	v_add_u32_e32 v116, 16, v141
	v_mov_b32_e32 v114, v226
	v_mov_b32_e32 v115, v227
	v_ffbh_u32_e32 v117, v115
	v_min_u32_e32 v117, 32, v117
	v_lshlrev_b64 v[114:115], v117, v[114:115]
	v_min_u32_e32 v114, 1, v114
	v_or_b32_e32 v114, v115, v114
	v_cvt_f32_u32_e32 v114, v114
	v_sub_u32_e32 v115, 32, v117
	v_ldexp_f32 v114, v114, v115
	v_fmamk_f32 v114, v114, 0x2e800000, v177
	v_cmp_gt_f32_e32 vcc, s34, v114
	v_mul_f32_e32 v115, 0x4b800000, v114
	s_nop 0
	v_cndmask_b32_e32 v114, v114, v115, vcc
	v_rsq_f32_e32 v114, v114
	s_nop 0
	v_mul_f32_e32 v115, 0x45800000, v114
	v_cndmask_b32_e32 v114, v114, v115, vcc
	v_mul_u32_u24_e32 v115, 0x210, v116
	v_add3_u32 v115, v138, v115, v140
	v_pk_mul_f32 v[112:113], v[112:113], v[114:115] op_sel_hi:[1,0]
	v_pk_mul_f32 v[110:111], v[110:111], v[114:115] op_sel_hi:[1,0]
	v_pk_mul_f32 v[116:117], v[108:109], v[114:115] op_sel_hi:[1,0]
	v_pk_mul_f32 v[108:109], v[106:107], v[114:115] op_sel_hi:[1,0]
	v_cvt_pk_bf16_f32 v106, v110, v111
	v_cvt_pk_bf16_f32 v107, v112, v113
	v_cvt_pk_bf16_f32 v108, v108, v109
	v_cvt_pk_bf16_f32 v109, v116, v117
	ds_write_b128 v115, v[106:109] offset:2080
	v_pk_mul_f32 v[104:105], v[104:105], v[114:115] op_sel_hi:[1,0]
	v_pk_mul_f32 v[102:103], v[102:103], v[114:115] op_sel_hi:[1,0]
	v_pk_mul_f32 v[106:107], v[100:101], v[114:115] op_sel_hi:[1,0]
	v_pk_mul_f32 v[100:101], v[98:99], v[114:115] op_sel_hi:[1,0]
	v_cvt_pk_bf16_f32 v98, v102, v103
	v_cvt_pk_bf16_f32 v99, v104, v105
	v_cvt_pk_bf16_f32 v100, v100, v101
	v_cvt_pk_bf16_f32 v101, v106, v107
	ds_write_b128 v115, v[98:101] offset:2144
	v_add_u32_e32 v100, 32, v141
	v_mov_b32_e32 v98, v228
	v_mov_b32_e32 v99, v229
	v_ffbh_u32_e32 v101, v99
	v_min_u32_e32 v101, 32, v101
	v_lshlrev_b64 v[98:99], v101, v[98:99]
	v_min_u32_e32 v98, 1, v98
	v_or_b32_e32 v98, v99, v98
	v_cvt_f32_u32_e32 v98, v98
	v_sub_u32_e32 v99, 32, v101
	v_ldexp_f32 v98, v98, v99
	v_fmamk_f32 v98, v98, 0x2e800000, v177
	v_cmp_gt_f32_e32 vcc, s34, v98
	v_mul_f32_e32 v99, 0x4b800000, v98
	s_nop 0
	v_cndmask_b32_e32 v98, v98, v99, vcc
	v_rsq_f32_e32 v98, v98
	s_nop 0
	v_mul_f32_e32 v99, 0x45800000, v98
	v_cndmask_b32_e32 v98, v98, v99, vcc
	v_mul_u32_u24_e32 v99, 0x210, v100
	v_add3_u32 v99, v138, v99, v140
	v_pk_mul_f32 v[96:97], v[96:97], v[98:99] op_sel_hi:[1,0]
	v_pk_mul_f32 v[94:95], v[94:95], v[98:99] op_sel_hi:[1,0]
	v_pk_mul_f32 v[100:101], v[92:93], v[98:99] op_sel_hi:[1,0]
	v_pk_mul_f32 v[92:93], v[90:91], v[98:99] op_sel_hi:[1,0]
	v_cvt_pk_bf16_f32 v90, v94, v95
	v_cvt_pk_bf16_f32 v91, v96, v97
	v_cvt_pk_bf16_f32 v92, v92, v93
	v_cvt_pk_bf16_f32 v93, v100, v101
	ds_write_b128 v99, v[90:93] offset:2080
	v_pk_mul_f32 v[88:89], v[88:89], v[98:99] op_sel_hi:[1,0]
	v_pk_mul_f32 v[86:87], v[86:87], v[98:99] op_sel_hi:[1,0]
	v_pk_mul_f32 v[90:91], v[84:85], v[98:99] op_sel_hi:[1,0]
	v_pk_mul_f32 v[84:85], v[82:83], v[98:99] op_sel_hi:[1,0]
	v_cvt_pk_bf16_f32 v82, v86, v87
	v_cvt_pk_bf16_f32 v83, v88, v89
	v_cvt_pk_bf16_f32 v84, v84, v85
	v_cvt_pk_bf16_f32 v85, v90, v91
	ds_write_b128 v99, v[82:85] offset:2144
	v_add_u32_e32 v84, 48, v141
	v_mov_b32_e32 v82, v230
	v_mov_b32_e32 v83, v231
	v_ffbh_u32_e32 v85, v83
	v_min_u32_e32 v85, 32, v85
	v_lshlrev_b64 v[82:83], v85, v[82:83]
	v_min_u32_e32 v82, 1, v82
	v_or_b32_e32 v82, v83, v82
	v_cvt_f32_u32_e32 v82, v82
	v_sub_u32_e32 v83, 32, v85
	v_ldexp_f32 v82, v82, v83
	v_fmamk_f32 v82, v82, 0x2e800000, v177
	v_cmp_gt_f32_e32 vcc, s34, v82
	v_mul_f32_e32 v83, 0x4b800000, v82
	s_nop 0
	v_cndmask_b32_e32 v82, v82, v83, vcc
	v_rsq_f32_e32 v82, v82
	s_nop 0
	v_mul_f32_e32 v83, 0x45800000, v82
	v_cndmask_b32_e32 v82, v82, v83, vcc
	v_mul_u32_u24_e32 v83, 0x210, v84
	v_add3_u32 v83, v138, v83, v140
	v_pk_mul_f32 v[80:81], v[80:81], v[82:83] op_sel_hi:[1,0]
	v_pk_mul_f32 v[78:79], v[78:79], v[82:83] op_sel_hi:[1,0]
	v_pk_mul_f32 v[84:85], v[76:77], v[82:83] op_sel_hi:[1,0]
	v_pk_mul_f32 v[76:77], v[74:75], v[82:83] op_sel_hi:[1,0]
	v_cvt_pk_bf16_f32 v74, v78, v79
	v_cvt_pk_bf16_f32 v75, v80, v81
	v_cvt_pk_bf16_f32 v76, v76, v77
	v_cvt_pk_bf16_f32 v77, v84, v85
	ds_write_b128 v83, v[74:77] offset:2080
	v_pk_mul_f32 v[72:73], v[72:73], v[82:83] op_sel_hi:[1,0]
	v_pk_mul_f32 v[70:71], v[70:71], v[82:83] op_sel_hi:[1,0]
	v_pk_mul_f32 v[74:75], v[68:69], v[82:83] op_sel_hi:[1,0]
	v_pk_mul_f32 v[68:69], v[66:67], v[82:83] op_sel_hi:[1,0]
	v_cvt_pk_bf16_f32 v66, v70, v71
	v_cvt_pk_bf16_f32 v67, v72, v73
	v_cvt_pk_bf16_f32 v68, v68, v69
	v_cvt_pk_bf16_f32 v69, v74, v75
	ds_write_b128 v83, v[66:69] offset:2144
	v_add_u32_e32 v68, 64, v141
	v_mov_b32_e32 v66, v232
	v_mov_b32_e32 v67, v233
	v_ffbh_u32_e32 v69, v67
	v_min_u32_e32 v69, 32, v69
	v_lshlrev_b64 v[66:67], v69, v[66:67]
	v_min_u32_e32 v66, 1, v66
	v_or_b32_e32 v66, v67, v66
	v_cvt_f32_u32_e32 v66, v66
	v_sub_u32_e32 v67, 32, v69
	v_ldexp_f32 v66, v66, v67
	v_fmamk_f32 v66, v66, 0x2e800000, v177
	v_cmp_gt_f32_e32 vcc, s34, v66
	v_mul_f32_e32 v67, 0x4b800000, v66
	s_nop 0
	v_cndmask_b32_e32 v66, v66, v67, vcc
	v_rsq_f32_e32 v66, v66
	s_nop 0
	v_mul_f32_e32 v67, 0x45800000, v66
	v_cndmask_b32_e32 v66, v66, v67, vcc
	v_mul_u32_u24_e32 v67, 0x210, v68
	v_add3_u32 v67, v138, v67, v140
	v_pk_mul_f32 v[64:65], v[64:65], v[66:67] op_sel_hi:[1,0]
	v_pk_mul_f32 v[62:63], v[62:63], v[66:67] op_sel_hi:[1,0]
	v_pk_mul_f32 v[68:69], v[60:61], v[66:67] op_sel_hi:[1,0]
	v_pk_mul_f32 v[60:61], v[58:59], v[66:67] op_sel_hi:[1,0]
	v_cvt_pk_bf16_f32 v58, v62, v63
	v_cvt_pk_bf16_f32 v59, v64, v65
	v_cvt_pk_bf16_f32 v60, v60, v61
	v_cvt_pk_bf16_f32 v61, v68, v69
	ds_write_b128 v67, v[58:61] offset:2080
	v_pk_mul_f32 v[56:57], v[56:57], v[66:67] op_sel_hi:[1,0]
	v_pk_mul_f32 v[54:55], v[54:55], v[66:67] op_sel_hi:[1,0]
	v_pk_mul_f32 v[58:59], v[52:53], v[66:67] op_sel_hi:[1,0]
	v_pk_mul_f32 v[52:53], v[50:51], v[66:67] op_sel_hi:[1,0]
	v_cvt_pk_bf16_f32 v50, v54, v55
	v_cvt_pk_bf16_f32 v51, v56, v57
	v_cvt_pk_bf16_f32 v52, v52, v53
	v_cvt_pk_bf16_f32 v53, v58, v59
	ds_write_b128 v67, v[50:53] offset:2144
	v_add_u32_e32 v52, 0x50, v141
	v_mov_b32_e32 v50, v234
	v_mov_b32_e32 v51, v235
	v_ffbh_u32_e32 v53, v51
	v_min_u32_e32 v53, 32, v53
	v_lshlrev_b64 v[50:51], v53, v[50:51]
	v_min_u32_e32 v50, 1, v50
	v_or_b32_e32 v50, v51, v50
	v_cvt_f32_u32_e32 v50, v50
	v_sub_u32_e32 v51, 32, v53
	v_ldexp_f32 v50, v50, v51
	v_fmamk_f32 v50, v50, 0x2e800000, v177
	v_cmp_gt_f32_e32 vcc, s34, v50
	v_mul_f32_e32 v51, 0x4b800000, v50
	s_nop 0
	v_cndmask_b32_e32 v50, v50, v51, vcc
	v_rsq_f32_e32 v50, v50
	s_nop 0
	v_mul_f32_e32 v51, 0x45800000, v50
	v_cndmask_b32_e32 v50, v50, v51, vcc
	v_mul_u32_u24_e32 v51, 0x210, v52
	v_add3_u32 v51, v138, v51, v140
	v_pk_mul_f32 v[48:49], v[48:49], v[50:51] op_sel_hi:[1,0]
	v_pk_mul_f32 v[46:47], v[46:47], v[50:51] op_sel_hi:[1,0]
	v_pk_mul_f32 v[52:53], v[44:45], v[50:51] op_sel_hi:[1,0]
	v_pk_mul_f32 v[44:45], v[42:43], v[50:51] op_sel_hi:[1,0]
	v_cvt_pk_bf16_f32 v42, v46, v47
	v_cvt_pk_bf16_f32 v43, v48, v49
	v_cvt_pk_bf16_f32 v44, v44, v45
	v_cvt_pk_bf16_f32 v45, v52, v53
	ds_write_b128 v51, v[42:45] offset:2080
	v_pk_mul_f32 v[40:41], v[40:41], v[50:51] op_sel_hi:[1,0]
	v_pk_mul_f32 v[38:39], v[38:39], v[50:51] op_sel_hi:[1,0]
	v_pk_mul_f32 v[42:43], v[36:37], v[50:51] op_sel_hi:[1,0]
	v_pk_mul_f32 v[36:37], v[34:35], v[50:51] op_sel_hi:[1,0]
	v_cvt_pk_bf16_f32 v34, v38, v39
	v_cvt_pk_bf16_f32 v35, v40, v41
	v_cvt_pk_bf16_f32 v36, v36, v37
	v_cvt_pk_bf16_f32 v37, v42, v43
	ds_write_b128 v51, v[34:37] offset:2144
	v_add_u32_e32 v36, 0x60, v141
	v_mov_b32_e32 v34, v236
	v_mov_b32_e32 v35, v237
	v_ffbh_u32_e32 v37, v35
	v_min_u32_e32 v37, 32, v37
	v_lshlrev_b64 v[34:35], v37, v[34:35]
	v_min_u32_e32 v34, 1, v34
	v_or_b32_e32 v34, v35, v34
	v_cvt_f32_u32_e32 v34, v34
	v_sub_u32_e32 v35, 32, v37
	v_ldexp_f32 v34, v34, v35
	v_fmamk_f32 v34, v34, 0x2e800000, v177
	v_cmp_gt_f32_e32 vcc, s34, v34
	v_mul_f32_e32 v35, 0x4b800000, v34
	s_nop 0
	v_cndmask_b32_e32 v34, v34, v35, vcc
	v_rsq_f32_e32 v34, v34
	s_nop 0
	v_mul_f32_e32 v35, 0x45800000, v34
	v_cndmask_b32_e32 v34, v34, v35, vcc
	v_mul_u32_u24_e32 v35, 0x210, v36
	v_add3_u32 v35, v138, v35, v140
	v_pk_mul_f32 v[32:33], v[32:33], v[34:35] op_sel_hi:[1,0]
	v_pk_mul_f32 v[30:31], v[30:31], v[34:35] op_sel_hi:[1,0]
	v_pk_mul_f32 v[36:37], v[28:29], v[34:35] op_sel_hi:[1,0]
	v_pk_mul_f32 v[28:29], v[26:27], v[34:35] op_sel_hi:[1,0]
	v_cvt_pk_bf16_f32 v26, v30, v31
	v_cvt_pk_bf16_f32 v27, v32, v33
	v_cvt_pk_bf16_f32 v28, v28, v29
	v_cvt_pk_bf16_f32 v29, v36, v37
	ds_write_b128 v35, v[26:29] offset:2080
	v_pk_mul_f32 v[24:25], v[24:25], v[34:35] op_sel_hi:[1,0]
	v_pk_mul_f32 v[22:23], v[22:23], v[34:35] op_sel_hi:[1,0]
	v_pk_mul_f32 v[26:27], v[20:21], v[34:35] op_sel_hi:[1,0]
	v_pk_mul_f32 v[20:21], v[18:19], v[34:35] op_sel_hi:[1,0]
	v_cvt_pk_bf16_f32 v18, v22, v23
	v_cvt_pk_bf16_f32 v19, v24, v25
	v_cvt_pk_bf16_f32 v20, v20, v21
	v_cvt_pk_bf16_f32 v21, v26, v27
	ds_write_b128 v35, v[18:21] offset:2144
	v_add_u32_e32 v20, 0x70, v141
	v_mov_b32_e32 v18, v238
	v_mov_b32_e32 v19, v239
	v_ffbh_u32_e32 v21, v19
	v_min_u32_e32 v21, 32, v21
	v_lshlrev_b64 v[18:19], v21, v[18:19]
	v_min_u32_e32 v18, 1, v18
	v_or_b32_e32 v18, v19, v18
	v_cvt_f32_u32_e32 v18, v18
	v_sub_u32_e32 v19, 32, v21
	v_ldexp_f32 v18, v18, v19
	v_fmamk_f32 v18, v18, 0x2e800000, v177
	v_cmp_gt_f32_e32 vcc, s34, v18
	v_mul_f32_e32 v19, 0x4b800000, v18
	s_nop 0
	v_cndmask_b32_e32 v18, v18, v19, vcc
	v_rsq_f32_e32 v18, v18
	s_nop 0
	v_mul_f32_e32 v19, 0x45800000, v18
	v_cndmask_b32_e32 v18, v18, v19, vcc
	v_mul_u32_u24_e32 v19, 0x210, v20
	v_add3_u32 v19, v138, v19, v140
	v_pk_mul_f32 v[16:17], v[16:17], v[18:19] op_sel_hi:[1,0]
	v_pk_mul_f32 v[14:15], v[14:15], v[18:19] op_sel_hi:[1,0]
	v_pk_mul_f32 v[20:21], v[12:13], v[18:19] op_sel_hi:[1,0]
	v_pk_mul_f32 v[12:13], v[10:11], v[18:19] op_sel_hi:[1,0]
	v_cvt_pk_bf16_f32 v10, v14, v15
	v_cvt_pk_bf16_f32 v11, v16, v17
	v_cvt_pk_bf16_f32 v12, v12, v13
	v_cvt_pk_bf16_f32 v13, v20, v21
	ds_write_b128 v19, v[10:13] offset:2080
	v_pk_mul_f32 v[8:9], v[8:9], v[18:19] op_sel_hi:[1,0]
	v_pk_mul_f32 v[6:7], v[6:7], v[18:19] op_sel_hi:[1,0]
	v_pk_mul_f32 v[10:11], v[4:5], v[18:19] op_sel_hi:[1,0]
	v_pk_mul_f32 v[4:5], v[2:3], v[18:19] op_sel_hi:[1,0]
	v_cvt_pk_bf16_f32 v2, v6, v7
	v_cvt_pk_bf16_f32 v3, v8, v9
	v_cvt_pk_bf16_f32 v4, v4, v5
	v_cvt_pk_bf16_f32 v5, v10, v11
	ds_write_b128 v19, v[2:5] offset:2144
	s_cbranch_scc1 .LBB0_40
	v_add_f32_e32 v2, v243, v246
	s_branch .LBB0_41

.LBB0_50:
	v_mov_b32_e32 v130, v132
	v_mov_b32_e32 v131, v133
	s_mul_i32 s5, s5, 0x580000
	v_add_u32_e32 v136, v131, v134
	v_lshl_add_u32 v142, v130, 3, v0
	v_lshlrev_b32_e32 v130, 7, v136
	v_or_b32_e32 v135, -2, v131
	v_and_b32_e32 v130, 0xffffff00, v130
	v_add_u32_e32 v130, v130, v135
	v_cmp_lt_i32_e32 vcc, 1, v136
	s_add_u32 s6, s17, s5
	s_addc_u32 s7, s18, 0
	v_cndmask_b32_e32 v130, 0, v130, vcc
	v_ashrrev_i32_e32 v131, 31, v130
	v_lshl_add_u64 v[130:131], v[130:131], 3, s[2:3]
	global_load_dwordx2 v[130:131], v[130:131], off
	s_ashr_i32 s5, s4, 31
	s_lshl_b64 s[4:5], s[4:5], 2
	s_add_u32 s4, s6, s4
	s_addc_u32 s5, s7, s5
	v_ashrrev_i32_e32 v143, 31, v142
	s_waitcnt vmcnt(0)
	v_ffbh_u32_e32 v137, v131
	v_min_u32_e32 v137, 32, v137
	v_lshlrev_b64 v[130:131], v137, v[130:131]
	v_min_u32_e32 v130, 1, v130
	v_or_b32_e32 v130, v131, v130
	v_cvt_f32_u32_e32 v130, v130
	v_sub_u32_e32 v131, 32, v137
	v_ldexp_f32 v130, v130, v131
	v_fmamk_f32 v130, v130, 0x2e800000, v177
	v_cmp_gt_f32_e32 vcc, s34, v130
	v_mul_f32_e32 v131, 0x4b800000, v130
	s_nop 0
	v_cndmask_b32_e32 v130, v130, v131, vcc
	v_rsq_f32_e32 v130, v130
	s_nop 0
	v_mul_f32_e32 v131, 0x45800000, v130
	v_cndmask_b32_e32 v144, v130, v131, vcc
	v_mov_b64_e32 v[130:131], s[4:5]
	v_mad_i64_i32 v[146:147], s[4:5], v136, s26, v[130:131]
	v_pk_mul_f32 v[138:139], v[126:127], v[144:145] op_sel_hi:[1,0]
	v_lshlrev_b64 v[126:127], 2, v[142:143]
	v_pk_mul_f32 v[140:141], v[128:129], v[144:145] op_sel_hi:[1,0]
	v_lshl_add_u64 v[128:129], v[146:147], 0, v[126:127]
	v_pk_mul_f32 v[116:117], v[116:117], v[144:145] op_sel_hi:[1,0]
	v_pk_mul_f32 v[114:115], v[114:115], v[144:145] op_sel_hi:[1,0]
	global_store_dwordx4 v[128:129], v[114:117], off offset:144
	v_pk_mul_f32 v[124:125], v[124:125], v[144:145] op_sel_hi:[1,0]
	v_pk_mul_f32 v[122:123], v[122:123], v[144:145] op_sel_hi:[1,0]
	v_add_u32_e32 v116, 16, v136
	v_lshlrev_b32_e32 v114, 7, v116
	v_and_b32_e32 v114, 0xffffff00, v114
	v_add_u32_e32 v114, v114, v135
	v_cmp_lt_i32_e32 vcc, 1, v116
	v_pk_mul_f32 v[120:121], v[120:121], v[144:145] op_sel_hi:[1,0]
	v_pk_mul_f32 v[118:119], v[118:119], v[144:145] op_sel_hi:[1,0]
	v_cndmask_b32_e32 v114, 0, v114, vcc
	v_ashrrev_i32_e32 v115, 31, v114
	global_store_dwordx4 v[128:129], v[138:141], off
	global_store_dwordx4 v[128:129], v[122:125], off offset:16
	global_store_dwordx4 v[128:129], v[118:121], off offset:128
	v_lshl_add_u64 v[114:115], v[114:115], 3, s[2:3]
	global_load_dwordx2 v[114:115], v[114:115], off
	s_waitcnt vmcnt(0)
	v_ffbh_u32_e32 v117, v115
	v_min_u32_e32 v117, 32, v117
	v_lshlrev_b64 v[114:115], v117, v[114:115]
	v_min_u32_e32 v114, 1, v114
	v_or_b32_e32 v114, v115, v114
	v_cvt_f32_u32_e32 v114, v114
	v_sub_u32_e32 v115, 32, v117
	v_mad_i64_i32 v[116:117], s[4:5], v116, s26, v[130:131]
	v_ldexp_f32 v114, v114, v115
	v_fmamk_f32 v114, v114, 0x2e800000, v177
	v_cmp_gt_f32_e32 vcc, s34, v114
	v_mul_f32_e32 v115, 0x4b800000, v114
	v_lshl_add_u64 v[116:117], v[116:117], 0, v[126:127]
	v_cndmask_b32_e32 v114, v114, v115, vcc
	v_rsq_f32_e32 v114, v114
	s_nop 0
	v_mul_f32_e32 v115, 0x45800000, v114
	v_cndmask_b32_e32 v114, v114, v115, vcc
	v_pk_mul_f32 v[100:101], v[100:101], v[114:115] op_sel_hi:[1,0]
	v_pk_mul_f32 v[98:99], v[98:99], v[114:115] op_sel_hi:[1,0]
	global_store_dwordx4 v[116:117], v[98:101], off offset:144
	v_pk_mul_f32 v[112:113], v[112:113], v[114:115] op_sel_hi:[1,0]
	v_pk_mul_f32 v[110:111], v[110:111], v[114:115] op_sel_hi:[1,0]
	v_add_u32_e32 v100, 32, v136
	v_lshlrev_b32_e32 v98, 7, v100
	v_and_b32_e32 v98, 0xffffff00, v98
	v_add_u32_e32 v98, v98, v135
	v_cmp_lt_i32_e32 vcc, 1, v100
	v_pk_mul_f32 v[108:109], v[108:109], v[114:115] op_sel_hi:[1,0]
	v_pk_mul_f32 v[106:107], v[106:107], v[114:115] op_sel_hi:[1,0]
	v_cndmask_b32_e32 v98, 0, v98, vcc
	v_pk_mul_f32 v[104:105], v[104:105], v[114:115] op_sel_hi:[1,0]
	v_pk_mul_f32 v[102:103], v[102:103], v[114:115] op_sel_hi:[1,0]
	v_ashrrev_i32_e32 v99, 31, v98
	global_store_dwordx4 v[116:117], v[110:113], off
	global_store_dwordx4 v[116:117], v[106:109], off offset:16
	global_store_dwordx4 v[116:117], v[102:105], off offset:128
	v_lshl_add_u64 v[98:99], v[98:99], 3, s[2:3]
	global_load_dwordx2 v[98:99], v[98:99], off
	s_waitcnt vmcnt(0)
	v_ffbh_u32_e32 v101, v99
	v_min_u32_e32 v101, 32, v101
	v_lshlrev_b64 v[98:99], v101, v[98:99]
	v_min_u32_e32 v98, 1, v98
	v_or_b32_e32 v98, v99, v98
	v_cvt_f32_u32_e32 v98, v98
	v_sub_u32_e32 v99, 32, v101
	v_mad_i64_i32 v[100:101], s[4:5], v100, s26, v[130:131]
	v_ldexp_f32 v98, v98, v99
	v_fmamk_f32 v98, v98, 0x2e800000, v177
	v_cmp_gt_f32_e32 vcc, s34, v98
	v_mul_f32_e32 v99, 0x4b800000, v98
	v_lshl_add_u64 v[100:101], v[100:101], 0, v[126:127]
	v_cndmask_b32_e32 v98, v98, v99, vcc
	v_rsq_f32_e32 v98, v98
	s_nop 0
	v_mul_f32_e32 v99, 0x45800000, v98
	v_cndmask_b32_e32 v98, v98, v99, vcc
	v_pk_mul_f32 v[84:85], v[84:85], v[98:99] op_sel_hi:[1,0]
	v_pk_mul_f32 v[82:83], v[82:83], v[98:99] op_sel_hi:[1,0]
	global_store_dwordx4 v[100:101], v[82:85], off offset:144
	v_pk_mul_f32 v[96:97], v[96:97], v[98:99] op_sel_hi:[1,0]
	v_pk_mul_f32 v[94:95], v[94:95], v[98:99] op_sel_hi:[1,0]
	v_add_u32_e32 v84, 48, v136
	v_lshlrev_b32_e32 v82, 7, v84
	v_and_b32_e32 v82, 0xffffff00, v82
	v_add_u32_e32 v82, v82, v135
	v_cmp_lt_i32_e32 vcc, 1, v84
	v_pk_mul_f32 v[92:93], v[92:93], v[98:99] op_sel_hi:[1,0]
	v_pk_mul_f32 v[90:91], v[90:91], v[98:99] op_sel_hi:[1,0]
	v_cndmask_b32_e32 v82, 0, v82, vcc
	v_pk_mul_f32 v[88:89], v[88:89], v[98:99] op_sel_hi:[1,0]
	v_pk_mul_f32 v[86:87], v[86:87], v[98:99] op_sel_hi:[1,0]
	v_ashrrev_i32_e32 v83, 31, v82
	global_store_dwordx4 v[100:101], v[94:97], off
	global_store_dwordx4 v[100:101], v[90:93], off offset:16
	global_store_dwordx4 v[100:101], v[86:89], off offset:128
	v_lshl_add_u64 v[82:83], v[82:83], 3, s[2:3]
	global_load_dwordx2 v[82:83], v[82:83], off
	s_waitcnt vmcnt(0)
	v_ffbh_u32_e32 v85, v83
	v_min_u32_e32 v85, 32, v85
	v_lshlrev_b64 v[82:83], v85, v[82:83]
	v_min_u32_e32 v82, 1, v82
	v_or_b32_e32 v82, v83, v82
	v_cvt_f32_u32_e32 v82, v82
	v_sub_u32_e32 v83, 32, v85
	v_mad_i64_i32 v[84:85], s[4:5], v84, s26, v[130:131]
	v_ldexp_f32 v82, v82, v83
	v_fmamk_f32 v82, v82, 0x2e800000, v177
	v_cmp_gt_f32_e32 vcc, s34, v82
	v_mul_f32_e32 v83, 0x4b800000, v82
	v_lshl_add_u64 v[84:85], v[84:85], 0, v[126:127]
	v_cndmask_b32_e32 v82, v82, v83, vcc
	v_rsq_f32_e32 v82, v82
	s_nop 0
	v_mul_f32_e32 v83, 0x45800000, v82
	v_cndmask_b32_e32 v82, v82, v83, vcc
	v_pk_mul_f32 v[68:69], v[68:69], v[82:83] op_sel_hi:[1,0]
	v_pk_mul_f32 v[66:67], v[66:67], v[82:83] op_sel_hi:[1,0]
	global_store_dwordx4 v[84:85], v[66:69], off offset:144
	v_pk_mul_f32 v[80:81], v[80:81], v[82:83] op_sel_hi:[1,0]
	v_pk_mul_f32 v[78:79], v[78:79], v[82:83] op_sel_hi:[1,0]
	v_add_u32_e32 v68, 64, v136
	v_lshlrev_b32_e32 v66, 7, v68
	v_and_b32_e32 v66, 0xffffff00, v66
	v_add_u32_e32 v66, v66, v135
	v_cmp_lt_i32_e32 vcc, 1, v68
	v_pk_mul_f32 v[76:77], v[76:77], v[82:83] op_sel_hi:[1,0]
	v_pk_mul_f32 v[74:75], v[74:75], v[82:83] op_sel_hi:[1,0]
	v_cndmask_b32_e32 v66, 0, v66, vcc
	v_pk_mul_f32 v[72:73], v[72:73], v[82:83] op_sel_hi:[1,0]
	v_pk_mul_f32 v[70:71], v[70:71], v[82:83] op_sel_hi:[1,0]
	v_ashrrev_i32_e32 v67, 31, v66
	global_store_dwordx4 v[84:85], v[78:81], off
	global_store_dwordx4 v[84:85], v[74:77], off offset:16
	global_store_dwordx4 v[84:85], v[70:73], off offset:128
	v_lshl_add_u64 v[66:67], v[66:67], 3, s[2:3]
	global_load_dwordx2 v[66:67], v[66:67], off
	s_waitcnt vmcnt(0)
	v_ffbh_u32_e32 v69, v67
	v_min_u32_e32 v69, 32, v69
	v_lshlrev_b64 v[66:67], v69, v[66:67]
	v_min_u32_e32 v66, 1, v66
	v_or_b32_e32 v66, v67, v66
	v_cvt_f32_u32_e32 v66, v66
	v_sub_u32_e32 v67, 32, v69
	v_mad_i64_i32 v[68:69], s[4:5], v68, s26, v[130:131]
	v_ldexp_f32 v66, v66, v67
	v_fmamk_f32 v66, v66, 0x2e800000, v177
	v_cmp_gt_f32_e32 vcc, s34, v66
	v_mul_f32_e32 v67, 0x4b800000, v66
	v_lshl_add_u64 v[68:69], v[68:69], 0, v[126:127]
	v_cndmask_b32_e32 v66, v66, v67, vcc
	v_rsq_f32_e32 v66, v66
	s_nop 0
	v_mul_f32_e32 v67, 0x45800000, v66
	v_cndmask_b32_e32 v66, v66, v67, vcc
	v_pk_mul_f32 v[52:53], v[52:53], v[66:67] op_sel_hi:[1,0]
	v_pk_mul_f32 v[50:51], v[50:51], v[66:67] op_sel_hi:[1,0]
	global_store_dwordx4 v[68:69], v[50:53], off offset:144
	v_pk_mul_f32 v[64:65], v[64:65], v[66:67] op_sel_hi:[1,0]
	v_pk_mul_f32 v[62:63], v[62:63], v[66:67] op_sel_hi:[1,0]
	v_add_u32_e32 v52, 0x50, v136
	v_lshlrev_b32_e32 v50, 7, v52
	v_and_b32_e32 v50, 0xffffff00, v50
	v_add_u32_e32 v50, v50, v135
	v_cmp_lt_i32_e32 vcc, 1, v52
	v_pk_mul_f32 v[60:61], v[60:61], v[66:67] op_sel_hi:[1,0]
	v_pk_mul_f32 v[58:59], v[58:59], v[66:67] op_sel_hi:[1,0]
	v_cndmask_b32_e32 v50, 0, v50, vcc
	v_pk_mul_f32 v[56:57], v[56:57], v[66:67] op_sel_hi:[1,0]
	v_pk_mul_f32 v[54:55], v[54:55], v[66:67] op_sel_hi:[1,0]
	v_ashrrev_i32_e32 v51, 31, v50
	global_store_dwordx4 v[68:69], v[62:65], off
	global_store_dwordx4 v[68:69], v[58:61], off offset:16
	global_store_dwordx4 v[68:69], v[54:57], off offset:128
	v_lshl_add_u64 v[50:51], v[50:51], 3, s[2:3]
	global_load_dwordx2 v[50:51], v[50:51], off
	s_waitcnt vmcnt(0)
	v_ffbh_u32_e32 v53, v51
	v_min_u32_e32 v53, 32, v53
	v_lshlrev_b64 v[50:51], v53, v[50:51]
	v_min_u32_e32 v50, 1, v50
	v_or_b32_e32 v50, v51, v50
	v_cvt_f32_u32_e32 v50, v50
	v_sub_u32_e32 v51, 32, v53
	v_mad_i64_i32 v[52:53], s[4:5], v52, s26, v[130:131]
	v_ldexp_f32 v50, v50, v51
	v_fmamk_f32 v50, v50, 0x2e800000, v177
	v_cmp_gt_f32_e32 vcc, s34, v50
	v_mul_f32_e32 v51, 0x4b800000, v50
	v_lshl_add_u64 v[52:53], v[52:53], 0, v[126:127]
	v_cndmask_b32_e32 v50, v50, v51, vcc
	v_rsq_f32_e32 v50, v50
	s_nop 0
	v_mul_f32_e32 v51, 0x45800000, v50
	v_cndmask_b32_e32 v50, v50, v51, vcc
	v_pk_mul_f32 v[36:37], v[36:37], v[50:51] op_sel_hi:[1,0]
	v_pk_mul_f32 v[34:35], v[34:35], v[50:51] op_sel_hi:[1,0]
	global_store_dwordx4 v[52:53], v[34:37], off offset:144
	v_pk_mul_f32 v[48:49], v[48:49], v[50:51] op_sel_hi:[1,0]
	v_pk_mul_f32 v[46:47], v[46:47], v[50:51] op_sel_hi:[1,0]
	v_add_u32_e32 v36, 0x60, v136
	v_lshlrev_b32_e32 v34, 7, v36
	v_and_b32_e32 v34, 0xffffff00, v34
	v_add_u32_e32 v34, v34, v135
	v_cmp_lt_i32_e32 vcc, 1, v36
	v_pk_mul_f32 v[44:45], v[44:45], v[50:51] op_sel_hi:[1,0]
	v_pk_mul_f32 v[42:43], v[42:43], v[50:51] op_sel_hi:[1,0]
	v_cndmask_b32_e32 v34, 0, v34, vcc
	v_pk_mul_f32 v[40:41], v[40:41], v[50:51] op_sel_hi:[1,0]
	v_pk_mul_f32 v[38:39], v[38:39], v[50:51] op_sel_hi:[1,0]
	v_ashrrev_i32_e32 v35, 31, v34
	global_store_dwordx4 v[52:53], v[46:49], off
	global_store_dwordx4 v[52:53], v[42:45], off offset:16
	global_store_dwordx4 v[52:53], v[38:41], off offset:128
	v_lshl_add_u64 v[34:35], v[34:35], 3, s[2:3]
	global_load_dwordx2 v[34:35], v[34:35], off
	s_waitcnt vmcnt(0)
	v_ffbh_u32_e32 v37, v35
	v_min_u32_e32 v37, 32, v37
	v_lshlrev_b64 v[34:35], v37, v[34:35]
	v_min_u32_e32 v34, 1, v34
	v_or_b32_e32 v34, v35, v34
	v_cvt_f32_u32_e32 v34, v34
	v_sub_u32_e32 v35, 32, v37
	v_mad_i64_i32 v[36:37], s[4:5], v36, s26, v[130:131]
	v_ldexp_f32 v34, v34, v35
	v_fmamk_f32 v34, v34, 0x2e800000, v177
	v_cmp_gt_f32_e32 vcc, s34, v34
	v_mul_f32_e32 v35, 0x4b800000, v34
	v_lshl_add_u64 v[36:37], v[36:37], 0, v[126:127]
	v_cndmask_b32_e32 v34, v34, v35, vcc
	v_rsq_f32_e32 v34, v34
	s_nop 0
	v_mul_f32_e32 v35, 0x45800000, v34
	v_cndmask_b32_e32 v34, v34, v35, vcc
	v_pk_mul_f32 v[20:21], v[20:21], v[34:35] op_sel_hi:[1,0]
	v_pk_mul_f32 v[18:19], v[18:19], v[34:35] op_sel_hi:[1,0]
	global_store_dwordx4 v[36:37], v[18:21], off offset:144
	v_pk_mul_f32 v[32:33], v[32:33], v[34:35] op_sel_hi:[1,0]
	v_pk_mul_f32 v[30:31], v[30:31], v[34:35] op_sel_hi:[1,0]
	v_add_u32_e32 v20, 0x70, v136
	v_lshlrev_b32_e32 v18, 7, v20
	v_and_b32_e32 v18, 0xffffff00, v18
	v_add_u32_e32 v18, v18, v135
	v_cmp_lt_i32_e32 vcc, 1, v20
	v_pk_mul_f32 v[28:29], v[28:29], v[34:35] op_sel_hi:[1,0]
	v_pk_mul_f32 v[26:27], v[26:27], v[34:35] op_sel_hi:[1,0]
	v_cndmask_b32_e32 v18, 0, v18, vcc
	v_pk_mul_f32 v[24:25], v[24:25], v[34:35] op_sel_hi:[1,0]
	v_pk_mul_f32 v[22:23], v[22:23], v[34:35] op_sel_hi:[1,0]
	v_ashrrev_i32_e32 v19, 31, v18
	global_store_dwordx4 v[36:37], v[30:33], off
	global_store_dwordx4 v[36:37], v[26:29], off offset:16
	global_store_dwordx4 v[36:37], v[22:25], off offset:128
	v_lshl_add_u64 v[18:19], v[18:19], 3, s[2:3]
	global_load_dwordx2 v[18:19], v[18:19], off
	s_waitcnt vmcnt(0)
	v_ffbh_u32_e32 v21, v19
	v_min_u32_e32 v21, 32, v21
	v_lshlrev_b64 v[18:19], v21, v[18:19]
	v_min_u32_e32 v18, 1, v18
	v_or_b32_e32 v18, v19, v18
	v_cvt_f32_u32_e32 v18, v18
	v_sub_u32_e32 v19, 32, v21
	v_mad_i64_i32 v[20:21], s[4:5], v20, s26, v[130:131]
	v_ldexp_f32 v18, v18, v19
	v_fmamk_f32 v18, v18, 0x2e800000, v177
	v_cmp_gt_f32_e32 vcc, s34, v18
	v_mul_f32_e32 v19, 0x4b800000, v18
	v_lshl_add_u64 v[20:21], v[20:21], 0, v[126:127]
	v_cndmask_b32_e32 v18, v18, v19, vcc
	v_rsq_f32_e32 v18, v18
	s_nop 0
	v_mul_f32_e32 v19, 0x45800000, v18
	v_cndmask_b32_e32 v18, v18, v19, vcc
	v_pk_mul_f32 v[16:17], v[16:17], v[18:19] op_sel_hi:[1,0]
	v_pk_mul_f32 v[14:15], v[14:15], v[18:19] op_sel_hi:[1,0]
	v_pk_mul_f32 v[12:13], v[12:13], v[18:19] op_sel_hi:[1,0]
	v_pk_mul_f32 v[10:11], v[10:11], v[18:19] op_sel_hi:[1,0]
	v_pk_mul_f32 v[8:9], v[8:9], v[18:19] op_sel_hi:[1,0]
	v_pk_mul_f32 v[6:7], v[6:7], v[18:19] op_sel_hi:[1,0]
	v_pk_mul_f32 v[4:5], v[4:5], v[18:19] op_sel_hi:[1,0]
	v_pk_mul_f32 v[2:3], v[2:3], v[18:19] op_sel_hi:[1,0]
	global_store_dwordx4 v[20:21], v[14:17], off
	global_store_dwordx4 v[20:21], v[10:13], off offset:16
	global_store_dwordx4 v[20:21], v[6:9], off offset:128
	global_store_dwordx4 v[20:21], v[2:5], off offset:144
	s_mov_b32 s4, s100
	s_waitcnt lgkmcnt(0)
	s_add_i32 s30, s4, s30
	s_cmp_lt_i32 s30, 44
	s_cbranch_scc0 .LBB0_55

.LBB0_55:
	v_mov_b32_e32 v2, v176
	s_mov_b32 s15, s100
	v_readlane_b32 s2, v251, 12
	s_waitcnt lgkmcnt(0)
	s_add_i32 s25, s15, s2
	s_cmpk_gt_i32 s25, 0x1ff
	s_cbranch_scc1 .LBB0_64
	s_add_u32 s2, s10, 0x2e00000
	s_addc_u32 s3, s11, 0
	s_add_u32 s4, s10, 0x2900000
	s_addc_u32 s5, s11, 0
	s_add_u32 s30, s10, s22
	s_addc_u32 s40, s11, 0
	s_add_u32 s6, s10, 0x2900080
	s_addc_u32 s7, s11, 0
	v_and_b32_e32 v0, 0xc0, v2
	v_bfe_u32 v130, v2, 4, 2
	v_and_b32_e32 v131, 15, v2
	v_ashrrev_i32_e32 v2, 1, v2
	s_add_u32 s8, s10, 0x2e00080
	v_and_b32_e32 v132, 0xffffff80, v2
	s_addc_u32 s9, s11, 0
	s_branch .LBB0_58

.LBB0_69:
	s_or_b64 exec, exec, s[16:17]
	s_mov_b32 s16, s100
	s_waitcnt lgkmcnt(0)
	s_add_i32 s15, s16, s15
	s_cmpk_gt_i32 s15, 0x3ff
	s_cbranch_scc1 .LBB0_92

.LBB0_104:
	s_lshl_b32 s4, s4, 4
	s_ashr_i32 s5, s4, 31
	v_mov_b32_e32 v14, v152
	v_mov_b32_e32 v135, v153
	s_lshl_b64 s[6:7], s[4:5], 2
	s_add_u32 s6, s40, s6
	v_lshlrev_b32_e32 v144, 2, v14
	s_addc_u32 s7, s41, s7
	v_ashrrev_i32_e32 v145, 31, v144
	v_add3_u32 v148, s15, v156, v135
	v_lshl_add_u64 v[14:15], v[144:145], 2, s[6:7]
	v_lshlrev_b64 v[144:145], 1, v[144:145]
	v_ashrrev_i32_e32 v149, 31, v148
	v_lshl_add_u64 v[146:147], s[2:3], 0, v[144:145]
	v_lshlrev_b64 v[150:151], 9, v[148:149]
	v_lshl_add_u64 v[150:151], v[146:147], 0, v[150:151]
	global_load_dwordx4 v[14:17], v[14:15], off
	v_lshl_add_u64 v[162:163], v[150:151], 0, v[0:1]
	global_load_dwordx2 v[162:163], v[162:163], off
	s_lshl_b64 s[2:3], s[4:5], 1
	v_lshlrev_b32_e32 v135, 4, v148
	s_add_u32 s2, s51, s2
	s_addc_u32 s3, s57, s3
	v_lshl_add_u64 v[144:145], s[2:3], 0, v[144:145]
	v_mov_b32_e32 v141, v1
	v_mov_b32_e32 v143, v1
	s_waitcnt vmcnt(0)
	v_lshlrev_b32_e32 v164, 16, v162
	v_and_b32_e32 v165, 0xffff0000, v162
	v_pk_fma_f32 v[130:131], v[14:15], v[164:165], v[130:131]
	v_lshlrev_b32_e32 v162, 16, v163
	v_pk_mul_f32 v[164:165], v[130:131], v[130:131]
	v_and_b32_e32 v163, 0xffff0000, v163
	v_fmamk_f32 v139, v164, 0xbdd2d3e8, v178
	v_mul_f32_e32 v139, v130, v139
	v_exp_f32_e32 v139, v139
	v_pk_fma_f32 v[132:133], v[16:17], v[162:163], v[132:133]
	v_add_f32_e32 v139, 1.0, v139
	v_rcp_f32_e32 v164, v139
	v_fmamk_f32 v139, v165, 0xbdd2d3e8, v178
	v_mul_f32_e32 v139, v131, v139
	v_exp_f32_e32 v139, v139
	v_pk_mul_f32 v[162:163], v[132:133], v[132:133]
	v_add_f32_e32 v139, 1.0, v139
	v_rcp_f32_e32 v165, v139
	v_mov_b32_e32 v139, v1
	v_pk_mul_f32 v[130:131], v[130:131], v[164:165]
	s_nop 0
	v_cvt_pk_bf16_f32 v130, v130, v131
	v_fmamk_f32 v131, v162, 0xbdd2d3e8, v178
	v_mul_f32_e32 v131, v132, v131
	v_exp_f32_e32 v131, v131
	s_nop 0
	v_add_f32_e32 v131, 1.0, v131
	v_rcp_f32_e32 v162, v131
	v_fmamk_f32 v131, v163, 0xbdd2d3e8, v178
	v_mul_f32_e32 v131, v133, v131
	v_exp_f32_e32 v131, v131
	s_nop 0
	v_add_f32_e32 v131, 1.0, v131
	v_rcp_f32_e32 v163, v131
	s_nop 0
	v_pk_mul_f32 v[132:133], v[132:133], v[162:163]
	s_nop 0
	v_cvt_pk_bf16_f32 v131, v132, v133
	v_or_b32_e32 v132, v135, v157
	v_ashrrev_i32_e32 v133, 31, v132
	v_lshlrev_b64 v[132:133], 11, v[132:133]
	v_lshl_add_u64 v[132:133], v[144:145], 0, v[132:133]
	global_store_dwordx2 v[132:133], v[130:131], off
	v_lshl_add_u64 v[130:131], v[150:151], 0, v[138:139]
	global_load_dwordx2 v[130:131], v[130:131], off
	s_waitcnt vmcnt(0)
	v_lshlrev_b32_e32 v132, 16, v130
	v_and_b32_e32 v133, 0xffff0000, v130
	v_pk_fma_f32 v[126:127], v[14:15], v[132:133], v[126:127]
	s_nop 0
	v_pk_mul_f32 v[132:133], v[126:127], v[126:127]
	s_nop 0
	v_fmamk_f32 v130, v132, 0xbdd2d3e8, v178
	v_mul_f32_e32 v130, v126, v130
	v_exp_f32_e32 v130, v130
	s_nop 0
	v_add_f32_e32 v130, 1.0, v130
	v_rcp_f32_e32 v132, v130
	v_fmamk_f32 v130, v133, 0xbdd2d3e8, v178
	v_mul_f32_e32 v130, v127, v130
	v_exp_f32_e32 v130, v130
	s_nop 0
	v_add_f32_e32 v130, 1.0, v130
	v_rcp_f32_e32 v133, v130
	v_lshlrev_b32_e32 v130, 16, v131
	v_and_b32_e32 v131, 0xffff0000, v131
	v_pk_fma_f32 v[128:129], v[16:17], v[130:131], v[128:129]
	v_pk_mul_f32 v[126:127], v[126:127], v[132:133]
	v_pk_mul_f32 v[130:131], v[128:129], v[128:129]
	v_cvt_pk_bf16_f32 v126, v126, v127
	v_fmamk_f32 v127, v130, 0xbdd2d3e8, v178
	v_mul_f32_e32 v127, v128, v127
	v_exp_f32_e32 v127, v127
	s_nop 0
	v_add_f32_e32 v127, 1.0, v127
	v_rcp_f32_e32 v130, v127
	v_fmamk_f32 v127, v131, 0xbdd2d3e8, v178
	v_mul_f32_e32 v127, v129, v127
	v_exp_f32_e32 v127, v127
	s_nop 0
	v_add_f32_e32 v127, 1.0, v127
	v_rcp_f32_e32 v131, v127
	s_nop 0
	v_pk_mul_f32 v[128:129], v[128:129], v[130:131]
	s_nop 0
	v_cvt_pk_bf16_f32 v127, v128, v129
	v_or_b32_e32 v128, v135, v158
	v_ashrrev_i32_e32 v129, 31, v128
	v_lshlrev_b64 v[128:129], 11, v[128:129]
	v_lshl_add_u64 v[128:129], v[144:145], 0, v[128:129]
	global_store_dwordx2 v[128:129], v[126:127], off
	v_lshl_add_u64 v[126:127], v[150:151], 0, v[140:141]
	global_load_dwordx2 v[126:127], v[126:127], off
	s_waitcnt vmcnt(0)
	v_lshlrev_b32_e32 v128, 16, v126
	v_and_b32_e32 v129, 0xffff0000, v126
	v_pk_fma_f32 v[122:123], v[14:15], v[128:129], v[122:123]
	s_nop 0
	v_pk_mul_f32 v[128:129], v[122:123], v[122:123]
	s_nop 0
	v_fmamk_f32 v126, v128, 0xbdd2d3e8, v178
	v_mul_f32_e32 v126, v122, v126
	v_exp_f32_e32 v126, v126
	s_nop 0
	v_add_f32_e32 v126, 1.0, v126
	v_rcp_f32_e32 v128, v126
	v_fmamk_f32 v126, v129, 0xbdd2d3e8, v178
	v_mul_f32_e32 v126, v123, v126
	v_exp_f32_e32 v126, v126
	s_nop 0
	v_add_f32_e32 v126, 1.0, v126
	v_rcp_f32_e32 v129, v126
	v_lshlrev_b32_e32 v126, 16, v127
	v_and_b32_e32 v127, 0xffff0000, v127
	v_pk_fma_f32 v[124:125], v[16:17], v[126:127], v[124:125]
	v_pk_mul_f32 v[122:123], v[122:123], v[128:129]
	v_pk_mul_f32 v[126:127], v[124:125], v[124:125]
	v_cvt_pk_bf16_f32 v122, v122, v123
	v_fmamk_f32 v123, v126, 0xbdd2d3e8, v178
	v_mul_f32_e32 v123, v124, v123
	v_exp_f32_e32 v123, v123
	s_nop 0
	v_add_f32_e32 v123, 1.0, v123
	v_rcp_f32_e32 v126, v123
	v_fmamk_f32 v123, v127, 0xbdd2d3e8, v178
	v_mul_f32_e32 v123, v125, v123
	v_exp_f32_e32 v123, v123
	s_nop 0
	v_add_f32_e32 v123, 1.0, v123
	v_rcp_f32_e32 v127, v123
	s_nop 0
	v_pk_mul_f32 v[124:125], v[124:125], v[126:127]
	s_nop 0
	v_cvt_pk_bf16_f32 v123, v124, v125
	v_or_b32_e32 v124, v135, v159
	v_ashrrev_i32_e32 v125, 31, v124
	v_lshlrev_b64 v[124:125], 11, v[124:125]
	v_lshl_add_u64 v[124:125], v[144:145], 0, v[124:125]
	global_store_dwordx2 v[124:125], v[122:123], off
	v_lshl_add_u64 v[122:123], v[150:151], 0, v[142:143]
	global_load_dwordx2 v[122:123], v[122:123], off
	s_waitcnt vmcnt(0)
	v_lshlrev_b32_e32 v124, 16, v122
	v_and_b32_e32 v125, 0xffff0000, v122
	v_pk_fma_f32 v[118:119], v[14:15], v[124:125], v[118:119]
	s_nop 0
	v_pk_mul_f32 v[124:125], v[118:119], v[118:119]
	s_nop 0
	v_fmamk_f32 v122, v124, 0xbdd2d3e8, v178
	v_mul_f32_e32 v122, v118, v122
	v_exp_f32_e32 v122, v122
	s_nop 0
	v_add_f32_e32 v122, 1.0, v122
	v_rcp_f32_e32 v124, v122
	v_fmamk_f32 v122, v125, 0xbdd2d3e8, v178
	v_mul_f32_e32 v122, v119, v122
	v_exp_f32_e32 v122, v122
	s_nop 0
	v_add_f32_e32 v122, 1.0, v122
	v_rcp_f32_e32 v125, v122
	v_lshlrev_b32_e32 v122, 16, v123
	v_and_b32_e32 v123, 0xffff0000, v123
	v_pk_fma_f32 v[120:121], v[16:17], v[122:123], v[120:121]
	v_pk_mul_f32 v[118:119], v[118:119], v[124:125]
	v_pk_mul_f32 v[122:123], v[120:121], v[120:121]
	v_cvt_pk_bf16_f32 v118, v118, v119
	v_fmamk_f32 v119, v122, 0xbdd2d3e8, v178
	v_mul_f32_e32 v119, v120, v119
	v_exp_f32_e32 v119, v119
	s_nop 0
	v_add_f32_e32 v119, 1.0, v119
	v_rcp_f32_e32 v122, v119
	v_fmamk_f32 v119, v123, 0xbdd2d3e8, v178
	v_mul_f32_e32 v119, v121, v119
	v_exp_f32_e32 v119, v119
	s_nop 0
	v_add_f32_e32 v119, 1.0, v119
	v_rcp_f32_e32 v123, v119
	s_nop 0
	v_pk_mul_f32 v[120:121], v[120:121], v[122:123]
	s_nop 0
	v_cvt_pk_bf16_f32 v119, v120, v121
	v_or_b32_e32 v120, v135, v160
	v_ashrrev_i32_e32 v121, 31, v120
	v_lshlrev_b64 v[120:121], 11, v[120:121]
	v_lshl_add_u64 v[120:121], v[144:145], 0, v[120:121]
	global_store_dwordx2 v[120:121], v[118:119], off
	v_add_u32_e32 v120, 16, v148
	v_ashrrev_i32_e32 v121, 31, v120
	v_lshlrev_b64 v[118:119], 9, v[120:121]
	v_lshl_add_u64 v[118:119], v[146:147], 0, v[118:119]
	v_lshl_add_u64 v[122:123], v[118:119], 0, v[0:1]
	global_load_dwordx2 v[122:123], v[122:123], off
	v_lshlrev_b32_e32 v120, 4, v120
	s_waitcnt vmcnt(0)
	v_lshlrev_b32_e32 v124, 16, v122
	v_and_b32_e32 v125, 0xffff0000, v122
	v_pk_fma_f32 v[114:115], v[14:15], v[124:125], v[114:115]
	v_lshlrev_b32_e32 v122, 16, v123
	v_pk_mul_f32 v[124:125], v[114:115], v[114:115]
	v_and_b32_e32 v123, 0xffff0000, v123
	v_fmamk_f32 v121, v124, 0xbdd2d3e8, v178
	v_mul_f32_e32 v121, v114, v121
	v_exp_f32_e32 v121, v121
	v_pk_fma_f32 v[116:117], v[16:17], v[122:123], v[116:117]
	v_add_f32_e32 v121, 1.0, v121
	v_rcp_f32_e32 v124, v121
	v_fmamk_f32 v121, v125, 0xbdd2d3e8, v178
	v_mul_f32_e32 v121, v115, v121
	v_exp_f32_e32 v121, v121
	v_pk_mul_f32 v[122:123], v[116:117], v[116:117]
	v_add_f32_e32 v121, 1.0, v121
	v_rcp_f32_e32 v125, v121
	s_nop 0
	v_pk_mul_f32 v[114:115], v[114:115], v[124:125]
	s_nop 0
	v_cvt_pk_bf16_f32 v114, v114, v115
	v_fmamk_f32 v115, v122, 0xbdd2d3e8, v178
	v_mul_f32_e32 v115, v116, v115
	v_exp_f32_e32 v115, v115
	s_nop 0
	v_add_f32_e32 v115, 1.0, v115
	v_rcp_f32_e32 v122, v115
	v_fmamk_f32 v115, v123, 0xbdd2d3e8, v178
	v_mul_f32_e32 v115, v117, v115
	v_exp_f32_e32 v115, v115
	s_nop 0
	v_add_f32_e32 v115, 1.0, v115
	v_rcp_f32_e32 v123, v115
	s_nop 0
	v_pk_mul_f32 v[116:117], v[116:117], v[122:123]
	s_nop 0
	v_cvt_pk_bf16_f32 v115, v116, v117
	v_or_b32_e32 v116, v120, v157
	v_ashrrev_i32_e32 v117, 31, v116
	v_lshlrev_b64 v[116:117], 11, v[116:117]
	v_lshl_add_u64 v[116:117], v[144:145], 0, v[116:117]
	global_store_dwordx2 v[116:117], v[114:115], off
	v_lshl_add_u64 v[114:115], v[118:119], 0, v[138:139]
	global_load_dwordx2 v[114:115], v[114:115], off
	s_waitcnt vmcnt(0)
	v_lshlrev_b32_e32 v116, 16, v114
	v_and_b32_e32 v117, 0xffff0000, v114
	v_pk_fma_f32 v[110:111], v[14:15], v[116:117], v[110:111]
	s_nop 0
	v_pk_mul_f32 v[116:117], v[110:111], v[110:111]
	s_nop 0
	v_fmamk_f32 v114, v116, 0xbdd2d3e8, v178
	v_mul_f32_e32 v114, v110, v114
	v_exp_f32_e32 v114, v114
	s_nop 0
	v_add_f32_e32 v114, 1.0, v114
	v_rcp_f32_e32 v116, v114
	v_fmamk_f32 v114, v117, 0xbdd2d3e8, v178
	v_mul_f32_e32 v114, v111, v114
	v_exp_f32_e32 v114, v114
	s_nop 0
	v_add_f32_e32 v114, 1.0, v114
	v_rcp_f32_e32 v117, v114
	v_lshlrev_b32_e32 v114, 16, v115
	v_and_b32_e32 v115, 0xffff0000, v115
	v_pk_fma_f32 v[112:113], v[16:17], v[114:115], v[112:113]
	v_pk_mul_f32 v[110:111], v[110:111], v[116:117]
	v_pk_mul_f32 v[114:115], v[112:113], v[112:113]
	v_cvt_pk_bf16_f32 v110, v110, v111
	v_fmamk_f32 v111, v114, 0xbdd2d3e8, v178
	v_mul_f32_e32 v111, v112, v111
	v_exp_f32_e32 v111, v111
	s_nop 0
	v_add_f32_e32 v111, 1.0, v111
	v_rcp_f32_e32 v114, v111
	v_fmamk_f32 v111, v115, 0xbdd2d3e8, v178
	v_mul_f32_e32 v111, v113, v111
	v_exp_f32_e32 v111, v111
	s_nop 0
	v_add_f32_e32 v111, 1.0, v111
	v_rcp_f32_e32 v115, v111
	s_nop 0
	v_pk_mul_f32 v[112:113], v[112:113], v[114:115]
	s_nop 0
	v_cvt_pk_bf16_f32 v111, v112, v113
	v_or_b32_e32 v112, v120, v158
	v_ashrrev_i32_e32 v113, 31, v112
	v_lshlrev_b64 v[112:113], 11, v[112:113]
	v_lshl_add_u64 v[112:113], v[144:145], 0, v[112:113]
	global_store_dwordx2 v[112:113], v[110:111], off
	v_lshl_add_u64 v[110:111], v[118:119], 0, v[140:141]
	global_load_dwordx2 v[110:111], v[110:111], off
	s_waitcnt vmcnt(0)
	v_lshlrev_b32_e32 v112, 16, v110
	v_and_b32_e32 v113, 0xffff0000, v110
	v_pk_fma_f32 v[106:107], v[14:15], v[112:113], v[106:107]
	s_nop 0
	v_pk_mul_f32 v[112:113], v[106:107], v[106:107]
	s_nop 0
	v_fmamk_f32 v110, v112, 0xbdd2d3e8, v178
	v_mul_f32_e32 v110, v106, v110
	v_exp_f32_e32 v110, v110
	s_nop 0
	v_add_f32_e32 v110, 1.0, v110
	v_rcp_f32_e32 v112, v110
	v_fmamk_f32 v110, v113, 0xbdd2d3e8, v178
	v_mul_f32_e32 v110, v107, v110
	v_exp_f32_e32 v110, v110
	s_nop 0
	v_add_f32_e32 v110, 1.0, v110
	v_rcp_f32_e32 v113, v110
	v_lshlrev_b32_e32 v110, 16, v111
	v_and_b32_e32 v111, 0xffff0000, v111
	v_pk_fma_f32 v[108:109], v[16:17], v[110:111], v[108:109]
	v_pk_mul_f32 v[106:107], v[106:107], v[112:113]
	v_pk_mul_f32 v[110:111], v[108:109], v[108:109]
	v_cvt_pk_bf16_f32 v106, v106, v107
	v_fmamk_f32 v107, v110, 0xbdd2d3e8, v178
	v_mul_f32_e32 v107, v108, v107
	v_exp_f32_e32 v107, v107
	s_nop 0
	v_add_f32_e32 v107, 1.0, v107
	v_rcp_f32_e32 v110, v107
	v_fmamk_f32 v107, v111, 0xbdd2d3e8, v178
	v_mul_f32_e32 v107, v109, v107
	v_exp_f32_e32 v107, v107
	s_nop 0
	v_add_f32_e32 v107, 1.0, v107
	v_rcp_f32_e32 v111, v107
	s_nop 0
	v_pk_mul_f32 v[108:109], v[108:109], v[110:111]
	s_nop 0
	v_cvt_pk_bf16_f32 v107, v108, v109
	v_or_b32_e32 v108, v120, v159
	v_ashrrev_i32_e32 v109, 31, v108
	v_lshlrev_b64 v[108:109], 11, v[108:109]
	v_lshl_add_u64 v[108:109], v[144:145], 0, v[108:109]
	global_store_dwordx2 v[108:109], v[106:107], off
	v_lshl_add_u64 v[106:107], v[118:119], 0, v[142:143]
	global_load_dwordx2 v[106:107], v[106:107], off
	s_waitcnt vmcnt(0)
	v_lshlrev_b32_e32 v108, 16, v106
	v_and_b32_e32 v109, 0xffff0000, v106
	v_pk_fma_f32 v[102:103], v[14:15], v[108:109], v[102:103]
	s_nop 0
	v_pk_mul_f32 v[108:109], v[102:103], v[102:103]
	s_nop 0
	v_fmamk_f32 v106, v108, 0xbdd2d3e8, v178
	v_mul_f32_e32 v106, v102, v106
	v_exp_f32_e32 v106, v106
	s_nop 0
	v_add_f32_e32 v106, 1.0, v106
	v_rcp_f32_e32 v108, v106
	v_fmamk_f32 v106, v109, 0xbdd2d3e8, v178
	v_mul_f32_e32 v106, v103, v106
	v_exp_f32_e32 v106, v106
	s_nop 0
	v_add_f32_e32 v106, 1.0, v106
	v_rcp_f32_e32 v109, v106
	v_lshlrev_b32_e32 v106, 16, v107
	v_and_b32_e32 v107, 0xffff0000, v107
	v_pk_fma_f32 v[104:105], v[16:17], v[106:107], v[104:105]
	v_pk_mul_f32 v[102:103], v[102:103], v[108:109]
	v_pk_mul_f32 v[106:107], v[104:105], v[104:105]
	v_cvt_pk_bf16_f32 v102, v102, v103
	v_fmamk_f32 v103, v106, 0xbdd2d3e8, v178
	v_mul_f32_e32 v103, v104, v103
	v_exp_f32_e32 v103, v103
	s_nop 0
	v_add_f32_e32 v103, 1.0, v103
	v_rcp_f32_e32 v106, v103
	v_fmamk_f32 v103, v107, 0xbdd2d3e8, v178
	v_mul_f32_e32 v103, v105, v103
	v_exp_f32_e32 v103, v103
	s_nop 0
	v_add_f32_e32 v103, 1.0, v103
	v_rcp_f32_e32 v107, v103
	s_nop 0
	v_pk_mul_f32 v[104:105], v[104:105], v[106:107]
	s_nop 0
	v_cvt_pk_bf16_f32 v103, v104, v105
	v_or_b32_e32 v104, v120, v160
	v_ashrrev_i32_e32 v105, 31, v104
	v_lshlrev_b64 v[104:105], 11, v[104:105]
	v_lshl_add_u64 v[104:105], v[144:145], 0, v[104:105]
	global_store_dwordx2 v[104:105], v[102:103], off
	v_add_u32_e32 v104, 32, v148
	v_ashrrev_i32_e32 v105, 31, v104
	v_lshlrev_b64 v[102:103], 9, v[104:105]
	v_lshl_add_u64 v[102:103], v[146:147], 0, v[102:103]
	v_lshl_add_u64 v[106:107], v[102:103], 0, v[0:1]
	global_load_dwordx2 v[106:107], v[106:107], off
	v_lshlrev_b32_e32 v104, 4, v104
	s_waitcnt vmcnt(0)
	v_lshlrev_b32_e32 v108, 16, v106
	v_and_b32_e32 v109, 0xffff0000, v106
	v_pk_fma_f32 v[98:99], v[14:15], v[108:109], v[98:99]
	v_lshlrev_b32_e32 v106, 16, v107
	v_pk_mul_f32 v[108:109], v[98:99], v[98:99]
	v_and_b32_e32 v107, 0xffff0000, v107
	v_fmamk_f32 v105, v108, 0xbdd2d3e8, v178
	v_mul_f32_e32 v105, v98, v105
	v_exp_f32_e32 v105, v105
	v_pk_fma_f32 v[100:101], v[16:17], v[106:107], v[100:101]
	v_add_f32_e32 v105, 1.0, v105
	v_rcp_f32_e32 v108, v105
	v_fmamk_f32 v105, v109, 0xbdd2d3e8, v178
	v_mul_f32_e32 v105, v99, v105
	v_exp_f32_e32 v105, v105
	v_pk_mul_f32 v[106:107], v[100:101], v[100:101]
	v_add_f32_e32 v105, 1.0, v105
	v_rcp_f32_e32 v109, v105
	s_nop 0
	v_pk_mul_f32 v[98:99], v[98:99], v[108:109]
	s_nop 0
	v_cvt_pk_bf16_f32 v98, v98, v99
	v_fmamk_f32 v99, v106, 0xbdd2d3e8, v178
	v_mul_f32_e32 v99, v100, v99
	v_exp_f32_e32 v99, v99
	s_nop 0
	v_add_f32_e32 v99, 1.0, v99
	v_rcp_f32_e32 v106, v99
	v_fmamk_f32 v99, v107, 0xbdd2d3e8, v178
	v_mul_f32_e32 v99, v101, v99
	v_exp_f32_e32 v99, v99
	s_nop 0
	v_add_f32_e32 v99, 1.0, v99
	v_rcp_f32_e32 v107, v99
	s_nop 0
	v_pk_mul_f32 v[100:101], v[100:101], v[106:107]
	s_nop 0
	v_cvt_pk_bf16_f32 v99, v100, v101
	v_or_b32_e32 v100, v104, v157
	v_ashrrev_i32_e32 v101, 31, v100
	v_lshlrev_b64 v[100:101], 11, v[100:101]
	v_lshl_add_u64 v[100:101], v[144:145], 0, v[100:101]
	global_store_dwordx2 v[100:101], v[98:99], off
	v_lshl_add_u64 v[98:99], v[102:103], 0, v[138:139]
	global_load_dwordx2 v[98:99], v[98:99], off
	s_waitcnt vmcnt(0)
	v_lshlrev_b32_e32 v100, 16, v98
	v_and_b32_e32 v101, 0xffff0000, v98
	v_pk_fma_f32 v[94:95], v[14:15], v[100:101], v[94:95]
	s_nop 0
	v_pk_mul_f32 v[100:101], v[94:95], v[94:95]
	s_nop 0
	v_fmamk_f32 v98, v100, 0xbdd2d3e8, v178
	v_mul_f32_e32 v98, v94, v98
	v_exp_f32_e32 v98, v98
	s_nop 0
	v_add_f32_e32 v98, 1.0, v98
	v_rcp_f32_e32 v100, v98
	v_fmamk_f32 v98, v101, 0xbdd2d3e8, v178
	v_mul_f32_e32 v98, v95, v98
	v_exp_f32_e32 v98, v98
	s_nop 0
	v_add_f32_e32 v98, 1.0, v98
	v_rcp_f32_e32 v101, v98
	v_lshlrev_b32_e32 v98, 16, v99
	v_and_b32_e32 v99, 0xffff0000, v99
	v_pk_fma_f32 v[96:97], v[16:17], v[98:99], v[96:97]
	v_pk_mul_f32 v[94:95], v[94:95], v[100:101]
	v_pk_mul_f32 v[98:99], v[96:97], v[96:97]
	v_cvt_pk_bf16_f32 v94, v94, v95
	v_fmamk_f32 v95, v98, 0xbdd2d3e8, v178
	v_mul_f32_e32 v95, v96, v95
	v_exp_f32_e32 v95, v95
	s_nop 0
	v_add_f32_e32 v95, 1.0, v95
	v_rcp_f32_e32 v98, v95
	v_fmamk_f32 v95, v99, 0xbdd2d3e8, v178
	v_mul_f32_e32 v95, v97, v95
	v_exp_f32_e32 v95, v95
	s_nop 0
	v_add_f32_e32 v95, 1.0, v95
	v_rcp_f32_e32 v99, v95
	s_nop 0
	v_pk_mul_f32 v[96:97], v[96:97], v[98:99]
	s_nop 0
	v_cvt_pk_bf16_f32 v95, v96, v97
	v_or_b32_e32 v96, v104, v158
	v_ashrrev_i32_e32 v97, 31, v96
	v_lshlrev_b64 v[96:97], 11, v[96:97]
	v_lshl_add_u64 v[96:97], v[144:145], 0, v[96:97]
	global_store_dwordx2 v[96:97], v[94:95], off
	v_lshl_add_u64 v[94:95], v[102:103], 0, v[140:141]
	global_load_dwordx2 v[94:95], v[94:95], off
	s_waitcnt vmcnt(0)
	v_lshlrev_b32_e32 v96, 16, v94
	v_and_b32_e32 v97, 0xffff0000, v94
	v_pk_fma_f32 v[90:91], v[14:15], v[96:97], v[90:91]
	s_nop 0
	v_pk_mul_f32 v[96:97], v[90:91], v[90:91]
	s_nop 0
	v_fmamk_f32 v94, v96, 0xbdd2d3e8, v178
	v_mul_f32_e32 v94, v90, v94
	v_exp_f32_e32 v94, v94
	s_nop 0
	v_add_f32_e32 v94, 1.0, v94
	v_rcp_f32_e32 v96, v94
	v_fmamk_f32 v94, v97, 0xbdd2d3e8, v178
	v_mul_f32_e32 v94, v91, v94
	v_exp_f32_e32 v94, v94
	s_nop 0
	v_add_f32_e32 v94, 1.0, v94
	v_rcp_f32_e32 v97, v94
	v_lshlrev_b32_e32 v94, 16, v95
	v_and_b32_e32 v95, 0xffff0000, v95
	v_pk_fma_f32 v[92:93], v[16:17], v[94:95], v[92:93]
	v_pk_mul_f32 v[90:91], v[90:91], v[96:97]
	v_pk_mul_f32 v[94:95], v[92:93], v[92:93]
	v_cvt_pk_bf16_f32 v90, v90, v91
	v_fmamk_f32 v91, v94, 0xbdd2d3e8, v178
	v_mul_f32_e32 v91, v92, v91
	v_exp_f32_e32 v91, v91
	s_nop 0
	v_add_f32_e32 v91, 1.0, v91
	v_rcp_f32_e32 v94, v91
	v_fmamk_f32 v91, v95, 0xbdd2d3e8, v178
	v_mul_f32_e32 v91, v93, v91
	v_exp_f32_e32 v91, v91
	s_nop 0
	v_add_f32_e32 v91, 1.0, v91
	v_rcp_f32_e32 v95, v91
	s_nop 0
	v_pk_mul_f32 v[92:93], v[92:93], v[94:95]
	s_nop 0
	v_cvt_pk_bf16_f32 v91, v92, v93
	v_or_b32_e32 v92, v104, v159
	v_ashrrev_i32_e32 v93, 31, v92
	v_lshlrev_b64 v[92:93], 11, v[92:93]
	v_lshl_add_u64 v[92:93], v[144:145], 0, v[92:93]
	global_store_dwordx2 v[92:93], v[90:91], off
	v_lshl_add_u64 v[90:91], v[102:103], 0, v[142:143]
	global_load_dwordx2 v[90:91], v[90:91], off
	s_waitcnt vmcnt(0)
	v_lshlrev_b32_e32 v92, 16, v90
	v_and_b32_e32 v93, 0xffff0000, v90
	v_pk_fma_f32 v[86:87], v[14:15], v[92:93], v[86:87]
	s_nop 0
	v_pk_mul_f32 v[92:93], v[86:87], v[86:87]
	s_nop 0
	v_fmamk_f32 v90, v92, 0xbdd2d3e8, v178
	v_mul_f32_e32 v90, v86, v90
	v_exp_f32_e32 v90, v90
	s_nop 0
	v_add_f32_e32 v90, 1.0, v90
	v_rcp_f32_e32 v92, v90
	v_fmamk_f32 v90, v93, 0xbdd2d3e8, v178
	v_mul_f32_e32 v90, v87, v90
	v_exp_f32_e32 v90, v90
	s_nop 0
	v_add_f32_e32 v90, 1.0, v90
	v_rcp_f32_e32 v93, v90
	v_lshlrev_b32_e32 v90, 16, v91
	v_and_b32_e32 v91, 0xffff0000, v91
	v_pk_fma_f32 v[88:89], v[16:17], v[90:91], v[88:89]
	v_pk_mul_f32 v[86:87], v[86:87], v[92:93]
	v_pk_mul_f32 v[90:91], v[88:89], v[88:89]
	v_cvt_pk_bf16_f32 v86, v86, v87
	v_fmamk_f32 v87, v90, 0xbdd2d3e8, v178
	v_mul_f32_e32 v87, v88, v87
	v_exp_f32_e32 v87, v87
	s_nop 0
	v_add_f32_e32 v87, 1.0, v87
	v_rcp_f32_e32 v90, v87
	v_fmamk_f32 v87, v91, 0xbdd2d3e8, v178
	v_mul_f32_e32 v87, v89, v87
	v_exp_f32_e32 v87, v87
	s_nop 0
	v_add_f32_e32 v87, 1.0, v87
	v_rcp_f32_e32 v91, v87
	s_nop 0
	v_pk_mul_f32 v[88:89], v[88:89], v[90:91]
	s_nop 0
	v_cvt_pk_bf16_f32 v87, v88, v89
	v_or_b32_e32 v88, v104, v160
	v_ashrrev_i32_e32 v89, 31, v88
	v_lshlrev_b64 v[88:89], 11, v[88:89]
	v_lshl_add_u64 v[88:89], v[144:145], 0, v[88:89]
	global_store_dwordx2 v[88:89], v[86:87], off
	v_add_u32_e32 v88, 48, v148
	v_ashrrev_i32_e32 v89, 31, v88
	v_lshlrev_b64 v[86:87], 9, v[88:89]
	v_lshl_add_u64 v[86:87], v[146:147], 0, v[86:87]
	v_lshl_add_u64 v[90:91], v[86:87], 0, v[0:1]
	global_load_dwordx2 v[90:91], v[90:91], off
	v_lshlrev_b32_e32 v88, 4, v88
	s_waitcnt vmcnt(0)
	v_lshlrev_b32_e32 v92, 16, v90
	v_and_b32_e32 v93, 0xffff0000, v90
	v_pk_fma_f32 v[82:83], v[14:15], v[92:93], v[82:83]
	v_lshlrev_b32_e32 v90, 16, v91
	v_pk_mul_f32 v[92:93], v[82:83], v[82:83]
	v_and_b32_e32 v91, 0xffff0000, v91
	v_fmamk_f32 v89, v92, 0xbdd2d3e8, v178
	v_mul_f32_e32 v89, v82, v89
	v_exp_f32_e32 v89, v89
	v_pk_fma_f32 v[84:85], v[16:17], v[90:91], v[84:85]
	v_add_f32_e32 v89, 1.0, v89
	v_rcp_f32_e32 v92, v89
	v_fmamk_f32 v89, v93, 0xbdd2d3e8, v178
	v_mul_f32_e32 v89, v83, v89
	v_exp_f32_e32 v89, v89
	v_pk_mul_f32 v[90:91], v[84:85], v[84:85]
	v_add_f32_e32 v89, 1.0, v89
	v_rcp_f32_e32 v93, v89
	s_nop 0
	v_pk_mul_f32 v[82:83], v[82:83], v[92:93]
	s_nop 0
	v_cvt_pk_bf16_f32 v82, v82, v83
	v_fmamk_f32 v83, v90, 0xbdd2d3e8, v178
	v_mul_f32_e32 v83, v84, v83
	v_exp_f32_e32 v83, v83
	s_nop 0
	v_add_f32_e32 v83, 1.0, v83
	v_rcp_f32_e32 v90, v83
	v_fmamk_f32 v83, v91, 0xbdd2d3e8, v178
	v_mul_f32_e32 v83, v85, v83
	v_exp_f32_e32 v83, v83
	s_nop 0
	v_add_f32_e32 v83, 1.0, v83
	v_rcp_f32_e32 v91, v83
	s_nop 0
	v_pk_mul_f32 v[84:85], v[84:85], v[90:91]
	s_nop 0
	v_cvt_pk_bf16_f32 v83, v84, v85
	v_or_b32_e32 v84, v88, v157
	v_ashrrev_i32_e32 v85, 31, v84
	v_lshlrev_b64 v[84:85], 11, v[84:85]
	v_lshl_add_u64 v[84:85], v[144:145], 0, v[84:85]
	global_store_dwordx2 v[84:85], v[82:83], off
	v_lshl_add_u64 v[82:83], v[86:87], 0, v[138:139]
	global_load_dwordx2 v[82:83], v[82:83], off
	s_waitcnt vmcnt(0)
	v_lshlrev_b32_e32 v84, 16, v82
	v_and_b32_e32 v85, 0xffff0000, v82
	v_pk_fma_f32 v[78:79], v[14:15], v[84:85], v[78:79]
	s_nop 0
	v_pk_mul_f32 v[84:85], v[78:79], v[78:79]
	s_nop 0
	v_fmamk_f32 v82, v84, 0xbdd2d3e8, v178
	v_mul_f32_e32 v82, v78, v82
	v_exp_f32_e32 v82, v82
	s_nop 0
	v_add_f32_e32 v82, 1.0, v82
	v_rcp_f32_e32 v84, v82
	v_fmamk_f32 v82, v85, 0xbdd2d3e8, v178
	v_mul_f32_e32 v82, v79, v82
	v_exp_f32_e32 v82, v82
	s_nop 0
	v_add_f32_e32 v82, 1.0, v82
	v_rcp_f32_e32 v85, v82
	v_lshlrev_b32_e32 v82, 16, v83
	v_and_b32_e32 v83, 0xffff0000, v83
	v_pk_fma_f32 v[80:81], v[16:17], v[82:83], v[80:81]
	v_pk_mul_f32 v[78:79], v[78:79], v[84:85]
	v_pk_mul_f32 v[82:83], v[80:81], v[80:81]
	v_cvt_pk_bf16_f32 v78, v78, v79
	v_fmamk_f32 v79, v82, 0xbdd2d3e8, v178
	v_mul_f32_e32 v79, v80, v79
	v_exp_f32_e32 v79, v79
	s_nop 0
	v_add_f32_e32 v79, 1.0, v79
	v_rcp_f32_e32 v82, v79
	v_fmamk_f32 v79, v83, 0xbdd2d3e8, v178
	v_mul_f32_e32 v79, v81, v79
	v_exp_f32_e32 v79, v79
	s_nop 0
	v_add_f32_e32 v79, 1.0, v79
	v_rcp_f32_e32 v83, v79
	s_nop 0
	v_pk_mul_f32 v[80:81], v[80:81], v[82:83]
	s_nop 0
	v_cvt_pk_bf16_f32 v79, v80, v81
	v_or_b32_e32 v80, v88, v158
	v_ashrrev_i32_e32 v81, 31, v80
	v_lshlrev_b64 v[80:81], 11, v[80:81]
	v_lshl_add_u64 v[80:81], v[144:145], 0, v[80:81]
	global_store_dwordx2 v[80:81], v[78:79], off
	v_lshl_add_u64 v[78:79], v[86:87], 0, v[140:141]
	global_load_dwordx2 v[78:79], v[78:79], off
	s_waitcnt vmcnt(0)
	v_lshlrev_b32_e32 v80, 16, v78
	v_and_b32_e32 v81, 0xffff0000, v78
	v_pk_fma_f32 v[74:75], v[14:15], v[80:81], v[74:75]
	s_nop 0
	v_pk_mul_f32 v[80:81], v[74:75], v[74:75]
	s_nop 0
	v_fmamk_f32 v78, v80, 0xbdd2d3e8, v178
	v_mul_f32_e32 v78, v74, v78
	v_exp_f32_e32 v78, v78
	s_nop 0
	v_add_f32_e32 v78, 1.0, v78
	v_rcp_f32_e32 v80, v78
	v_fmamk_f32 v78, v81, 0xbdd2d3e8, v178
	v_mul_f32_e32 v78, v75, v78
	v_exp_f32_e32 v78, v78
	s_nop 0
	v_add_f32_e32 v78, 1.0, v78
	v_rcp_f32_e32 v81, v78
	v_lshlrev_b32_e32 v78, 16, v79
	v_and_b32_e32 v79, 0xffff0000, v79
	v_pk_fma_f32 v[76:77], v[16:17], v[78:79], v[76:77]
	v_pk_mul_f32 v[74:75], v[74:75], v[80:81]
	v_pk_mul_f32 v[78:79], v[76:77], v[76:77]
	v_cvt_pk_bf16_f32 v74, v74, v75
	v_fmamk_f32 v75, v78, 0xbdd2d3e8, v178
	v_mul_f32_e32 v75, v76, v75
	v_exp_f32_e32 v75, v75
	s_nop 0
	v_add_f32_e32 v75, 1.0, v75
	v_rcp_f32_e32 v78, v75
	v_fmamk_f32 v75, v79, 0xbdd2d3e8, v178
	v_mul_f32_e32 v75, v77, v75
	v_exp_f32_e32 v75, v75
	s_nop 0
	v_add_f32_e32 v75, 1.0, v75
	v_rcp_f32_e32 v79, v75
	s_nop 0
	v_pk_mul_f32 v[76:77], v[76:77], v[78:79]
	s_nop 0
	v_cvt_pk_bf16_f32 v75, v76, v77
	v_or_b32_e32 v76, v88, v159
	v_ashrrev_i32_e32 v77, 31, v76
	v_lshlrev_b64 v[76:77], 11, v[76:77]
	v_lshl_add_u64 v[76:77], v[144:145], 0, v[76:77]
	global_store_dwordx2 v[76:77], v[74:75], off
	v_lshl_add_u64 v[74:75], v[86:87], 0, v[142:143]
	global_load_dwordx2 v[74:75], v[74:75], off
	s_waitcnt vmcnt(0)
	v_lshlrev_b32_e32 v76, 16, v74
	v_and_b32_e32 v77, 0xffff0000, v74
	v_pk_fma_f32 v[70:71], v[14:15], v[76:77], v[70:71]
	s_nop 0
	v_pk_mul_f32 v[76:77], v[70:71], v[70:71]
	s_nop 0
	v_fmamk_f32 v74, v76, 0xbdd2d3e8, v178
	v_mul_f32_e32 v74, v70, v74
	v_exp_f32_e32 v74, v74
	s_nop 0
	v_add_f32_e32 v74, 1.0, v74
	v_rcp_f32_e32 v76, v74
	v_fmamk_f32 v74, v77, 0xbdd2d3e8, v178
	v_mul_f32_e32 v74, v71, v74
	v_exp_f32_e32 v74, v74
	s_nop 0
	v_add_f32_e32 v74, 1.0, v74
	v_rcp_f32_e32 v77, v74
	v_lshlrev_b32_e32 v74, 16, v75
	v_and_b32_e32 v75, 0xffff0000, v75
	v_pk_fma_f32 v[72:73], v[16:17], v[74:75], v[72:73]
	v_pk_mul_f32 v[70:71], v[70:71], v[76:77]
	v_pk_mul_f32 v[74:75], v[72:73], v[72:73]
	v_cvt_pk_bf16_f32 v70, v70, v71
	v_fmamk_f32 v71, v74, 0xbdd2d3e8, v178
	v_mul_f32_e32 v71, v72, v71
	v_exp_f32_e32 v71, v71
	s_nop 0
	v_add_f32_e32 v71, 1.0, v71
	v_rcp_f32_e32 v74, v71
	v_fmamk_f32 v71, v75, 0xbdd2d3e8, v178
	v_mul_f32_e32 v71, v73, v71
	v_exp_f32_e32 v71, v71
	s_nop 0
	v_add_f32_e32 v71, 1.0, v71
	v_rcp_f32_e32 v75, v71
	s_nop 0
	v_pk_mul_f32 v[72:73], v[72:73], v[74:75]
	s_nop 0
	v_cvt_pk_bf16_f32 v71, v72, v73
	v_or_b32_e32 v72, v88, v160
	v_ashrrev_i32_e32 v73, 31, v72
	v_lshlrev_b64 v[72:73], 11, v[72:73]
	v_lshl_add_u64 v[72:73], v[144:145], 0, v[72:73]
	global_store_dwordx2 v[72:73], v[70:71], off
	v_add_u32_e32 v72, 64, v148
	v_ashrrev_i32_e32 v73, 31, v72
	v_lshlrev_b64 v[70:71], 9, v[72:73]
	v_lshl_add_u64 v[70:71], v[146:147], 0, v[70:71]
	v_lshl_add_u64 v[74:75], v[70:71], 0, v[0:1]
	global_load_dwordx2 v[74:75], v[74:75], off
	v_lshlrev_b32_e32 v72, 4, v72
	s_waitcnt vmcnt(0)
	v_lshlrev_b32_e32 v76, 16, v74
	v_and_b32_e32 v77, 0xffff0000, v74
	v_pk_fma_f32 v[66:67], v[14:15], v[76:77], v[66:67]
	v_lshlrev_b32_e32 v74, 16, v75
	v_pk_mul_f32 v[76:77], v[66:67], v[66:67]
	v_and_b32_e32 v75, 0xffff0000, v75
	v_fmamk_f32 v73, v76, 0xbdd2d3e8, v178
	v_mul_f32_e32 v73, v66, v73
	v_exp_f32_e32 v73, v73
	v_pk_fma_f32 v[68:69], v[16:17], v[74:75], v[68:69]
	v_add_f32_e32 v73, 1.0, v73
	v_rcp_f32_e32 v76, v73
	v_fmamk_f32 v73, v77, 0xbdd2d3e8, v178
	v_mul_f32_e32 v73, v67, v73
	v_exp_f32_e32 v73, v73
	v_pk_mul_f32 v[74:75], v[68:69], v[68:69]
	v_add_f32_e32 v73, 1.0, v73
	v_rcp_f32_e32 v77, v73
	s_nop 0
	v_pk_mul_f32 v[66:67], v[66:67], v[76:77]
	s_nop 0
	v_cvt_pk_bf16_f32 v66, v66, v67
	v_fmamk_f32 v67, v74, 0xbdd2d3e8, v178
	v_mul_f32_e32 v67, v68, v67
	v_exp_f32_e32 v67, v67
	s_nop 0
	v_add_f32_e32 v67, 1.0, v67
	v_rcp_f32_e32 v74, v67
	v_fmamk_f32 v67, v75, 0xbdd2d3e8, v178
	v_mul_f32_e32 v67, v69, v67
	v_exp_f32_e32 v67, v67
	s_nop 0
	v_add_f32_e32 v67, 1.0, v67
	v_rcp_f32_e32 v75, v67
	s_nop 0
	v_pk_mul_f32 v[68:69], v[68:69], v[74:75]
	s_nop 0
	v_cvt_pk_bf16_f32 v67, v68, v69
	v_or_b32_e32 v68, v72, v157
	v_ashrrev_i32_e32 v69, 31, v68
	v_lshlrev_b64 v[68:69], 11, v[68:69]
	v_lshl_add_u64 v[68:69], v[144:145], 0, v[68:69]
	global_store_dwordx2 v[68:69], v[66:67], off
	v_lshl_add_u64 v[66:67], v[70:71], 0, v[138:139]
	global_load_dwordx2 v[66:67], v[66:67], off
	s_waitcnt vmcnt(0)
	v_lshlrev_b32_e32 v68, 16, v66
	v_and_b32_e32 v69, 0xffff0000, v66
	v_pk_fma_f32 v[62:63], v[14:15], v[68:69], v[62:63]
	s_nop 0
	v_pk_mul_f32 v[68:69], v[62:63], v[62:63]
	s_nop 0
	v_fmamk_f32 v66, v68, 0xbdd2d3e8, v178
	v_mul_f32_e32 v66, v62, v66
	v_exp_f32_e32 v66, v66
	s_nop 0
	v_add_f32_e32 v66, 1.0, v66
	v_rcp_f32_e32 v68, v66
	v_fmamk_f32 v66, v69, 0xbdd2d3e8, v178
	v_mul_f32_e32 v66, v63, v66
	v_exp_f32_e32 v66, v66
	s_nop 0
	v_add_f32_e32 v66, 1.0, v66
	v_rcp_f32_e32 v69, v66
	v_lshlrev_b32_e32 v66, 16, v67
	v_and_b32_e32 v67, 0xffff0000, v67
	v_pk_fma_f32 v[64:65], v[16:17], v[66:67], v[64:65]
	v_pk_mul_f32 v[62:63], v[62:63], v[68:69]
	v_pk_mul_f32 v[66:67], v[64:65], v[64:65]
	v_cvt_pk_bf16_f32 v62, v62, v63
	v_fmamk_f32 v63, v66, 0xbdd2d3e8, v178
	v_mul_f32_e32 v63, v64, v63
	v_exp_f32_e32 v63, v63
	s_nop 0
	v_add_f32_e32 v63, 1.0, v63
	v_rcp_f32_e32 v66, v63
	v_fmamk_f32 v63, v67, 0xbdd2d3e8, v178
	v_mul_f32_e32 v63, v65, v63
	v_exp_f32_e32 v63, v63
	s_nop 0
	v_add_f32_e32 v63, 1.0, v63
	v_rcp_f32_e32 v67, v63
	s_nop 0
	v_pk_mul_f32 v[64:65], v[64:65], v[66:67]
	s_nop 0
	v_cvt_pk_bf16_f32 v63, v64, v65
	v_or_b32_e32 v64, v72, v158
	v_ashrrev_i32_e32 v65, 31, v64
	v_lshlrev_b64 v[64:65], 11, v[64:65]
	v_lshl_add_u64 v[64:65], v[144:145], 0, v[64:65]
	global_store_dwordx2 v[64:65], v[62:63], off
	v_lshl_add_u64 v[62:63], v[70:71], 0, v[140:141]
	global_load_dwordx2 v[62:63], v[62:63], off
	s_waitcnt vmcnt(0)
	v_lshlrev_b32_e32 v64, 16, v62
	v_and_b32_e32 v65, 0xffff0000, v62
	v_pk_fma_f32 v[58:59], v[14:15], v[64:65], v[58:59]
	s_nop 0
	v_pk_mul_f32 v[64:65], v[58:59], v[58:59]
	s_nop 0
	v_fmamk_f32 v62, v64, 0xbdd2d3e8, v178
	v_mul_f32_e32 v62, v58, v62
	v_exp_f32_e32 v62, v62
	s_nop 0
	v_add_f32_e32 v62, 1.0, v62
	v_rcp_f32_e32 v64, v62
	v_fmamk_f32 v62, v65, 0xbdd2d3e8, v178
	v_mul_f32_e32 v62, v59, v62
	v_exp_f32_e32 v62, v62
	s_nop 0
	v_add_f32_e32 v62, 1.0, v62
	v_rcp_f32_e32 v65, v62
	v_lshlrev_b32_e32 v62, 16, v63
	v_and_b32_e32 v63, 0xffff0000, v63
	v_pk_fma_f32 v[60:61], v[16:17], v[62:63], v[60:61]
	v_pk_mul_f32 v[58:59], v[58:59], v[64:65]
	v_pk_mul_f32 v[62:63], v[60:61], v[60:61]
	v_cvt_pk_bf16_f32 v58, v58, v59
	v_fmamk_f32 v59, v62, 0xbdd2d3e8, v178
	v_mul_f32_e32 v59, v60, v59
	v_exp_f32_e32 v59, v59
	s_nop 0
	v_add_f32_e32 v59, 1.0, v59
	v_rcp_f32_e32 v62, v59
	v_fmamk_f32 v59, v63, 0xbdd2d3e8, v178
	v_mul_f32_e32 v59, v61, v59
	v_exp_f32_e32 v59, v59
	s_nop 0
	v_add_f32_e32 v59, 1.0, v59
	v_rcp_f32_e32 v63, v59
	s_nop 0
	v_pk_mul_f32 v[60:61], v[60:61], v[62:63]
	s_nop 0
	v_cvt_pk_bf16_f32 v59, v60, v61
	v_or_b32_e32 v60, v72, v159
	v_ashrrev_i32_e32 v61, 31, v60
	v_lshlrev_b64 v[60:61], 11, v[60:61]
	v_lshl_add_u64 v[60:61], v[144:145], 0, v[60:61]
	global_store_dwordx2 v[60:61], v[58:59], off
	v_lshl_add_u64 v[58:59], v[70:71], 0, v[142:143]
	global_load_dwordx2 v[58:59], v[58:59], off
	s_waitcnt vmcnt(0)
	v_lshlrev_b32_e32 v60, 16, v58
	v_and_b32_e32 v61, 0xffff0000, v58
	v_pk_fma_f32 v[54:55], v[14:15], v[60:61], v[54:55]
	s_nop 0
	v_pk_mul_f32 v[60:61], v[54:55], v[54:55]
	s_nop 0
	v_fmamk_f32 v58, v60, 0xbdd2d3e8, v178
	v_mul_f32_e32 v58, v54, v58
	v_exp_f32_e32 v58, v58
	s_nop 0
	v_add_f32_e32 v58, 1.0, v58
	v_rcp_f32_e32 v60, v58
	v_fmamk_f32 v58, v61, 0xbdd2d3e8, v178
	v_mul_f32_e32 v58, v55, v58
	v_exp_f32_e32 v58, v58
	s_nop 0
	v_add_f32_e32 v58, 1.0, v58
	v_rcp_f32_e32 v61, v58
	v_lshlrev_b32_e32 v58, 16, v59
	v_and_b32_e32 v59, 0xffff0000, v59
	v_pk_fma_f32 v[56:57], v[16:17], v[58:59], v[56:57]
	v_pk_mul_f32 v[54:55], v[54:55], v[60:61]
	v_pk_mul_f32 v[58:59], v[56:57], v[56:57]
	v_cvt_pk_bf16_f32 v54, v54, v55
	v_fmamk_f32 v55, v58, 0xbdd2d3e8, v178
	v_mul_f32_e32 v55, v56, v55
	v_exp_f32_e32 v55, v55
	s_nop 0
	v_add_f32_e32 v55, 1.0, v55
	v_rcp_f32_e32 v58, v55
	v_fmamk_f32 v55, v59, 0xbdd2d3e8, v178
	v_mul_f32_e32 v55, v57, v55
	v_exp_f32_e32 v55, v55
	s_nop 0
	v_add_f32_e32 v55, 1.0, v55
	v_rcp_f32_e32 v59, v55
	s_nop 0
	v_pk_mul_f32 v[56:57], v[56:57], v[58:59]
	s_nop 0
	v_cvt_pk_bf16_f32 v55, v56, v57
	v_or_b32_e32 v56, v72, v160
	v_ashrrev_i32_e32 v57, 31, v56
	v_lshlrev_b64 v[56:57], 11, v[56:57]
	v_lshl_add_u64 v[56:57], v[144:145], 0, v[56:57]
	global_store_dwordx2 v[56:57], v[54:55], off
	v_add_u32_e32 v56, 0x50, v148
	v_ashrrev_i32_e32 v57, 31, v56
	v_lshlrev_b64 v[54:55], 9, v[56:57]
	v_lshl_add_u64 v[54:55], v[146:147], 0, v[54:55]
	v_lshl_add_u64 v[58:59], v[54:55], 0, v[0:1]
	global_load_dwordx2 v[58:59], v[58:59], off
	v_lshlrev_b32_e32 v56, 4, v56
	s_waitcnt vmcnt(0)
	v_lshlrev_b32_e32 v60, 16, v58
	v_and_b32_e32 v61, 0xffff0000, v58
	v_pk_fma_f32 v[50:51], v[14:15], v[60:61], v[50:51]
	v_lshlrev_b32_e32 v58, 16, v59
	v_pk_mul_f32 v[60:61], v[50:51], v[50:51]
	v_and_b32_e32 v59, 0xffff0000, v59
	v_fmamk_f32 v57, v60, 0xbdd2d3e8, v178
	v_mul_f32_e32 v57, v50, v57
	v_exp_f32_e32 v57, v57
	v_pk_fma_f32 v[52:53], v[16:17], v[58:59], v[52:53]
	v_add_f32_e32 v57, 1.0, v57
	v_rcp_f32_e32 v60, v57
	v_fmamk_f32 v57, v61, 0xbdd2d3e8, v178
	v_mul_f32_e32 v57, v51, v57
	v_exp_f32_e32 v57, v57
	v_pk_mul_f32 v[58:59], v[52:53], v[52:53]
	v_add_f32_e32 v57, 1.0, v57
	v_rcp_f32_e32 v61, v57
	s_nop 0
	v_pk_mul_f32 v[50:51], v[50:51], v[60:61]
	s_nop 0
	v_cvt_pk_bf16_f32 v50, v50, v51
	v_fmamk_f32 v51, v58, 0xbdd2d3e8, v178
	v_mul_f32_e32 v51, v52, v51
	v_exp_f32_e32 v51, v51
	s_nop 0
	v_add_f32_e32 v51, 1.0, v51
	v_rcp_f32_e32 v58, v51
	v_fmamk_f32 v51, v59, 0xbdd2d3e8, v178
	v_mul_f32_e32 v51, v53, v51
	v_exp_f32_e32 v51, v51
	s_nop 0
	v_add_f32_e32 v51, 1.0, v51
	v_rcp_f32_e32 v59, v51
	s_nop 0
	v_pk_mul_f32 v[52:53], v[52:53], v[58:59]
	s_nop 0
	v_cvt_pk_bf16_f32 v51, v52, v53
	v_or_b32_e32 v52, v56, v157
	v_ashrrev_i32_e32 v53, 31, v52
	v_lshlrev_b64 v[52:53], 11, v[52:53]
	v_lshl_add_u64 v[52:53], v[144:145], 0, v[52:53]
	global_store_dwordx2 v[52:53], v[50:51], off
	v_lshl_add_u64 v[50:51], v[54:55], 0, v[138:139]
	global_load_dwordx2 v[50:51], v[50:51], off
	s_waitcnt vmcnt(0)
	v_lshlrev_b32_e32 v52, 16, v50
	v_and_b32_e32 v53, 0xffff0000, v50
	v_pk_fma_f32 v[46:47], v[14:15], v[52:53], v[46:47]
	s_nop 0
	v_pk_mul_f32 v[52:53], v[46:47], v[46:47]
	s_nop 0
	v_fmamk_f32 v50, v52, 0xbdd2d3e8, v178
	v_mul_f32_e32 v50, v46, v50
	v_exp_f32_e32 v50, v50
	s_nop 0
	v_add_f32_e32 v50, 1.0, v50
	v_rcp_f32_e32 v52, v50
	v_fmamk_f32 v50, v53, 0xbdd2d3e8, v178
	v_mul_f32_e32 v50, v47, v50
	v_exp_f32_e32 v50, v50
	s_nop 0
	v_add_f32_e32 v50, 1.0, v50
	v_rcp_f32_e32 v53, v50
	v_lshlrev_b32_e32 v50, 16, v51
	v_and_b32_e32 v51, 0xffff0000, v51
	v_pk_fma_f32 v[48:49], v[16:17], v[50:51], v[48:49]
	v_pk_mul_f32 v[46:47], v[46:47], v[52:53]
	v_pk_mul_f32 v[50:51], v[48:49], v[48:49]
	v_cvt_pk_bf16_f32 v46, v46, v47
	v_fmamk_f32 v47, v50, 0xbdd2d3e8, v178
	v_mul_f32_e32 v47, v48, v47
	v_exp_f32_e32 v47, v47
	s_nop 0
	v_add_f32_e32 v47, 1.0, v47
	v_rcp_f32_e32 v50, v47
	v_fmamk_f32 v47, v51, 0xbdd2d3e8, v178
	v_mul_f32_e32 v47, v49, v47
	v_exp_f32_e32 v47, v47
	s_nop 0
	v_add_f32_e32 v47, 1.0, v47
	v_rcp_f32_e32 v51, v47
	s_nop 0
	v_pk_mul_f32 v[48:49], v[48:49], v[50:51]
	s_nop 0
	v_cvt_pk_bf16_f32 v47, v48, v49
	v_or_b32_e32 v48, v56, v158
	v_ashrrev_i32_e32 v49, 31, v48
	v_lshlrev_b64 v[48:49], 11, v[48:49]
	v_lshl_add_u64 v[48:49], v[144:145], 0, v[48:49]
	global_store_dwordx2 v[48:49], v[46:47], off
	v_lshl_add_u64 v[46:47], v[54:55], 0, v[140:141]
	global_load_dwordx2 v[46:47], v[46:47], off
	s_waitcnt vmcnt(0)
	v_lshlrev_b32_e32 v48, 16, v46
	v_and_b32_e32 v49, 0xffff0000, v46
	v_pk_fma_f32 v[42:43], v[14:15], v[48:49], v[42:43]
	s_nop 0
	v_pk_mul_f32 v[48:49], v[42:43], v[42:43]
	s_nop 0
	v_fmamk_f32 v46, v48, 0xbdd2d3e8, v178
	v_mul_f32_e32 v46, v42, v46
	v_exp_f32_e32 v46, v46
	s_nop 0
	v_add_f32_e32 v46, 1.0, v46
	v_rcp_f32_e32 v48, v46
	v_fmamk_f32 v46, v49, 0xbdd2d3e8, v178
	v_mul_f32_e32 v46, v43, v46
	v_exp_f32_e32 v46, v46
	s_nop 0
	v_add_f32_e32 v46, 1.0, v46
	v_rcp_f32_e32 v49, v46
	v_lshlrev_b32_e32 v46, 16, v47
	v_and_b32_e32 v47, 0xffff0000, v47
	v_pk_fma_f32 v[44:45], v[16:17], v[46:47], v[44:45]
	v_pk_mul_f32 v[42:43], v[42:43], v[48:49]
	v_pk_mul_f32 v[46:47], v[44:45], v[44:45]
	v_cvt_pk_bf16_f32 v42, v42, v43
	v_fmamk_f32 v43, v46, 0xbdd2d3e8, v178
	v_mul_f32_e32 v43, v44, v43
	v_exp_f32_e32 v43, v43
	s_nop 0
	v_add_f32_e32 v43, 1.0, v43
	v_rcp_f32_e32 v46, v43
	v_fmamk_f32 v43, v47, 0xbdd2d3e8, v178
	v_mul_f32_e32 v43, v45, v43
	v_exp_f32_e32 v43, v43
	s_nop 0
	v_add_f32_e32 v43, 1.0, v43
	v_rcp_f32_e32 v47, v43
	s_nop 0
	v_pk_mul_f32 v[44:45], v[44:45], v[46:47]
	s_nop 0
	v_cvt_pk_bf16_f32 v43, v44, v45
	v_or_b32_e32 v44, v56, v159
	v_ashrrev_i32_e32 v45, 31, v44
	v_lshlrev_b64 v[44:45], 11, v[44:45]
	v_lshl_add_u64 v[44:45], v[144:145], 0, v[44:45]
	global_store_dwordx2 v[44:45], v[42:43], off
	v_lshl_add_u64 v[42:43], v[54:55], 0, v[142:143]
	global_load_dwordx2 v[42:43], v[42:43], off
	s_waitcnt vmcnt(0)
	v_lshlrev_b32_e32 v44, 16, v42
	v_and_b32_e32 v45, 0xffff0000, v42
	v_pk_fma_f32 v[38:39], v[14:15], v[44:45], v[38:39]
	s_nop 0
	v_pk_mul_f32 v[44:45], v[38:39], v[38:39]
	s_nop 0
	v_fmamk_f32 v42, v44, 0xbdd2d3e8, v178
	v_mul_f32_e32 v42, v38, v42
	v_exp_f32_e32 v42, v42
	s_nop 0
	v_add_f32_e32 v42, 1.0, v42
	v_rcp_f32_e32 v44, v42
	v_fmamk_f32 v42, v45, 0xbdd2d3e8, v178
	v_mul_f32_e32 v42, v39, v42
	v_exp_f32_e32 v42, v42
	s_nop 0
	v_add_f32_e32 v42, 1.0, v42
	v_rcp_f32_e32 v45, v42
	v_lshlrev_b32_e32 v42, 16, v43
	v_and_b32_e32 v43, 0xffff0000, v43
	v_pk_fma_f32 v[40:41], v[16:17], v[42:43], v[40:41]
	v_pk_mul_f32 v[38:39], v[38:39], v[44:45]
	v_pk_mul_f32 v[42:43], v[40:41], v[40:41]
	v_cvt_pk_bf16_f32 v38, v38, v39
	v_fmamk_f32 v39, v42, 0xbdd2d3e8, v178
	v_mul_f32_e32 v39, v40, v39
	v_exp_f32_e32 v39, v39
	s_nop 0
	v_add_f32_e32 v39, 1.0, v39
	v_rcp_f32_e32 v42, v39
	v_fmamk_f32 v39, v43, 0xbdd2d3e8, v178
	v_mul_f32_e32 v39, v41, v39
	v_exp_f32_e32 v39, v39
	s_nop 0
	v_add_f32_e32 v39, 1.0, v39
	v_rcp_f32_e32 v43, v39
	s_nop 0
	v_pk_mul_f32 v[40:41], v[40:41], v[42:43]
	s_nop 0
	v_cvt_pk_bf16_f32 v39, v40, v41
	v_or_b32_e32 v40, v56, v160
	v_ashrrev_i32_e32 v41, 31, v40
	v_lshlrev_b64 v[40:41], 11, v[40:41]
	v_lshl_add_u64 v[40:41], v[144:145], 0, v[40:41]
	global_store_dwordx2 v[40:41], v[38:39], off
	v_add_u32_e32 v40, 0x60, v148
	v_ashrrev_i32_e32 v41, 31, v40
	v_lshlrev_b64 v[38:39], 9, v[40:41]
	v_lshl_add_u64 v[38:39], v[146:147], 0, v[38:39]
	v_lshl_add_u64 v[42:43], v[38:39], 0, v[0:1]
	global_load_dwordx2 v[42:43], v[42:43], off
	v_lshlrev_b32_e32 v40, 4, v40
	s_waitcnt vmcnt(0)
	v_lshlrev_b32_e32 v44, 16, v42
	v_and_b32_e32 v45, 0xffff0000, v42
	v_pk_fma_f32 v[34:35], v[14:15], v[44:45], v[34:35]
	v_lshlrev_b32_e32 v42, 16, v43
	v_pk_mul_f32 v[44:45], v[34:35], v[34:35]
	v_and_b32_e32 v43, 0xffff0000, v43
	v_fmamk_f32 v41, v44, 0xbdd2d3e8, v178
	v_mul_f32_e32 v41, v34, v41
	v_exp_f32_e32 v41, v41
	v_pk_fma_f32 v[36:37], v[16:17], v[42:43], v[36:37]
	v_add_f32_e32 v41, 1.0, v41
	v_rcp_f32_e32 v44, v41
	v_fmamk_f32 v41, v45, 0xbdd2d3e8, v178
	v_mul_f32_e32 v41, v35, v41
	v_exp_f32_e32 v41, v41
	v_pk_mul_f32 v[42:43], v[36:37], v[36:37]
	v_add_f32_e32 v41, 1.0, v41
	v_rcp_f32_e32 v45, v41
	s_nop 0
	v_pk_mul_f32 v[34:35], v[34:35], v[44:45]
	s_nop 0
	v_cvt_pk_bf16_f32 v34, v34, v35
	v_fmamk_f32 v35, v42, 0xbdd2d3e8, v178
	v_mul_f32_e32 v35, v36, v35
	v_exp_f32_e32 v35, v35
	s_nop 0
	v_add_f32_e32 v35, 1.0, v35
	v_rcp_f32_e32 v42, v35
	v_fmamk_f32 v35, v43, 0xbdd2d3e8, v178
	v_mul_f32_e32 v35, v37, v35
	v_exp_f32_e32 v35, v35
	s_nop 0
	v_add_f32_e32 v35, 1.0, v35
	v_rcp_f32_e32 v43, v35
	s_nop 0
	v_pk_mul_f32 v[36:37], v[36:37], v[42:43]
	s_nop 0
	v_cvt_pk_bf16_f32 v35, v36, v37
	v_or_b32_e32 v36, v40, v157
	v_ashrrev_i32_e32 v37, 31, v36
	v_lshlrev_b64 v[36:37], 11, v[36:37]
	v_lshl_add_u64 v[36:37], v[144:145], 0, v[36:37]
	global_store_dwordx2 v[36:37], v[34:35], off
	v_lshl_add_u64 v[34:35], v[38:39], 0, v[138:139]
	global_load_dwordx2 v[34:35], v[34:35], off
	s_waitcnt vmcnt(0)
	v_lshlrev_b32_e32 v36, 16, v34
	v_and_b32_e32 v37, 0xffff0000, v34
	v_pk_fma_f32 v[30:31], v[14:15], v[36:37], v[30:31]
	s_nop 0
	v_pk_mul_f32 v[36:37], v[30:31], v[30:31]
	s_nop 0
	v_fmamk_f32 v34, v36, 0xbdd2d3e8, v178
	v_mul_f32_e32 v34, v30, v34
	v_exp_f32_e32 v34, v34
	s_nop 0
	v_add_f32_e32 v34, 1.0, v34
	v_rcp_f32_e32 v36, v34
	v_fmamk_f32 v34, v37, 0xbdd2d3e8, v178
	v_mul_f32_e32 v34, v31, v34
	v_exp_f32_e32 v34, v34
	s_nop 0
	v_add_f32_e32 v34, 1.0, v34
	v_rcp_f32_e32 v37, v34
	v_lshlrev_b32_e32 v34, 16, v35
	v_and_b32_e32 v35, 0xffff0000, v35
	v_pk_fma_f32 v[32:33], v[16:17], v[34:35], v[32:33]
	v_pk_mul_f32 v[30:31], v[30:31], v[36:37]
	v_pk_mul_f32 v[34:35], v[32:33], v[32:33]
	v_cvt_pk_bf16_f32 v30, v30, v31
	v_fmamk_f32 v31, v34, 0xbdd2d3e8, v178
	v_mul_f32_e32 v31, v32, v31
	v_exp_f32_e32 v31, v31
	s_nop 0
	v_add_f32_e32 v31, 1.0, v31
	v_rcp_f32_e32 v34, v31
	v_fmamk_f32 v31, v35, 0xbdd2d3e8, v178
	v_mul_f32_e32 v31, v33, v31
	v_exp_f32_e32 v31, v31
	s_nop 0
	v_add_f32_e32 v31, 1.0, v31
	v_rcp_f32_e32 v35, v31
	s_nop 0
	v_pk_mul_f32 v[32:33], v[32:33], v[34:35]
	s_nop 0
	v_cvt_pk_bf16_f32 v31, v32, v33
	v_or_b32_e32 v32, v40, v158
	v_ashrrev_i32_e32 v33, 31, v32
	v_lshlrev_b64 v[32:33], 11, v[32:33]
	v_lshl_add_u64 v[32:33], v[144:145], 0, v[32:33]
	global_store_dwordx2 v[32:33], v[30:31], off
	v_lshl_add_u64 v[30:31], v[38:39], 0, v[140:141]
	global_load_dwordx2 v[30:31], v[30:31], off
	s_waitcnt vmcnt(0)
	v_lshlrev_b32_e32 v32, 16, v30
	v_and_b32_e32 v33, 0xffff0000, v30
	v_pk_fma_f32 v[26:27], v[14:15], v[32:33], v[26:27]
	s_nop 0
	v_pk_mul_f32 v[32:33], v[26:27], v[26:27]
	s_nop 0
	v_fmamk_f32 v30, v32, 0xbdd2d3e8, v178
	v_mul_f32_e32 v30, v26, v30
	v_exp_f32_e32 v30, v30
	s_nop 0
	v_add_f32_e32 v30, 1.0, v30
	v_rcp_f32_e32 v32, v30
	v_fmamk_f32 v30, v33, 0xbdd2d3e8, v178
	v_mul_f32_e32 v30, v27, v30
	v_exp_f32_e32 v30, v30
	s_nop 0
	v_add_f32_e32 v30, 1.0, v30
	v_rcp_f32_e32 v33, v30
	v_lshlrev_b32_e32 v30, 16, v31
	v_and_b32_e32 v31, 0xffff0000, v31
	v_pk_fma_f32 v[28:29], v[16:17], v[30:31], v[28:29]
	v_pk_mul_f32 v[26:27], v[26:27], v[32:33]
	v_pk_mul_f32 v[30:31], v[28:29], v[28:29]
	v_cvt_pk_bf16_f32 v26, v26, v27
	v_fmamk_f32 v27, v30, 0xbdd2d3e8, v178
	v_mul_f32_e32 v27, v28, v27
	v_exp_f32_e32 v27, v27
	s_nop 0
	v_add_f32_e32 v27, 1.0, v27
	v_rcp_f32_e32 v30, v27
	v_fmamk_f32 v27, v31, 0xbdd2d3e8, v178
	v_mul_f32_e32 v27, v29, v27
	v_exp_f32_e32 v27, v27
	s_nop 0
	v_add_f32_e32 v27, 1.0, v27
	v_rcp_f32_e32 v31, v27
	s_nop 0
	v_pk_mul_f32 v[28:29], v[28:29], v[30:31]
	s_nop 0
	v_cvt_pk_bf16_f32 v27, v28, v29
	v_or_b32_e32 v28, v40, v159
	v_ashrrev_i32_e32 v29, 31, v28
	v_lshlrev_b64 v[28:29], 11, v[28:29]
	v_lshl_add_u64 v[28:29], v[144:145], 0, v[28:29]
	global_store_dwordx2 v[28:29], v[26:27], off
	v_lshl_add_u64 v[26:27], v[38:39], 0, v[142:143]
	global_load_dwordx2 v[26:27], v[26:27], off
	s_waitcnt vmcnt(0)
	v_lshlrev_b32_e32 v28, 16, v26
	v_and_b32_e32 v29, 0xffff0000, v26
	v_pk_fma_f32 v[22:23], v[14:15], v[28:29], v[22:23]
	s_nop 0
	v_pk_mul_f32 v[28:29], v[22:23], v[22:23]
	s_nop 0
	v_fmamk_f32 v26, v28, 0xbdd2d3e8, v178
	v_mul_f32_e32 v26, v22, v26
	v_exp_f32_e32 v26, v26
	s_nop 0
	v_add_f32_e32 v26, 1.0, v26
	v_rcp_f32_e32 v28, v26
	v_fmamk_f32 v26, v29, 0xbdd2d3e8, v178
	v_mul_f32_e32 v26, v23, v26
	v_exp_f32_e32 v26, v26
	s_nop 0
	v_add_f32_e32 v26, 1.0, v26
	v_rcp_f32_e32 v29, v26
	v_lshlrev_b32_e32 v26, 16, v27
	v_and_b32_e32 v27, 0xffff0000, v27
	v_pk_fma_f32 v[24:25], v[16:17], v[26:27], v[24:25]
	v_pk_mul_f32 v[22:23], v[22:23], v[28:29]
	v_pk_mul_f32 v[26:27], v[24:25], v[24:25]
	v_cvt_pk_bf16_f32 v22, v22, v23
	v_fmamk_f32 v23, v26, 0xbdd2d3e8, v178
	v_mul_f32_e32 v23, v24, v23
	v_exp_f32_e32 v23, v23
	s_nop 0
	v_add_f32_e32 v23, 1.0, v23
	v_rcp_f32_e32 v26, v23
	v_fmamk_f32 v23, v27, 0xbdd2d3e8, v178
	v_mul_f32_e32 v23, v25, v23
	v_exp_f32_e32 v23, v23
	s_nop 0
	v_add_f32_e32 v23, 1.0, v23
	v_rcp_f32_e32 v27, v23
	s_nop 0
	v_pk_mul_f32 v[24:25], v[24:25], v[26:27]
	s_nop 0
	v_cvt_pk_bf16_f32 v23, v24, v25
	v_or_b32_e32 v24, v40, v160
	v_ashrrev_i32_e32 v25, 31, v24
	v_lshlrev_b64 v[24:25], 11, v[24:25]
	v_lshl_add_u64 v[24:25], v[144:145], 0, v[24:25]
	global_store_dwordx2 v[24:25], v[22:23], off
	v_add_u32_e32 v24, 0x70, v148
	v_ashrrev_i32_e32 v25, 31, v24
	v_lshlrev_b64 v[22:23], 9, v[24:25]
	v_lshl_add_u64 v[22:23], v[146:147], 0, v[22:23]
	v_lshl_add_u64 v[26:27], v[22:23], 0, v[0:1]
	global_load_dwordx2 v[26:27], v[26:27], off
	v_lshlrev_b32_e32 v24, 4, v24
	s_waitcnt vmcnt(0)
	v_lshlrev_b32_e32 v28, 16, v26
	v_and_b32_e32 v29, 0xffff0000, v26
	v_pk_fma_f32 v[18:19], v[14:15], v[28:29], v[18:19]
	v_lshlrev_b32_e32 v26, 16, v27
	v_pk_mul_f32 v[28:29], v[18:19], v[18:19]
	v_and_b32_e32 v27, 0xffff0000, v27
	v_fmamk_f32 v25, v28, 0xbdd2d3e8, v178
	v_mul_f32_e32 v25, v18, v25
	v_exp_f32_e32 v25, v25
	v_pk_fma_f32 v[20:21], v[16:17], v[26:27], v[20:21]
	v_add_f32_e32 v25, 1.0, v25
	v_rcp_f32_e32 v28, v25
	v_fmamk_f32 v25, v29, 0xbdd2d3e8, v178
	v_mul_f32_e32 v25, v19, v25
	v_exp_f32_e32 v25, v25
	v_pk_mul_f32 v[26:27], v[20:21], v[20:21]
	v_add_f32_e32 v25, 1.0, v25
	v_rcp_f32_e32 v29, v25
	s_nop 0
	v_pk_mul_f32 v[18:19], v[18:19], v[28:29]
	s_nop 0
	v_cvt_pk_bf16_f32 v18, v18, v19
	v_fmamk_f32 v19, v26, 0xbdd2d3e8, v178
	v_mul_f32_e32 v19, v20, v19
	v_exp_f32_e32 v19, v19
	s_nop 0
	v_add_f32_e32 v19, 1.0, v19
	v_rcp_f32_e32 v26, v19
	v_fmamk_f32 v19, v27, 0xbdd2d3e8, v178
	v_mul_f32_e32 v19, v21, v19
	v_exp_f32_e32 v19, v19
	s_nop 0
	v_add_f32_e32 v19, 1.0, v19
	v_rcp_f32_e32 v27, v19
	s_nop 0
	v_pk_mul_f32 v[20:21], v[20:21], v[26:27]
	s_nop 0
	v_cvt_pk_bf16_f32 v19, v20, v21
	v_or_b32_e32 v20, v24, v157
	v_ashrrev_i32_e32 v21, 31, v20
	v_lshlrev_b64 v[20:21], 11, v[20:21]
	v_lshl_add_u64 v[20:21], v[144:145], 0, v[20:21]
	global_store_dwordx2 v[20:21], v[18:19], off
	v_lshl_add_u64 v[18:19], v[22:23], 0, v[138:139]
	global_load_dwordx2 v[18:19], v[18:19], off
	s_waitcnt vmcnt(0)
	v_lshlrev_b32_e32 v20, 16, v18
	v_and_b32_e32 v21, 0xffff0000, v18
	v_pk_fma_f32 v[10:11], v[14:15], v[20:21], v[10:11]
	s_nop 0
	v_pk_mul_f32 v[20:21], v[10:11], v[10:11]
	s_nop 0
	v_fmamk_f32 v18, v20, 0xbdd2d3e8, v178
	v_mul_f32_e32 v18, v10, v18
	v_exp_f32_e32 v18, v18
	s_nop 0
	v_add_f32_e32 v18, 1.0, v18
	v_rcp_f32_e32 v20, v18
	v_fmamk_f32 v18, v21, 0xbdd2d3e8, v178
	v_mul_f32_e32 v18, v11, v18
	v_exp_f32_e32 v18, v18
	s_nop 0
	v_add_f32_e32 v18, 1.0, v18
	v_rcp_f32_e32 v21, v18
	v_lshlrev_b32_e32 v18, 16, v19
	v_and_b32_e32 v19, 0xffff0000, v19
	v_pk_fma_f32 v[12:13], v[16:17], v[18:19], v[12:13]
	v_pk_mul_f32 v[10:11], v[10:11], v[20:21]
	v_pk_mul_f32 v[18:19], v[12:13], v[12:13]
	v_cvt_pk_bf16_f32 v10, v10, v11
	v_fmamk_f32 v11, v18, 0xbdd2d3e8, v178
	v_mul_f32_e32 v11, v12, v11
	v_exp_f32_e32 v11, v11
	s_nop 0
	v_add_f32_e32 v11, 1.0, v11
	v_rcp_f32_e32 v18, v11
	v_fmamk_f32 v11, v19, 0xbdd2d3e8, v178
	v_mul_f32_e32 v11, v13, v11
	v_exp_f32_e32 v11, v11
	s_nop 0
	v_add_f32_e32 v11, 1.0, v11
	v_rcp_f32_e32 v19, v11
	s_nop 0
	v_pk_mul_f32 v[12:13], v[12:13], v[18:19]
	s_nop 0
	v_cvt_pk_bf16_f32 v11, v12, v13
	v_or_b32_e32 v12, v24, v158
	v_ashrrev_i32_e32 v13, 31, v12
	v_lshlrev_b64 v[12:13], 11, v[12:13]
	v_lshl_add_u64 v[12:13], v[144:145], 0, v[12:13]
	global_store_dwordx2 v[12:13], v[10:11], off
	v_lshl_add_u64 v[10:11], v[22:23], 0, v[140:141]
	global_load_dwordx2 v[10:11], v[10:11], off
	s_waitcnt vmcnt(0)
	v_lshlrev_b32_e32 v12, 16, v10
	v_and_b32_e32 v13, 0xffff0000, v10
	v_pk_fma_f32 v[6:7], v[14:15], v[12:13], v[6:7]
	s_nop 0
	v_pk_mul_f32 v[12:13], v[6:7], v[6:7]
	s_nop 0
	v_fmamk_f32 v10, v12, 0xbdd2d3e8, v178
	v_mul_f32_e32 v10, v6, v10
	v_exp_f32_e32 v10, v10
	s_nop 0
	v_add_f32_e32 v10, 1.0, v10
	v_rcp_f32_e32 v12, v10
	v_fmamk_f32 v10, v13, 0xbdd2d3e8, v178
	v_mul_f32_e32 v10, v7, v10
	v_exp_f32_e32 v10, v10
	s_nop 0
	v_add_f32_e32 v10, 1.0, v10
	v_rcp_f32_e32 v13, v10
	v_lshlrev_b32_e32 v10, 16, v11
	v_and_b32_e32 v11, 0xffff0000, v11
	v_pk_fma_f32 v[8:9], v[16:17], v[10:11], v[8:9]
	v_pk_mul_f32 v[6:7], v[6:7], v[12:13]
	v_pk_mul_f32 v[10:11], v[8:9], v[8:9]
	v_cvt_pk_bf16_f32 v6, v6, v7
	v_fmamk_f32 v7, v10, 0xbdd2d3e8, v178
	v_mul_f32_e32 v7, v8, v7
	v_exp_f32_e32 v7, v7
	s_nop 0
	v_add_f32_e32 v7, 1.0, v7
	v_rcp_f32_e32 v10, v7
	v_fmamk_f32 v7, v11, 0xbdd2d3e8, v178
	v_mul_f32_e32 v7, v9, v7
	v_exp_f32_e32 v7, v7
	s_nop 0
	v_add_f32_e32 v7, 1.0, v7
	v_rcp_f32_e32 v11, v7
	s_nop 0
	v_pk_mul_f32 v[8:9], v[8:9], v[10:11]
	s_nop 0
	v_cvt_pk_bf16_f32 v7, v8, v9
	v_or_b32_e32 v8, v24, v159
	v_ashrrev_i32_e32 v9, 31, v8
	v_lshlrev_b64 v[8:9], 11, v[8:9]
	v_lshl_add_u64 v[8:9], v[144:145], 0, v[8:9]
	global_store_dwordx2 v[8:9], v[6:7], off
	v_lshl_add_u64 v[6:7], v[22:23], 0, v[142:143]
	global_load_dwordx2 v[6:7], v[6:7], off
	s_waitcnt vmcnt(0)
	v_lshlrev_b32_e32 v8, 16, v6
	v_and_b32_e32 v9, 0xffff0000, v6
	v_pk_fma_f32 v[2:3], v[14:15], v[8:9], v[2:3]
	s_nop 0
	v_pk_mul_f32 v[8:9], v[2:3], v[2:3]
	s_nop 0
	v_fmamk_f32 v6, v8, 0xbdd2d3e8, v178
	v_mul_f32_e32 v6, v2, v6
	v_exp_f32_e32 v6, v6
	s_nop 0
	v_add_f32_e32 v6, 1.0, v6
	v_rcp_f32_e32 v8, v6
	v_fmamk_f32 v6, v9, 0xbdd2d3e8, v178
	v_mul_f32_e32 v6, v3, v6
	v_exp_f32_e32 v6, v6
	s_nop 0
	v_add_f32_e32 v6, 1.0, v6
	v_rcp_f32_e32 v9, v6
	v_lshlrev_b32_e32 v6, 16, v7
	v_and_b32_e32 v7, 0xffff0000, v7
	v_pk_fma_f32 v[4:5], v[16:17], v[6:7], v[4:5]
	v_pk_mul_f32 v[2:3], v[2:3], v[8:9]
	v_pk_mul_f32 v[6:7], v[4:5], v[4:5]
	v_cvt_pk_bf16_f32 v2, v2, v3
	v_fmamk_f32 v3, v6, 0xbdd2d3e8, v178
	v_mul_f32_e32 v3, v4, v3
	v_exp_f32_e32 v3, v3
	s_nop 0
	v_add_f32_e32 v3, 1.0, v3
	v_rcp_f32_e32 v6, v3
	v_fmamk_f32 v3, v7, 0xbdd2d3e8, v178
	v_mul_f32_e32 v3, v5, v3
	v_exp_f32_e32 v3, v3
	s_nop 0
	v_add_f32_e32 v3, 1.0, v3
	v_rcp_f32_e32 v7, v3
	s_nop 0
	v_pk_mul_f32 v[4:5], v[4:5], v[6:7]
	s_nop 0
	v_cvt_pk_bf16_f32 v3, v4, v5
	v_or_b32_e32 v4, v24, v160
	v_ashrrev_i32_e32 v5, 31, v4
	v_lshlrev_b64 v[4:5], 11, v[4:5]
	v_lshl_add_u64 v[4:5], v[144:145], 0, v[4:5]
	global_store_dwordx2 v[4:5], v[2:3], off
	s_mov_b32 s2, s100
	s_waitcnt lgkmcnt(0)
	s_add_i32 s65, s2, s65
	s_cmpk_gt_i32 s65, 0x1ff
	s_cbranch_scc1 .LBB0_127

.LBB0_133:
	v_div_scale_f32 v0, s[6:7], v128, v128, 1.0
	v_rcp_f32_e32 v2, v0
	v_mov_b32_e32 v163, v1
	v_fma_f32 v3, -v0, v2, 1.0
	v_fmac_f32_e32 v2, v3, v2
	v_div_scale_f32 v3, vcc, 1.0, v128, 1.0
	v_mul_f32_e32 v4, v3, v2
	v_fma_f32 v5, -v0, v4, v3
	v_fmac_f32_e32 v4, v5, v2
	v_fma_f32 v0, -v0, v4, v3
	v_div_fmas_f32 v0, v0, v2, v4
	v_div_scale_f32 v2, s[6:7], v116, v116, v190
	v_rcp_f32_e32 v3, v2
	v_div_fixup_f32 v0, v0, v128, 1.0
	v_fma_f32 v4, -v2, v3, 1.0
	v_fmac_f32_e32 v3, v4, v3
	v_div_scale_f32 v4, vcc, v190, v116, v190
	v_mul_f32_e32 v5, v4, v3
	v_fma_f32 v6, -v2, v5, v4
	v_fmac_f32_e32 v5, v6, v3
	v_fma_f32 v2, -v2, v5, v4
	v_div_fmas_f32 v2, v2, v3, v5
	v_div_fixup_f32 v2, v2, v116, v190
	v_pk_mul_f32 v[4:5], v[112:113], v[2:3] op_sel_hi:[1,0]
	v_pk_mul_f32 v[6:7], v[114:115], v[2:3] op_sel_hi:[1,0]
	v_pk_fma_f32 v[16:17], v[104:105], v[0:1], v[4:5] op_sel_hi:[1,0,1] neg_lo:[0,0,1] neg_hi:[0,0,1]
	v_pk_mul_f32 v[4:5], v[108:109], v[2:3] op_sel_hi:[1,0]
	v_pk_fma_f32 v[12:13], v[106:107], v[0:1], v[6:7] op_sel_hi:[1,0,1] neg_lo:[0,0,1] neg_hi:[0,0,1]
	v_pk_fma_f32 v[8:9], v[100:101], v[0:1], v[4:5] op_sel_hi:[1,0,1] neg_lo:[0,0,1] neg_hi:[0,0,1]
	v_pk_mul_f32 v[6:7], v[110:111], v[2:3] op_sel_hi:[1,0]
	v_mov_b32_e32 v10, v17
	v_mov_b32_e32 v11, v9
	v_pk_fma_f32 v[6:7], v[102:103], v[0:1], v[6:7] op_sel_hi:[1,0,1] neg_lo:[0,0,1] neg_hi:[0,0,1]
	v_mov_b32_e32 v4, v16
	v_mov_b32_e32 v5, v8
	v_pk_mul_f32 v[10:11], v[10:11], v[10:11]
	v_pk_mul_f32 v[14:15], v[98:99], v[2:3] op_sel_hi:[1,0]
	v_pk_fma_f32 v[4:5], v[4:5], v[4:5], v[10:11]
	v_mov_b32_e32 v10, v12
	v_mov_b32_e32 v11, v6
	v_pk_fma_f32 v[4:5], v[10:11], v[10:11], v[4:5]
	v_mov_b32_e32 v10, v13
	v_mov_b32_e32 v11, v7
	v_pk_fma_f32 v[4:5], v[10:11], v[10:11], v[4:5]
	v_pk_mul_f32 v[10:11], v[96:97], v[2:3] op_sel_hi:[1,0]
	s_waitcnt vmcnt(1)
	v_pk_fma_f32 v[28:29], v[90:91], v[0:1], v[14:15] op_sel_hi:[1,0,1] neg_lo:[0,0,1] neg_hi:[0,0,1]
	v_pk_fma_f32 v[32:33], v[88:89], v[0:1], v[10:11] op_sel_hi:[1,0,1] neg_lo:[0,0,1] neg_hi:[0,0,1]
	v_pk_mul_f32 v[10:11], v[92:93], v[2:3] op_sel_hi:[1,0]
	v_pk_mul_f32 v[14:15], v[94:95], v[2:3] op_sel_hi:[1,0]
	v_pk_fma_f32 v[24:25], v[84:85], v[0:1], v[10:11] op_sel_hi:[1,0,1] neg_lo:[0,0,1] neg_hi:[0,0,1]
	v_pk_fma_f32 v[20:21], v[86:87], v[0:1], v[14:15] op_sel_hi:[1,0,1] neg_lo:[0,0,1] neg_hi:[0,0,1]
	v_mov_b32_e32 v14, v25
	v_mov_b32_e32 v15, v33
	v_mov_b32_e32 v10, v24
	v_mov_b32_e32 v11, v32
	v_pk_mul_f32 v[14:15], v[14:15], v[14:15]
	s_nop 0
	v_pk_fma_f32 v[10:11], v[10:11], v[10:11], v[14:15]
	v_mov_b32_e32 v14, v20
	v_mov_b32_e32 v15, v28
	v_pk_fma_f32 v[10:11], v[14:15], v[14:15], v[10:11]
	v_mov_b32_e32 v14, v21
	v_mov_b32_e32 v15, v29
	v_pk_fma_f32 v[38:39], v[14:15], v[14:15], v[10:11]
	v_pk_mul_f32 v[10:11], v[80:81], v[2:3] op_sel_hi:[1,0]
	v_pk_mul_f32 v[14:15], v[82:83], v[2:3] op_sel_hi:[1,0]
	v_pk_fma_f32 v[36:37], v[72:73], v[0:1], v[10:11] op_sel_hi:[1,0,1] neg_lo:[0,0,1] neg_hi:[0,0,1]
	v_pk_mul_f32 v[10:11], v[76:77], v[2:3] op_sel_hi:[1,0]
	v_pk_fma_f32 v[34:35], v[74:75], v[0:1], v[14:15] op_sel_hi:[1,0,1] neg_lo:[0,0,1] neg_hi:[0,0,1]
	v_pk_mul_f32 v[14:15], v[78:79], v[2:3] op_sel_hi:[1,0]
	v_pk_fma_f32 v[22:23], v[68:69], v[0:1], v[10:11] op_sel_hi:[1,0,1] neg_lo:[0,0,1] neg_hi:[0,0,1]
	v_pk_fma_f32 v[18:19], v[70:71], v[0:1], v[14:15] op_sel_hi:[1,0,1] neg_lo:[0,0,1] neg_hi:[0,0,1]
	v_mov_b32_e32 v14, v23
	v_mov_b32_e32 v15, v37
	v_mov_b32_e32 v10, v22
	v_mov_b32_e32 v11, v36
	v_pk_mul_f32 v[14:15], v[14:15], v[14:15]
	s_nop 0
	v_pk_fma_f32 v[10:11], v[10:11], v[10:11], v[14:15]
	v_mov_b32_e32 v14, v18
	v_mov_b32_e32 v15, v34
	v_pk_fma_f32 v[10:11], v[14:15], v[14:15], v[10:11]
	v_mov_b32_e32 v14, v19
	v_mov_b32_e32 v15, v35
	s_waitcnt vmcnt(0)
	v_pk_fma_f32 v[40:41], v[14:15], v[14:15], v[10:11]
	v_pk_mul_f32 v[14:15], v[66:67], v[2:3] op_sel_hi:[1,0]
	v_pk_mul_f32 v[10:11], v[64:65], v[2:3] op_sel_hi:[1,0]
	v_pk_fma_f32 v[26:27], v[58:59], v[0:1], v[14:15] op_sel_hi:[1,0,1] neg_lo:[0,0,1] neg_hi:[0,0,1]
	v_pk_mul_f32 v[14:15], v[60:61], v[2:3] op_sel_hi:[1,0]
	v_pk_fma_f32 v[30:31], v[56:57], v[0:1], v[10:11] op_sel_hi:[1,0,1] neg_lo:[0,0,1] neg_hi:[0,0,1]
	v_pk_mul_f32 v[2:3], v[62:63], v[2:3] op_sel_hi:[1,0]
	v_pk_fma_f32 v[14:15], v[52:53], v[0:1], v[14:15] op_sel_hi:[1,0,1] neg_lo:[0,0,1] neg_hi:[0,0,1]
	v_pk_fma_f32 v[10:11], v[54:55], v[0:1], v[2:3] op_sel_hi:[1,0,1] neg_lo:[0,0,1] neg_hi:[0,0,1]
	v_mov_b32_e32 v42, v15
	v_mov_b32_e32 v43, v31
	v_add_f32_e32 v0, v4, v5
	v_mov_b32_e32 v2, v14
	v_mov_b32_e32 v3, v30
	v_pk_mul_f32 v[42:43], v[42:43], v[42:43]
	v_add_f32_e32 v0, v39, v0
	v_pk_fma_f32 v[2:3], v[2:3], v[2:3], v[42:43]
	v_mov_b32_e32 v42, v10
	v_mov_b32_e32 v43, v26
	v_add_f32_e32 v0, v38, v0
	v_pk_fma_f32 v[2:3], v[42:43], v[42:43], v[2:3]
	v_mov_b32_e32 v42, v11
	v_mov_b32_e32 v43, v27
	v_add_f32_e32 v0, v41, v0
	v_pk_fma_f32 v[2:3], v[42:43], v[42:43], v[2:3]
	v_add_f32_e32 v0, v40, v0
	v_add_f32_e32 v0, v3, v0
	v_add_f32_e32 v0, v2, v0
	ds_bpermute_b32 v2, v195, v0
	v_lshl_add_u64 v[38:39], v[164:165], 0, v[162:163]
	s_waitcnt lgkmcnt(0)
	v_add_f32_e32 v0, v0, v2
	ds_bpermute_b32 v2, v196, v0
	s_waitcnt lgkmcnt(0)
	v_add_f32_e32 v0, v0, v2
	v_fmamk_f32 v0, v0, 0x3c000000, v177
	v_cmp_gt_f32_e32 vcc, s34, v0
	v_mul_f32_e32 v2, 0x4b800000, v0
	s_nop 0
	v_cndmask_b32_e32 v0, v0, v2, vcc
	v_rsq_f32_e32 v0, v0
	s_nop 0
	v_mul_f32_e32 v2, 0x45800000, v0
	v_cndmask_b32_e32 v0, v0, v2, vcc
	global_load_dwordx4 v[2:5], v[136:137], off
	v_mul_f32_e32 v0, v191, v0
	v_pk_mul_f32 v[16:17], v[16:17], v[0:1] op_sel_hi:[1,0]
	v_pk_mul_f32 v[12:13], v[12:13], v[0:1] op_sel_hi:[1,0]
	v_pk_mul_f32 v[8:9], v[8:9], v[0:1] op_sel_hi:[1,0]
	v_pk_mul_f32 v[6:7], v[6:7], v[0:1] op_sel_hi:[1,0]
	s_waitcnt vmcnt(0)
	v_pk_mul_f32 v[4:5], v[4:5], v[12:13]
	v_pk_mul_f32 v[2:3], v[2:3], v[16:17]
	s_nop 0
	v_cvt_pk_bf16_f32 v2, v2, v3
	v_cvt_pk_bf16_f32 v3, v4, v5
	global_store_dwordx2 v[38:39], v[2:3], off
	global_load_dwordx4 v[2:5], v[136:137], off offset:64
	s_waitcnt vmcnt(0)
	v_pk_mul_f32 v[4:5], v[4:5], v[6:7]
	v_pk_mul_f32 v[2:3], v[2:3], v[8:9]
	v_pk_mul_f32 v[6:7], v[32:33], v[0:1] op_sel_hi:[1,0]
	v_cvt_pk_bf16_f32 v2, v2, v3
	v_cvt_pk_bf16_f32 v3, v4, v5
	global_store_dwordx2 v[38:39], v[2:3], off offset:32
	global_load_dwordx4 v[2:5], v[136:137], off offset:128
	v_pk_mul_f32 v[8:9], v[28:29], v[0:1] op_sel_hi:[1,0]
	s_waitcnt vmcnt(0)
	v_pk_mul_f32 v[2:3], v[2:3], v[6:7]
	v_pk_mul_f32 v[4:5], v[4:5], v[8:9]
	v_cvt_pk_bf16_f32 v2, v2, v3
	v_cvt_pk_bf16_f32 v3, v4, v5
	global_store_dwordx2 v[38:39], v[2:3], off offset:64
	global_load_dwordx4 v[2:5], v[136:137], off offset:192
	v_pk_mul_f32 v[6:7], v[24:25], v[0:1] op_sel_hi:[1,0]
	v_pk_mul_f32 v[8:9], v[20:21], v[0:1] op_sel_hi:[1,0]
	s_waitcnt vmcnt(0)
	v_pk_mul_f32 v[2:3], v[2:3], v[6:7]
	v_pk_mul_f32 v[4:5], v[4:5], v[8:9]
	v_cvt_pk_bf16_f32 v2, v2, v3
	v_cvt_pk_bf16_f32 v3, v4, v5
	global_store_dwordx2 v[38:39], v[2:3], off offset:96
	global_load_dwordx4 v[2:5], v[136:137], off offset:256
	v_pk_mul_f32 v[6:7], v[36:37], v[0:1] op_sel_hi:[1,0]
	v_pk_mul_f32 v[8:9], v[34:35], v[0:1] op_sel_hi:[1,0]
	s_waitcnt vmcnt(0)
	v_pk_mul_f32 v[2:3], v[2:3], v[6:7]
	v_pk_mul_f32 v[4:5], v[4:5], v[8:9]
	v_cvt_pk_bf16_f32 v2, v2, v3
	v_cvt_pk_bf16_f32 v3, v4, v5
	global_store_dwordx2 v[38:39], v[2:3], off offset:128
	global_load_dwordx4 v[2:5], v[136:137], off offset:320
	v_pk_mul_f32 v[6:7], v[22:23], v[0:1] op_sel_hi:[1,0]
	v_pk_mul_f32 v[8:9], v[18:19], v[0:1] op_sel_hi:[1,0]
	s_waitcnt vmcnt(0)
	v_pk_mul_f32 v[2:3], v[2:3], v[6:7]
	v_pk_mul_f32 v[4:5], v[4:5], v[8:9]
	v_cvt_pk_bf16_f32 v2, v2, v3
	v_cvt_pk_bf16_f32 v3, v4, v5
	global_store_dwordx2 v[38:39], v[2:3], off offset:160
	global_load_dwordx4 v[2:5], v[136:137], off offset:384
	v_pk_mul_f32 v[6:7], v[30:31], v[0:1] op_sel_hi:[1,0]
	v_pk_mul_f32 v[8:9], v[26:27], v[0:1] op_sel_hi:[1,0]
	s_waitcnt vmcnt(0)
	v_pk_mul_f32 v[2:3], v[2:3], v[6:7]
	v_pk_mul_f32 v[4:5], v[4:5], v[8:9]
	v_cvt_pk_bf16_f32 v2, v2, v3
	v_cvt_pk_bf16_f32 v3, v4, v5
	global_store_dwordx2 v[38:39], v[2:3], off offset:192
	global_load_dwordx4 v[2:5], v[136:137], off offset:448
	v_pk_mul_f32 v[6:7], v[14:15], v[0:1] op_sel_hi:[1,0]
	v_pk_mul_f32 v[8:9], v[10:11], v[0:1] op_sel_hi:[1,0]
	s_waitcnt vmcnt(0)
	v_pk_mul_f32 v[2:3], v[6:7], v[2:3]
	v_pk_mul_f32 v[4:5], v[8:9], v[4:5]
	v_cvt_pk_bf16_f32 v2, v2, v3
	v_cvt_pk_bf16_f32 v3, v4, v5
	global_store_dwordx2 v[38:39], v[2:3], off offset:224
	s_mov_b32 s6, s100
	s_waitcnt lgkmcnt(0)
	s_add_i32 s40, s40, s6
	s_cmpk_gt_i32 s40, 0x7ff
	s_cbranch_scc1 .LBB0_194

.LBB0_200:
	v_mov_b32_e32 v126, v174
	v_mov_b32_e32 v166, v175
	s_ashr_i32 s9, s8, 31
	v_add3_u32 v162, s15, v189, v166
	v_ashrrev_i32_e32 v163, 31, v162
	v_lshl_add_u64 v[128:129], v[162:163], 3, s[42:43]
	global_load_dwordx2 v[130:131], v[128:129], off
	s_lshl_b64 s[6:7], s[8:9], 1
	s_add_u32 s2, s40, s6
	s_addc_u32 s3, s41, s7
	v_lshlrev_b32_e32 v170, 3, v126
	v_add_u32_e32 v126, v170, v0
	s_add_u32 s6, s12, s6
	s_addc_u32 s7, s13, s7
	v_ashrrev_i32_e32 v127, 31, v126
	v_lshlrev_b64 v[164:165], 1, v[126:127]
	v_add_u32_e32 v168, 16, v162
	v_or_b32_e32 v171, s8, v0
	v_ashrrev_i32_e32 v169, 31, v168
	v_add_u32_e32 v170, v170, v171
	v_lshlrev_b64 v[172:173], 12, v[162:163]
	v_ashrrev_i32_e32 v171, 31, v170
	v_lshl_add_u64 v[172:173], s[4:5], 0, v[172:173]
	v_add3_u32 v166, s15, v190, v166
	s_waitcnt vmcnt(0)
	v_ffbh_u32_e32 v132, v131
	v_min_u32_e32 v132, 32, v132
	v_lshlrev_b64 v[130:131], v132, v[130:131]
	v_min_u32_e32 v130, 1, v130
	v_or_b32_e32 v130, v131, v130
	v_cvt_f32_u32_e32 v130, v130
	v_sub_u32_e32 v131, 32, v132
	v_ldexp_f32 v130, v130, v131
	v_fmamk_f32 v130, v130, 0x2e800000, v177
	v_cmp_gt_f32_e32 vcc, s34, v130
	v_mul_f32_e32 v131, 0x4b800000, v130
	s_nop 0
	v_cndmask_b32_e32 v130, v130, v131, vcc
	v_rsq_f32_e32 v130, v130
	s_nop 0
	v_mul_f32_e32 v131, 0x45800000, v130
	v_cndmask_b32_e32 v167, v130, v131, vcc
	v_lshlrev_b64 v[130:131], 11, v[162:163]
	v_lshl_add_u64 v[132:133], s[2:3], 0, v[130:131]
	v_lshl_add_u64 v[130:131], s[6:7], 0, v[130:131]
	v_lshl_add_u64 v[126:127], v[132:133], 0, v[164:165]
	v_lshl_add_u64 v[130:131], v[130:131], 0, v[164:165]
	global_load_dwordx4 v[158:161], v[126:127], off
	global_load_dwordx4 v[154:157], v[130:131], off
	global_load_dwordx4 v[150:153], v[126:127], off offset:64
	global_load_dwordx4 v[146:149], v[130:131], off offset:64
	v_mul_f32_e32 v144, v144, v167
	global_load_dwordx2 v[126:127], v[128:129], off offset:128
	v_mul_f32_e32 v145, v145, v167
	v_mul_f32_e32 v144, 0xbfb8aa3b, v144
	v_mul_f32_e32 v145, 0xbfb8aa3b, v145
	v_mul_f32_e32 v122, v122, v167
	v_mul_f32_e32 v123, v123, v167
	v_exp_f32_e32 v144, v144
	v_exp_f32_e32 v145, v145
	v_mul_f32_e32 v122, 0xbfb8aa3b, v122
	v_mul_f32_e32 v123, 0xbfb8aa3b, v123
	v_mul_f32_e32 v124, v124, v167
	v_mul_f32_e32 v125, v125, v167
	v_mul_f32_e32 v142, v142, v167
	v_mul_f32_e32 v143, v143, v167
	v_exp_f32_e32 v122, v122
	v_exp_f32_e32 v123, v123
	v_mul_f32_e32 v124, 0xbfb8aa3b, v124
	v_mul_f32_e32 v125, 0xbfb8aa3b, v125
	v_mul_f32_e32 v142, 0xbfb8aa3b, v142
	v_mul_f32_e32 v143, 0xbfb8aa3b, v143
	v_exp_f32_e32 v124, v124
	v_exp_f32_e32 v125, v125
	v_exp_f32_e32 v142, v142
	v_exp_f32_e32 v143, v143
	v_mul_f32_e32 v118, v118, v167
	v_mul_f32_e32 v119, v119, v167
	v_add_f32_e32 v144, 1.0, v144
	v_add_f32_e32 v145, 1.0, v145
	v_mul_f32_e32 v118, 0xbfb8aa3b, v118
	v_mul_f32_e32 v119, 0xbfb8aa3b, v119
	v_mul_f32_e32 v120, v120, v167
	v_mul_f32_e32 v121, v121, v167
	v_rcp_f32_e32 v144, v144
	v_rcp_f32_e32 v145, v145
	v_add_f32_e32 v122, 1.0, v122
	v_add_f32_e32 v123, 1.0, v123
	v_exp_f32_e32 v118, v118
	v_exp_f32_e32 v119, v119
	v_mul_f32_e32 v120, 0xbfb8aa3b, v120
	v_mul_f32_e32 v121, 0xbfb8aa3b, v121
	v_mul_f32_e32 v114, v114, v167
	v_mul_f32_e32 v115, v115, v167
	v_rcp_f32_e32 v122, v122
	v_rcp_f32_e32 v123, v123
	v_add_f32_e32 v124, 1.0, v124
	v_add_f32_e32 v125, 1.0, v125
	v_exp_f32_e32 v120, v120
	v_exp_f32_e32 v121, v121
	v_mul_f32_e32 v114, 0xbfb8aa3b, v114
	v_mul_f32_e32 v115, 0xbfb8aa3b, v115
	v_mul_f32_e32 v116, v116, v167
	v_mul_f32_e32 v117, v117, v167
	v_add_f32_e32 v142, 1.0, v142
	v_add_f32_e32 v143, 1.0, v143
	v_rcp_f32_e32 v124, v124
	v_rcp_f32_e32 v125, v125
	v_exp_f32_e32 v114, v114
	v_exp_f32_e32 v115, v115
	v_mul_f32_e32 v116, 0xbfb8aa3b, v116
	v_mul_f32_e32 v117, 0xbfb8aa3b, v117
	v_rcp_f32_e32 v142, v142
	v_rcp_f32_e32 v143, v143
	v_exp_f32_e32 v116, v116
	v_exp_f32_e32 v117, v117
	v_add_f32_e32 v118, 1.0, v118
	v_add_f32_e32 v119, 1.0, v119
	v_rcp_f32_e32 v118, v118
	v_rcp_f32_e32 v119, v119
	v_add_f32_e32 v120, 1.0, v120
	v_add_f32_e32 v121, 1.0, v121
	v_rcp_f32_e32 v120, v120
	v_rcp_f32_e32 v121, v121
	v_add_f32_e32 v114, 1.0, v114
	v_add_f32_e32 v115, 1.0, v115
	v_rcp_f32_e32 v114, v114
	v_rcp_f32_e32 v115, v115
	s_waitcnt vmcnt(3)
	v_lshlrev_b32_e32 v194, 16, v154
	v_lshlrev_b32_e32 v192, 16, v158
	v_and_b32_e32 v193, 0xffff0000, v158
	v_and_b32_e32 v195, 0xffff0000, v154
	s_waitcnt vmcnt(0)
	v_ffbh_u32_e32 v128, v127
	v_min_u32_e32 v128, 32, v128
	v_lshlrev_b64 v[126:127], v128, v[126:127]
	v_min_u32_e32 v126, 1, v126
	v_or_b32_e32 v126, v127, v126
	v_cvt_f32_u32_e32 v126, v126
	v_sub_u32_e32 v127, 32, v128
	v_lshlrev_b32_e32 v158, 16, v159
	v_and_b32_e32 v159, 0xffff0000, v159
	v_ldexp_f32 v126, v126, v127
	v_fmamk_f32 v126, v126, 0x2e800000, v177
	v_cmp_gt_f32_e32 vcc, s34, v126
	v_mul_f32_e32 v127, 0x4b800000, v126
	v_lshlrev_b32_e32 v154, 16, v155
	v_cndmask_b32_e32 v126, v126, v127, vcc
	v_rsq_f32_e32 v126, v126
	v_and_b32_e32 v155, 0xffff0000, v155
	v_pk_fma_f32 v[144:145], v[144:145], v[154:155], v[158:159]
	v_lshlrev_b32_e32 v154, 16, v160
	v_mul_f32_e32 v127, 0x45800000, v126
	v_and_b32_e32 v155, 0xffff0000, v160
	v_lshlrev_b32_e32 v158, 16, v156
	v_and_b32_e32 v159, 0xffff0000, v156
	v_cndmask_b32_e32 v191, v126, v127, vcc
	v_lshlrev_b64 v[126:127], 11, v[168:169]
	v_pk_fma_f32 v[122:123], v[122:123], v[158:159], v[154:155]
	v_lshlrev_b32_e32 v154, 16, v161
	v_and_b32_e32 v155, 0xffff0000, v161
	v_lshlrev_b32_e32 v156, 16, v157
	v_and_b32_e32 v157, 0xffff0000, v157
	v_lshl_add_u64 v[128:129], s[2:3], 0, v[126:127]
	v_lshl_add_u64 v[126:127], s[6:7], 0, v[126:127]
	v_pk_fma_f32 v[124:125], v[124:125], v[156:157], v[154:155]
	v_lshlrev_b64 v[154:155], 2, v[170:171]
	v_lshl_add_u64 v[128:129], v[128:129], 0, v[164:165]
	v_lshl_add_u64 v[126:127], v[126:127], 0, v[164:165]
	v_pk_fma_f32 v[142:143], v[142:143], v[194:195], v[192:193]
	v_lshl_add_u64 v[156:157], v[172:173], 0, v[154:155]
	v_add_f32_e32 v116, 1.0, v116
	v_add_f32_e32 v117, 1.0, v117
	global_load_dwordx4 v[138:141], v[128:129], off
	global_load_dwordx4 v[134:137], v[126:127], off
	global_load_dwordx4 v[130:133], v[128:129], off offset:64
	s_nop 0
	global_load_dwordx4 v[126:129], v[126:127], off offset:64
	global_store_dwordx4 v[156:157], v[142:145], off
	global_store_dwordx4 v[156:157], v[122:125], off offset:16
	v_rcp_f32_e32 v116, v116
	v_rcp_f32_e32 v117, v117
	v_lshlrev_b32_e32 v122, 16, v150
	v_and_b32_e32 v123, 0xffff0000, v150
	v_lshlrev_b32_e32 v124, 16, v146
	v_and_b32_e32 v125, 0xffff0000, v146
	v_pk_fma_f32 v[118:119], v[118:119], v[124:125], v[122:123]
	v_lshlrev_b32_e32 v122, 16, v151
	v_and_b32_e32 v123, 0xffff0000, v151
	v_lshlrev_b32_e32 v124, 16, v147
	v_and_b32_e32 v125, 0xffff0000, v147
	v_pk_fma_f32 v[120:121], v[120:121], v[124:125], v[122:123]
	v_lshlrev_b32_e32 v122, 16, v152
	v_and_b32_e32 v123, 0xffff0000, v152
	v_lshlrev_b32_e32 v124, 16, v148
	v_and_b32_e32 v125, 0xffff0000, v148
	v_pk_fma_f32 v[114:115], v[114:115], v[124:125], v[122:123]
	v_lshlrev_b32_e32 v122, 16, v153
	v_and_b32_e32 v123, 0xffff0000, v153
	v_lshlrev_b32_e32 v124, 16, v149
	v_and_b32_e32 v125, 0xffff0000, v149
	v_ashrrev_i32_e32 v167, 31, v166
	v_pk_fma_f32 v[116:117], v[116:117], v[124:125], v[122:123]
	global_store_dwordx4 v[156:157], v[118:121], off offset:128
	global_store_dwordx4 v[156:157], v[114:117], off offset:144
	v_lshl_add_u64 v[146:147], v[166:167], 3, s[42:43]
	global_load_dwordx2 v[114:115], v[146:147], off
	v_mul_f32_e32 v112, v112, v191
	v_mul_f32_e32 v113, v113, v191
	v_mul_f32_e32 v112, 0xbfb8aa3b, v112
	v_mul_f32_e32 v113, 0xbfb8aa3b, v113
	v_mul_f32_e32 v106, v106, v191
	v_mul_f32_e32 v107, v107, v191
	v_mul_f32_e32 v110, v110, v191
	v_mul_f32_e32 v111, v111, v191
	v_exp_f32_e32 v112, v112
	v_exp_f32_e32 v113, v113
	v_mul_f32_e32 v106, 0xbfb8aa3b, v106
	v_mul_f32_e32 v107, 0xbfb8aa3b, v107
	v_mul_f32_e32 v108, v108, v191
	v_mul_f32_e32 v109, v109, v191
	v_mul_f32_e32 v110, 0xbfb8aa3b, v110
	v_mul_f32_e32 v111, 0xbfb8aa3b, v111
	v_exp_f32_e32 v106, v106
	v_exp_f32_e32 v107, v107
	v_mul_f32_e32 v108, 0xbfb8aa3b, v108
	v_mul_f32_e32 v109, 0xbfb8aa3b, v109
	v_exp_f32_e32 v110, v110
	v_exp_f32_e32 v111, v111
	v_exp_f32_e32 v108, v108
	v_exp_f32_e32 v109, v109
	v_mul_f32_e32 v102, v102, v191
	v_mul_f32_e32 v103, v103, v191
	v_mul_f32_e32 v102, 0xbfb8aa3b, v102
	v_mul_f32_e32 v103, 0xbfb8aa3b, v103
	v_mul_f32_e32 v104, v104, v191
	v_mul_f32_e32 v105, v105, v191
	v_add_f32_e32 v112, 1.0, v112
	v_add_f32_e32 v113, 1.0, v113
	v_exp_f32_e32 v102, v102
	v_exp_f32_e32 v103, v103
	v_mul_f32_e32 v104, 0xbfb8aa3b, v104
	v_mul_f32_e32 v105, 0xbfb8aa3b, v105
	v_mul_f32_e32 v98, v98, v191
	v_mul_f32_e32 v99, v99, v191
	v_rcp_f32_e32 v112, v112
	v_rcp_f32_e32 v113, v113
	v_add_f32_e32 v106, 1.0, v106
	v_add_f32_e32 v107, 1.0, v107
	v_exp_f32_e32 v104, v104
	v_exp_f32_e32 v105, v105
	v_mul_f32_e32 v98, 0xbfb8aa3b, v98
	v_mul_f32_e32 v99, 0xbfb8aa3b, v99
	v_mul_f32_e32 v100, v100, v191
	v_mul_f32_e32 v101, v101, v191
	v_add_f32_e32 v110, 1.0, v110
	v_add_f32_e32 v111, 1.0, v111
	v_rcp_f32_e32 v106, v106
	v_rcp_f32_e32 v107, v107
	v_add_f32_e32 v108, 1.0, v108
	v_add_f32_e32 v109, 1.0, v109
	v_exp_f32_e32 v98, v98
	v_exp_f32_e32 v99, v99
	v_mul_f32_e32 v100, 0xbfb8aa3b, v100
	v_mul_f32_e32 v101, 0xbfb8aa3b, v101
	v_rcp_f32_e32 v110, v110
	v_rcp_f32_e32 v111, v111
	v_rcp_f32_e32 v108, v108
	v_rcp_f32_e32 v109, v109
	v_exp_f32_e32 v100, v100
	v_exp_f32_e32 v101, v101
	s_waitcnt vmcnt(8)
	v_lshlrev_b32_e32 v152, 16, v138
	v_and_b32_e32 v153, 0xffff0000, v138
	s_waitcnt vmcnt(7)
	v_lshlrev_b32_e32 v156, 16, v134
	v_and_b32_e32 v157, 0xffff0000, v134
	v_lshlrev_b32_e32 v138, 16, v139
	v_and_b32_e32 v139, 0xffff0000, v139
	v_lshlrev_b32_e32 v134, 16, v135
	v_and_b32_e32 v135, 0xffff0000, v135
	v_add_f32_e32 v102, 1.0, v102
	v_add_f32_e32 v103, 1.0, v103
	v_lshlrev_b64 v[150:151], 12, v[168:169]
	v_pk_fma_f32 v[112:113], v[112:113], v[134:135], v[138:139]
	v_lshlrev_b32_e32 v134, 16, v140
	v_and_b32_e32 v135, 0xffff0000, v140
	v_lshlrev_b32_e32 v138, 16, v136
	s_waitcnt vmcnt(0)
	v_ffbh_u32_e32 v116, v115
	v_min_u32_e32 v116, 32, v116
	v_lshlrev_b64 v[114:115], v116, v[114:115]
	v_min_u32_e32 v114, 1, v114
	v_or_b32_e32 v114, v115, v114
	v_cvt_f32_u32_e32 v114, v114
	v_sub_u32_e32 v115, 32, v116
	v_and_b32_e32 v139, 0xffff0000, v136
	v_rcp_f32_e32 v102, v102
	v_ldexp_f32 v114, v114, v115
	v_fmamk_f32 v114, v114, 0x2e800000, v177
	v_cmp_gt_f32_e32 vcc, s34, v114
	v_mul_f32_e32 v115, 0x4b800000, v114
	v_rcp_f32_e32 v103, v103
	v_cndmask_b32_e32 v114, v114, v115, vcc
	v_rsq_f32_e32 v114, v114
	v_add_f32_e32 v104, 1.0, v104
	v_add_f32_e32 v105, 1.0, v105
	v_lshl_add_u64 v[150:151], s[4:5], 0, v[150:151]
	v_mul_f32_e32 v115, 0x45800000, v114
	v_cndmask_b32_e32 v148, v114, v115, vcc
	v_lshlrev_b64 v[114:115], 11, v[166:167]
	v_lshl_add_u64 v[116:117], s[2:3], 0, v[114:115]
	v_lshl_add_u64 v[114:115], s[6:7], 0, v[114:115]
	v_pk_fma_f32 v[106:107], v[106:107], v[138:139], v[134:135]
	v_lshlrev_b32_e32 v134, 16, v141
	v_and_b32_e32 v135, 0xffff0000, v141
	v_lshlrev_b32_e32 v136, 16, v137
	v_and_b32_e32 v137, 0xffff0000, v137
	v_rcp_f32_e32 v104, v104
	v_rcp_f32_e32 v105, v105
	v_add_f32_e32 v98, 1.0, v98
	v_add_f32_e32 v99, 1.0, v99
	v_lshl_add_u64 v[116:117], v[116:117], 0, v[164:165]
	v_lshl_add_u64 v[114:115], v[114:115], 0, v[164:165]
	v_pk_fma_f32 v[110:111], v[110:111], v[156:157], v[152:153]
	v_pk_fma_f32 v[108:109], v[108:109], v[136:137], v[134:135]
	v_lshl_add_u64 v[134:135], v[150:151], 0, v[154:155]
	v_rcp_f32_e32 v98, v98
	v_rcp_f32_e32 v99, v99
	v_add_f32_e32 v100, 1.0, v100
	v_add_f32_e32 v101, 1.0, v101
	global_load_dwordx4 v[142:145], v[116:117], off
	global_load_dwordx4 v[122:125], v[114:115], off
	global_load_dwordx4 v[118:121], v[116:117], off offset:64
	s_nop 0
	global_load_dwordx4 v[114:117], v[114:115], off offset:64
	global_store_dwordx4 v[134:135], v[110:113], off
	global_store_dwordx4 v[134:135], v[106:109], off offset:16
	v_rcp_f32_e32 v100, v100
	v_rcp_f32_e32 v101, v101
	v_lshlrev_b32_e32 v106, 16, v130
	v_and_b32_e32 v107, 0xffff0000, v130
	v_lshlrev_b32_e32 v108, 16, v126
	v_and_b32_e32 v109, 0xffff0000, v126
	v_pk_fma_f32 v[102:103], v[102:103], v[108:109], v[106:107]
	v_lshlrev_b32_e32 v106, 16, v131
	v_and_b32_e32 v107, 0xffff0000, v131
	v_lshlrev_b32_e32 v108, 16, v127
	v_and_b32_e32 v109, 0xffff0000, v127
	v_pk_fma_f32 v[104:105], v[104:105], v[108:109], v[106:107]
	v_lshlrev_b32_e32 v106, 16, v132
	v_and_b32_e32 v107, 0xffff0000, v132
	v_lshlrev_b32_e32 v108, 16, v128
	v_and_b32_e32 v109, 0xffff0000, v128
	v_pk_fma_f32 v[98:99], v[98:99], v[108:109], v[106:107]
	v_lshlrev_b32_e32 v106, 16, v133
	v_and_b32_e32 v107, 0xffff0000, v133
	v_lshlrev_b32_e32 v108, 16, v129
	v_and_b32_e32 v109, 0xffff0000, v129
	v_pk_fma_f32 v[100:101], v[100:101], v[108:109], v[106:107]
	global_store_dwordx4 v[134:135], v[102:105], off offset:128
	global_store_dwordx4 v[134:135], v[98:101], off offset:144
	global_load_dwordx2 v[100:101], v[146:147], off offset:128
	v_mul_f32_e32 v94, v94, v148
	v_mul_f32_e32 v95, v95, v148
	v_mul_f32_e32 v94, 0xbfb8aa3b, v94
	v_mul_f32_e32 v95, 0xbfb8aa3b, v95
	v_mul_f32_e32 v96, v96, v148
	v_mul_f32_e32 v97, v97, v148
	v_exp_f32_e32 v94, v94
	v_exp_f32_e32 v95, v95
	v_mul_f32_e32 v96, 0xbfb8aa3b, v96
	v_mul_f32_e32 v97, 0xbfb8aa3b, v97
	v_mul_f32_e32 v90, v90, v148
	v_mul_f32_e32 v91, v91, v148
	v_exp_f32_e32 v96, v96
	v_exp_f32_e32 v97, v97
	v_mul_f32_e32 v90, 0xbfb8aa3b, v90
	v_mul_f32_e32 v91, 0xbfb8aa3b, v91
	v_mul_f32_e32 v92, v92, v148
	v_mul_f32_e32 v93, v93, v148
	v_exp_f32_e32 v90, v90
	v_exp_f32_e32 v91, v91
	v_mul_f32_e32 v92, 0xbfb8aa3b, v92
	v_mul_f32_e32 v93, 0xbfb8aa3b, v93
	v_exp_f32_e32 v92, v92
	v_exp_f32_e32 v93, v93
	v_mul_f32_e32 v86, v86, v148
	v_mul_f32_e32 v87, v87, v148
	v_add_f32_e32 v94, 1.0, v94
	v_add_f32_e32 v95, 1.0, v95
	v_mul_f32_e32 v86, 0xbfb8aa3b, v86
	v_mul_f32_e32 v87, 0xbfb8aa3b, v87
	v_mul_f32_e32 v88, v88, v148
	v_mul_f32_e32 v89, v89, v148
	v_rcp_f32_e32 v94, v94
	v_rcp_f32_e32 v95, v95
	v_add_f32_e32 v96, 1.0, v96
	v_add_f32_e32 v97, 1.0, v97
	v_exp_f32_e32 v86, v86
	v_exp_f32_e32 v87, v87
	v_mul_f32_e32 v88, 0xbfb8aa3b, v88
	v_mul_f32_e32 v89, 0xbfb8aa3b, v89
	v_mul_f32_e32 v82, v82, v148
	v_mul_f32_e32 v83, v83, v148
	v_rcp_f32_e32 v96, v96
	v_rcp_f32_e32 v97, v97
	v_add_f32_e32 v90, 1.0, v90
	v_add_f32_e32 v91, 1.0, v91
	v_exp_f32_e32 v88, v88
	v_exp_f32_e32 v89, v89
	v_mul_f32_e32 v82, 0xbfb8aa3b, v82
	v_mul_f32_e32 v83, 0xbfb8aa3b, v83
	v_mul_f32_e32 v84, v84, v148
	v_mul_f32_e32 v85, v85, v148
	v_rcp_f32_e32 v90, v90
	v_rcp_f32_e32 v91, v91
	v_add_f32_e32 v92, 1.0, v92
	v_add_f32_e32 v93, 1.0, v93
	v_exp_f32_e32 v82, v82
	v_exp_f32_e32 v83, v83
	v_mul_f32_e32 v84, 0xbfb8aa3b, v84
	v_mul_f32_e32 v85, 0xbfb8aa3b, v85
	v_add_u32_e32 v98, 16, v166
	v_add_u32_e32 v128, 32, v162
	s_waitcnt vmcnt(8)
	v_lshlrev_b32_e32 v130, 16, v142
	v_and_b32_e32 v131, 0xffff0000, v142
	s_waitcnt vmcnt(7)
	v_lshlrev_b32_e32 v132, 16, v122
	v_and_b32_e32 v133, 0xffff0000, v122
	v_rcp_f32_e32 v92, v92
	v_rcp_f32_e32 v93, v93
	v_exp_f32_e32 v84, v84
	v_exp_f32_e32 v85, v85
	v_ashrrev_i32_e32 v99, 31, v98
	v_ashrrev_i32_e32 v129, 31, v128
	v_pk_fma_f32 v[94:95], v[94:95], v[132:133], v[130:131]
	v_lshlrev_b32_e32 v130, 16, v143
	v_and_b32_e32 v131, 0xffff0000, v143
	v_lshlrev_b32_e32 v122, 16, v123
	v_and_b32_e32 v123, 0xffff0000, v123
	v_add_f32_e32 v86, 1.0, v86
	v_add_f32_e32 v87, 1.0, v87
	s_waitcnt vmcnt(0)
	v_ffbh_u32_e32 v102, v101
	v_min_u32_e32 v102, 32, v102
	v_lshlrev_b64 v[100:101], v102, v[100:101]
	v_min_u32_e32 v100, 1, v100
	v_or_b32_e32 v100, v101, v100
	v_cvt_f32_u32_e32 v100, v100
	v_sub_u32_e32 v101, 32, v102
	v_lshlrev_b64 v[98:99], 11, v[98:99]
	v_lshlrev_b64 v[128:129], 12, v[128:129]
	v_ldexp_f32 v100, v100, v101
	v_fmamk_f32 v100, v100, 0x2e800000, v177
	v_cmp_gt_f32_e32 vcc, s34, v100
	v_mul_f32_e32 v101, 0x4b800000, v100
	v_pk_fma_f32 v[96:97], v[96:97], v[122:123], v[130:131]
	v_cndmask_b32_e32 v100, v100, v101, vcc
	v_rsq_f32_e32 v100, v100
	v_lshlrev_b32_e32 v122, 16, v144
	v_and_b32_e32 v123, 0xffff0000, v144
	v_lshlrev_b32_e32 v130, 16, v124
	v_mul_f32_e32 v101, 0x45800000, v100
	v_and_b32_e32 v131, 0xffff0000, v124
	v_rcp_f32_e32 v86, v86
	v_rcp_f32_e32 v87, v87
	v_add_f32_e32 v88, 1.0, v88
	v_add_f32_e32 v89, 1.0, v89
	v_cndmask_b32_e32 v126, v100, v101, vcc
	v_lshl_add_u64 v[100:101], s[2:3], 0, v[98:99]
	v_lshl_add_u64 v[98:99], s[6:7], 0, v[98:99]
	v_lshl_add_u64 v[128:129], s[4:5], 0, v[128:129]
	v_pk_fma_f32 v[90:91], v[90:91], v[130:131], v[122:123]
	v_lshlrev_b32_e32 v122, 16, v145
	v_and_b32_e32 v123, 0xffff0000, v145
	v_lshlrev_b32_e32 v124, 16, v125
	v_and_b32_e32 v125, 0xffff0000, v125
	v_rcp_f32_e32 v88, v88
	v_rcp_f32_e32 v89, v89
	v_add_f32_e32 v82, 1.0, v82
	v_add_f32_e32 v83, 1.0, v83
	v_lshl_add_u64 v[100:101], v[100:101], 0, v[164:165]
	v_lshl_add_u64 v[98:99], v[98:99], 0, v[164:165]
	v_pk_fma_f32 v[92:93], v[92:93], v[124:125], v[122:123]
	v_lshl_add_u64 v[122:123], v[128:129], 0, v[154:155]
	v_rcp_f32_e32 v82, v82
	v_rcp_f32_e32 v83, v83
	v_add_f32_e32 v84, 1.0, v84
	v_add_f32_e32 v85, 1.0, v85
	global_load_dwordx4 v[106:109], v[100:101], off
	global_load_dwordx4 v[110:113], v[98:99], off
	global_load_dwordx4 v[102:105], v[100:101], off offset:64
	s_nop 0
	global_load_dwordx4 v[98:101], v[98:99], off offset:64
	global_store_dwordx4 v[122:123], v[94:97], off
	global_store_dwordx4 v[122:123], v[90:93], off offset:16
	v_rcp_f32_e32 v84, v84
	v_rcp_f32_e32 v85, v85
	v_lshlrev_b32_e32 v90, 16, v118
	v_and_b32_e32 v91, 0xffff0000, v118
	v_lshlrev_b32_e32 v92, 16, v114
	v_and_b32_e32 v93, 0xffff0000, v114
	v_pk_fma_f32 v[86:87], v[86:87], v[92:93], v[90:91]
	v_lshlrev_b32_e32 v90, 16, v119
	v_and_b32_e32 v91, 0xffff0000, v119
	v_lshlrev_b32_e32 v92, 16, v115
	v_and_b32_e32 v93, 0xffff0000, v115
	v_pk_fma_f32 v[88:89], v[88:89], v[92:93], v[90:91]
	v_lshlrev_b32_e32 v90, 16, v120
	v_and_b32_e32 v91, 0xffff0000, v120
	v_lshlrev_b32_e32 v92, 16, v116
	v_and_b32_e32 v93, 0xffff0000, v116
	v_pk_fma_f32 v[82:83], v[82:83], v[92:93], v[90:91]
	v_lshlrev_b32_e32 v90, 16, v121
	v_and_b32_e32 v91, 0xffff0000, v121
	v_lshlrev_b32_e32 v92, 16, v117
	v_and_b32_e32 v93, 0xffff0000, v117
	v_pk_fma_f32 v[84:85], v[84:85], v[92:93], v[90:91]
	global_store_dwordx4 v[122:123], v[86:89], off offset:128
	global_store_dwordx4 v[122:123], v[82:85], off offset:144
	global_load_dwordx2 v[84:85], v[146:147], off offset:256
	v_mul_f32_e32 v80, v80, v126
	v_mul_f32_e32 v81, v81, v126
	v_mul_f32_e32 v80, 0xbfb8aa3b, v80
	v_mul_f32_e32 v81, 0xbfb8aa3b, v81
	v_mul_f32_e32 v74, v74, v126
	v_mul_f32_e32 v75, v75, v126
	v_mul_f32_e32 v78, v78, v126
	v_mul_f32_e32 v79, v79, v126
	v_exp_f32_e32 v80, v80
	v_exp_f32_e32 v81, v81
	v_mul_f32_e32 v74, 0xbfb8aa3b, v74
	v_mul_f32_e32 v75, 0xbfb8aa3b, v75
	v_mul_f32_e32 v76, v76, v126
	v_mul_f32_e32 v77, v77, v126
	v_mul_f32_e32 v78, 0xbfb8aa3b, v78
	v_mul_f32_e32 v79, 0xbfb8aa3b, v79
	v_exp_f32_e32 v74, v74
	v_exp_f32_e32 v75, v75
	v_mul_f32_e32 v76, 0xbfb8aa3b, v76
	v_mul_f32_e32 v77, 0xbfb8aa3b, v77
	v_exp_f32_e32 v78, v78
	v_exp_f32_e32 v79, v79
	v_exp_f32_e32 v76, v76
	v_exp_f32_e32 v77, v77
	v_mul_f32_e32 v70, v70, v126
	v_mul_f32_e32 v71, v71, v126
	v_mul_f32_e32 v70, 0xbfb8aa3b, v70
	v_mul_f32_e32 v71, 0xbfb8aa3b, v71
	v_mul_f32_e32 v72, v72, v126
	v_mul_f32_e32 v73, v73, v126
	v_add_f32_e32 v80, 1.0, v80
	v_add_f32_e32 v81, 1.0, v81
	v_exp_f32_e32 v70, v70
	v_exp_f32_e32 v71, v71
	v_mul_f32_e32 v72, 0xbfb8aa3b, v72
	v_mul_f32_e32 v73, 0xbfb8aa3b, v73
	v_mul_f32_e32 v66, v66, v126
	v_mul_f32_e32 v67, v67, v126
	v_rcp_f32_e32 v80, v80
	v_rcp_f32_e32 v81, v81
	v_add_f32_e32 v74, 1.0, v74
	v_add_f32_e32 v75, 1.0, v75
	v_exp_f32_e32 v72, v72
	v_exp_f32_e32 v73, v73
	v_mul_f32_e32 v66, 0xbfb8aa3b, v66
	v_mul_f32_e32 v67, 0xbfb8aa3b, v67
	v_mul_f32_e32 v68, v68, v126
	v_mul_f32_e32 v69, v69, v126
	v_add_f32_e32 v78, 1.0, v78
	v_add_f32_e32 v79, 1.0, v79
	v_rcp_f32_e32 v74, v74
	v_rcp_f32_e32 v75, v75
	v_add_f32_e32 v76, 1.0, v76
	v_add_f32_e32 v77, 1.0, v77
	v_exp_f32_e32 v66, v66
	v_exp_f32_e32 v67, v67
	v_mul_f32_e32 v68, 0xbfb8aa3b, v68
	v_mul_f32_e32 v69, 0xbfb8aa3b, v69
	v_add_u32_e32 v82, 32, v166
	v_add_u32_e32 v116, 48, v162
	v_rcp_f32_e32 v78, v78
	v_rcp_f32_e32 v79, v79
	v_rcp_f32_e32 v76, v76
	v_rcp_f32_e32 v77, v77
	v_exp_f32_e32 v68, v68
	v_exp_f32_e32 v69, v69
	v_ashrrev_i32_e32 v83, 31, v82
	v_ashrrev_i32_e32 v117, 31, v116
	s_waitcnt vmcnt(8)
	v_lshlrev_b32_e32 v118, 16, v106
	v_and_b32_e32 v119, 0xffff0000, v106
	s_waitcnt vmcnt(7)
	v_lshlrev_b32_e32 v120, 16, v110
	v_and_b32_e32 v121, 0xffff0000, v110
	v_lshlrev_b32_e32 v106, 16, v107
	v_and_b32_e32 v107, 0xffff0000, v107
	v_lshlrev_b32_e32 v110, 16, v111
	v_and_b32_e32 v111, 0xffff0000, v111
	v_add_f32_e32 v70, 1.0, v70
	v_add_f32_e32 v71, 1.0, v71
	v_lshlrev_b64 v[82:83], 11, v[82:83]
	s_waitcnt vmcnt(0)
	v_ffbh_u32_e32 v86, v85
	v_min_u32_e32 v86, 32, v86
	v_lshlrev_b64 v[84:85], v86, v[84:85]
	v_min_u32_e32 v84, 1, v84
	v_or_b32_e32 v84, v85, v84
	v_cvt_f32_u32_e32 v84, v84
	v_sub_u32_e32 v85, 32, v86
	v_lshlrev_b64 v[116:117], 12, v[116:117]
	v_pk_fma_f32 v[80:81], v[80:81], v[110:111], v[106:107]
	v_ldexp_f32 v84, v84, v85
	v_fmamk_f32 v84, v84, 0x2e800000, v177
	v_cmp_gt_f32_e32 vcc, s34, v84
	v_mul_f32_e32 v85, 0x4b800000, v84
	v_lshlrev_b32_e32 v106, 16, v108
	v_cndmask_b32_e32 v84, v84, v85, vcc
	v_rsq_f32_e32 v84, v84
	v_and_b32_e32 v107, 0xffff0000, v108
	v_lshlrev_b32_e32 v110, 16, v112
	v_and_b32_e32 v111, 0xffff0000, v112
	v_mul_f32_e32 v85, 0x45800000, v84
	v_rcp_f32_e32 v70, v70
	v_rcp_f32_e32 v71, v71
	v_add_f32_e32 v72, 1.0, v72
	v_add_f32_e32 v73, 1.0, v73
	v_cndmask_b32_e32 v114, v84, v85, vcc
	v_lshl_add_u64 v[84:85], s[2:3], 0, v[82:83]
	v_lshl_add_u64 v[82:83], s[6:7], 0, v[82:83]
	v_lshl_add_u64 v[116:117], s[4:5], 0, v[116:117]
	v_pk_fma_f32 v[74:75], v[74:75], v[110:111], v[106:107]
	v_lshlrev_b32_e32 v106, 16, v109
	v_and_b32_e32 v107, 0xffff0000, v109
	v_lshlrev_b32_e32 v108, 16, v113
	v_and_b32_e32 v109, 0xffff0000, v113
	v_rcp_f32_e32 v72, v72
	v_rcp_f32_e32 v73, v73
	v_add_f32_e32 v66, 1.0, v66
	v_add_f32_e32 v67, 1.0, v67
	v_lshl_add_u64 v[84:85], v[84:85], 0, v[164:165]
	v_lshl_add_u64 v[82:83], v[82:83], 0, v[164:165]
	v_pk_fma_f32 v[78:79], v[78:79], v[120:121], v[118:119]
	v_pk_fma_f32 v[76:77], v[76:77], v[108:109], v[106:107]
	v_lshl_add_u64 v[106:107], v[116:117], 0, v[154:155]
	v_rcp_f32_e32 v66, v66
	v_rcp_f32_e32 v67, v67
	v_add_f32_e32 v68, 1.0, v68
	v_add_f32_e32 v69, 1.0, v69
	global_load_dwordx4 v[94:97], v[84:85], off
	global_load_dwordx4 v[90:93], v[82:83], off
	global_load_dwordx4 v[86:89], v[84:85], off offset:64
	s_nop 0
	global_load_dwordx4 v[82:85], v[82:83], off offset:64
	global_store_dwordx4 v[106:107], v[78:81], off
	global_store_dwordx4 v[106:107], v[74:77], off offset:16
	v_rcp_f32_e32 v68, v68
	v_rcp_f32_e32 v69, v69
	v_lshlrev_b32_e32 v74, 16, v102
	v_and_b32_e32 v75, 0xffff0000, v102
	v_lshlrev_b32_e32 v76, 16, v98
	v_and_b32_e32 v77, 0xffff0000, v98
	v_pk_fma_f32 v[70:71], v[70:71], v[76:77], v[74:75]
	v_lshlrev_b32_e32 v74, 16, v103
	v_and_b32_e32 v75, 0xffff0000, v103
	v_lshlrev_b32_e32 v76, 16, v99
	v_and_b32_e32 v77, 0xffff0000, v99
	v_pk_fma_f32 v[72:73], v[72:73], v[76:77], v[74:75]
	v_lshlrev_b32_e32 v74, 16, v104
	v_and_b32_e32 v75, 0xffff0000, v104
	v_lshlrev_b32_e32 v76, 16, v100
	v_and_b32_e32 v77, 0xffff0000, v100
	v_pk_fma_f32 v[66:67], v[66:67], v[76:77], v[74:75]
	v_lshlrev_b32_e32 v74, 16, v105
	v_and_b32_e32 v75, 0xffff0000, v105
	v_lshlrev_b32_e32 v76, 16, v101
	v_and_b32_e32 v77, 0xffff0000, v101
	v_pk_fma_f32 v[68:69], v[68:69], v[76:77], v[74:75]
	global_store_dwordx4 v[106:107], v[70:73], off offset:128
	global_store_dwordx4 v[106:107], v[66:69], off offset:144
	global_load_dwordx2 v[68:69], v[146:147], off offset:384
	v_mul_f32_e32 v64, v64, v114
	v_mul_f32_e32 v65, v65, v114
	v_mul_f32_e32 v64, 0xbfb8aa3b, v64
	v_mul_f32_e32 v65, 0xbfb8aa3b, v65
	v_mul_f32_e32 v58, v58, v114
	v_mul_f32_e32 v59, v59, v114
	v_mul_f32_e32 v62, v62, v114
	v_mul_f32_e32 v63, v63, v114
	v_exp_f32_e32 v64, v64
	v_exp_f32_e32 v65, v65
	v_mul_f32_e32 v58, 0xbfb8aa3b, v58
	v_mul_f32_e32 v59, 0xbfb8aa3b, v59
	v_mul_f32_e32 v60, v60, v114
	v_mul_f32_e32 v61, v61, v114
	v_mul_f32_e32 v62, 0xbfb8aa3b, v62
	v_mul_f32_e32 v63, 0xbfb8aa3b, v63
	v_exp_f32_e32 v58, v58
	v_exp_f32_e32 v59, v59
	v_mul_f32_e32 v60, 0xbfb8aa3b, v60
	v_mul_f32_e32 v61, 0xbfb8aa3b, v61
	v_exp_f32_e32 v62, v62
	v_exp_f32_e32 v63, v63
	v_exp_f32_e32 v60, v60
	v_exp_f32_e32 v61, v61
	v_mul_f32_e32 v54, v54, v114
	v_mul_f32_e32 v55, v55, v114
	v_mul_f32_e32 v54, 0xbfb8aa3b, v54
	v_mul_f32_e32 v55, 0xbfb8aa3b, v55
	v_mul_f32_e32 v56, v56, v114
	v_mul_f32_e32 v57, v57, v114
	v_add_f32_e32 v64, 1.0, v64
	v_add_f32_e32 v65, 1.0, v65
	v_exp_f32_e32 v54, v54
	v_exp_f32_e32 v55, v55
	v_mul_f32_e32 v56, 0xbfb8aa3b, v56
	v_mul_f32_e32 v57, 0xbfb8aa3b, v57
	v_mul_f32_e32 v50, v50, v114
	v_mul_f32_e32 v51, v51, v114
	v_rcp_f32_e32 v64, v64
	v_rcp_f32_e32 v65, v65
	v_add_f32_e32 v58, 1.0, v58
	v_add_f32_e32 v59, 1.0, v59
	v_exp_f32_e32 v56, v56
	v_exp_f32_e32 v57, v57
	v_mul_f32_e32 v50, 0xbfb8aa3b, v50
	v_mul_f32_e32 v51, 0xbfb8aa3b, v51
	v_mul_f32_e32 v52, v52, v114
	v_mul_f32_e32 v53, v53, v114
	v_add_f32_e32 v62, 1.0, v62
	v_add_f32_e32 v63, 1.0, v63
	v_rcp_f32_e32 v58, v58
	v_rcp_f32_e32 v59, v59
	v_add_f32_e32 v60, 1.0, v60
	v_add_f32_e32 v61, 1.0, v61
	v_exp_f32_e32 v50, v50
	v_exp_f32_e32 v51, v51
	v_mul_f32_e32 v52, 0xbfb8aa3b, v52
	v_mul_f32_e32 v53, 0xbfb8aa3b, v53
	v_add_u32_e32 v66, 48, v166
	v_add_u32_e32 v100, 64, v162
	v_rcp_f32_e32 v62, v62
	v_rcp_f32_e32 v63, v63
	v_rcp_f32_e32 v60, v60
	v_rcp_f32_e32 v61, v61
	v_exp_f32_e32 v52, v52
	v_exp_f32_e32 v53, v53
	v_ashrrev_i32_e32 v67, 31, v66
	v_ashrrev_i32_e32 v101, 31, v100
	s_waitcnt vmcnt(8)
	v_lshlrev_b32_e32 v102, 16, v94
	v_and_b32_e32 v103, 0xffff0000, v94
	s_waitcnt vmcnt(7)
	v_lshlrev_b32_e32 v104, 16, v90
	v_and_b32_e32 v105, 0xffff0000, v90
	v_lshlrev_b32_e32 v94, 16, v95
	v_and_b32_e32 v95, 0xffff0000, v95
	v_lshlrev_b32_e32 v90, 16, v91
	v_and_b32_e32 v91, 0xffff0000, v91
	v_add_f32_e32 v54, 1.0, v54
	v_add_f32_e32 v55, 1.0, v55
	v_lshlrev_b64 v[66:67], 11, v[66:67]
	s_waitcnt vmcnt(0)
	v_ffbh_u32_e32 v70, v69
	v_min_u32_e32 v70, 32, v70
	v_lshlrev_b64 v[68:69], v70, v[68:69]
	v_min_u32_e32 v68, 1, v68
	v_or_b32_e32 v68, v69, v68
	v_cvt_f32_u32_e32 v68, v68
	v_sub_u32_e32 v69, 32, v70
	v_lshlrev_b64 v[100:101], 12, v[100:101]
	v_pk_fma_f32 v[64:65], v[64:65], v[90:91], v[94:95]
	v_ldexp_f32 v68, v68, v69
	v_fmamk_f32 v68, v68, 0x2e800000, v177
	v_cmp_gt_f32_e32 vcc, s34, v68
	v_mul_f32_e32 v69, 0x4b800000, v68
	v_lshlrev_b32_e32 v90, 16, v96
	v_cndmask_b32_e32 v68, v68, v69, vcc
	v_rsq_f32_e32 v68, v68
	v_and_b32_e32 v91, 0xffff0000, v96
	v_lshlrev_b32_e32 v94, 16, v92
	v_and_b32_e32 v95, 0xffff0000, v92
	v_mul_f32_e32 v69, 0x45800000, v68
	v_rcp_f32_e32 v54, v54
	v_rcp_f32_e32 v55, v55
	v_add_f32_e32 v56, 1.0, v56
	v_add_f32_e32 v57, 1.0, v57
	v_cndmask_b32_e32 v98, v68, v69, vcc
	v_lshl_add_u64 v[68:69], s[2:3], 0, v[66:67]
	v_lshl_add_u64 v[66:67], s[6:7], 0, v[66:67]
	v_lshl_add_u64 v[100:101], s[4:5], 0, v[100:101]
	v_pk_fma_f32 v[58:59], v[58:59], v[94:95], v[90:91]
	v_lshlrev_b32_e32 v90, 16, v97
	v_and_b32_e32 v91, 0xffff0000, v97
	v_lshlrev_b32_e32 v92, 16, v93
	v_and_b32_e32 v93, 0xffff0000, v93
	v_rcp_f32_e32 v56, v56
	v_rcp_f32_e32 v57, v57
	v_add_f32_e32 v50, 1.0, v50
	v_add_f32_e32 v51, 1.0, v51
	v_lshl_add_u64 v[68:69], v[68:69], 0, v[164:165]
	v_lshl_add_u64 v[66:67], v[66:67], 0, v[164:165]
	v_pk_fma_f32 v[62:63], v[62:63], v[104:105], v[102:103]
	v_pk_fma_f32 v[60:61], v[60:61], v[92:93], v[90:91]
	v_lshl_add_u64 v[90:91], v[100:101], 0, v[154:155]
	v_rcp_f32_e32 v50, v50
	v_rcp_f32_e32 v51, v51
	v_add_f32_e32 v52, 1.0, v52
	v_add_f32_e32 v53, 1.0, v53
	global_load_dwordx4 v[74:77], v[68:69], off
	global_load_dwordx4 v[78:81], v[66:67], off
	global_load_dwordx4 v[70:73], v[68:69], off offset:64
	s_nop 0
	global_load_dwordx4 v[66:69], v[66:67], off offset:64
	global_store_dwordx4 v[90:91], v[62:65], off
	global_store_dwordx4 v[90:91], v[58:61], off offset:16
	v_rcp_f32_e32 v52, v52
	v_rcp_f32_e32 v53, v53
	v_lshlrev_b32_e32 v58, 16, v86
	v_and_b32_e32 v59, 0xffff0000, v86
	v_lshlrev_b32_e32 v60, 16, v82
	v_and_b32_e32 v61, 0xffff0000, v82
	v_pk_fma_f32 v[54:55], v[54:55], v[60:61], v[58:59]
	v_lshlrev_b32_e32 v58, 16, v87
	v_and_b32_e32 v59, 0xffff0000, v87
	v_lshlrev_b32_e32 v60, 16, v83
	v_and_b32_e32 v61, 0xffff0000, v83
	v_pk_fma_f32 v[56:57], v[56:57], v[60:61], v[58:59]
	v_lshlrev_b32_e32 v58, 16, v88
	v_and_b32_e32 v59, 0xffff0000, v88
	v_lshlrev_b32_e32 v60, 16, v84
	v_and_b32_e32 v61, 0xffff0000, v84
	v_pk_fma_f32 v[50:51], v[50:51], v[60:61], v[58:59]
	v_lshlrev_b32_e32 v58, 16, v89
	v_and_b32_e32 v59, 0xffff0000, v89
	v_lshlrev_b32_e32 v60, 16, v85
	v_and_b32_e32 v61, 0xffff0000, v85
	v_pk_fma_f32 v[52:53], v[52:53], v[60:61], v[58:59]
	global_store_dwordx4 v[90:91], v[54:57], off offset:128
	global_store_dwordx4 v[90:91], v[50:53], off offset:144
	global_load_dwordx2 v[52:53], v[146:147], off offset:512
	v_mul_f32_e32 v48, v48, v98
	v_mul_f32_e32 v49, v49, v98
	v_mul_f32_e32 v48, 0xbfb8aa3b, v48
	v_mul_f32_e32 v49, 0xbfb8aa3b, v49
	v_mul_f32_e32 v42, v42, v98
	v_mul_f32_e32 v43, v43, v98
	v_mul_f32_e32 v46, v46, v98
	v_mul_f32_e32 v47, v47, v98
	v_exp_f32_e32 v48, v48
	v_exp_f32_e32 v49, v49
	v_mul_f32_e32 v42, 0xbfb8aa3b, v42
	v_mul_f32_e32 v43, 0xbfb8aa3b, v43
	v_mul_f32_e32 v44, v44, v98
	v_mul_f32_e32 v45, v45, v98
	v_mul_f32_e32 v46, 0xbfb8aa3b, v46
	v_mul_f32_e32 v47, 0xbfb8aa3b, v47
	v_exp_f32_e32 v42, v42
	v_exp_f32_e32 v43, v43
	v_mul_f32_e32 v44, 0xbfb8aa3b, v44
	v_mul_f32_e32 v45, 0xbfb8aa3b, v45
	v_exp_f32_e32 v46, v46
	v_exp_f32_e32 v47, v47
	v_exp_f32_e32 v44, v44
	v_exp_f32_e32 v45, v45
	v_mul_f32_e32 v38, v38, v98
	v_mul_f32_e32 v39, v39, v98
	v_mul_f32_e32 v38, 0xbfb8aa3b, v38
	v_mul_f32_e32 v39, 0xbfb8aa3b, v39
	v_mul_f32_e32 v40, v40, v98
	v_mul_f32_e32 v41, v41, v98
	v_add_f32_e32 v48, 1.0, v48
	v_add_f32_e32 v49, 1.0, v49
	v_exp_f32_e32 v38, v38
	v_exp_f32_e32 v39, v39
	v_mul_f32_e32 v40, 0xbfb8aa3b, v40
	v_mul_f32_e32 v41, 0xbfb8aa3b, v41
	v_mul_f32_e32 v34, v34, v98
	v_mul_f32_e32 v35, v35, v98
	v_rcp_f32_e32 v48, v48
	v_rcp_f32_e32 v49, v49
	v_add_f32_e32 v42, 1.0, v42
	v_add_f32_e32 v43, 1.0, v43
	v_exp_f32_e32 v40, v40
	v_exp_f32_e32 v41, v41
	v_mul_f32_e32 v34, 0xbfb8aa3b, v34
	v_mul_f32_e32 v35, 0xbfb8aa3b, v35
	v_mul_f32_e32 v36, v36, v98
	v_mul_f32_e32 v37, v37, v98
	v_add_f32_e32 v46, 1.0, v46
	v_add_f32_e32 v47, 1.0, v47
	v_rcp_f32_e32 v42, v42
	v_rcp_f32_e32 v43, v43
	v_add_f32_e32 v44, 1.0, v44
	v_add_f32_e32 v45, 1.0, v45
	v_exp_f32_e32 v34, v34
	v_exp_f32_e32 v35, v35
	v_mul_f32_e32 v36, 0xbfb8aa3b, v36
	v_mul_f32_e32 v37, 0xbfb8aa3b, v37
	v_add_u32_e32 v50, 64, v166
	v_add_u32_e32 v84, 0x50, v162
	v_rcp_f32_e32 v46, v46
	v_rcp_f32_e32 v47, v47
	v_rcp_f32_e32 v44, v44
	v_rcp_f32_e32 v45, v45
	v_exp_f32_e32 v36, v36
	v_exp_f32_e32 v37, v37
	v_ashrrev_i32_e32 v51, 31, v50
	v_ashrrev_i32_e32 v85, 31, v84
	s_waitcnt vmcnt(8)
	v_lshlrev_b32_e32 v86, 16, v74
	v_and_b32_e32 v87, 0xffff0000, v74
	s_waitcnt vmcnt(7)
	v_lshlrev_b32_e32 v88, 16, v78
	v_and_b32_e32 v89, 0xffff0000, v78
	v_lshlrev_b32_e32 v74, 16, v75
	v_and_b32_e32 v75, 0xffff0000, v75
	v_lshlrev_b32_e32 v78, 16, v79
	v_and_b32_e32 v79, 0xffff0000, v79
	v_add_f32_e32 v38, 1.0, v38
	v_add_f32_e32 v39, 1.0, v39
	v_lshlrev_b64 v[50:51], 11, v[50:51]
	s_waitcnt vmcnt(0)
	v_ffbh_u32_e32 v54, v53
	v_min_u32_e32 v54, 32, v54
	v_lshlrev_b64 v[52:53], v54, v[52:53]
	v_min_u32_e32 v52, 1, v52
	v_or_b32_e32 v52, v53, v52
	v_cvt_f32_u32_e32 v52, v52
	v_sub_u32_e32 v53, 32, v54
	v_lshlrev_b64 v[84:85], 12, v[84:85]
	v_pk_fma_f32 v[48:49], v[48:49], v[78:79], v[74:75]
	v_ldexp_f32 v52, v52, v53
	v_fmamk_f32 v52, v52, 0x2e800000, v177
	v_cmp_gt_f32_e32 vcc, s34, v52
	v_mul_f32_e32 v53, 0x4b800000, v52
	v_lshlrev_b32_e32 v74, 16, v76
	v_cndmask_b32_e32 v52, v52, v53, vcc
	v_rsq_f32_e32 v52, v52
	v_and_b32_e32 v75, 0xffff0000, v76
	v_lshlrev_b32_e32 v78, 16, v80
	v_and_b32_e32 v79, 0xffff0000, v80
	v_mul_f32_e32 v53, 0x45800000, v52
	v_rcp_f32_e32 v38, v38
	v_rcp_f32_e32 v39, v39
	v_add_f32_e32 v40, 1.0, v40
	v_add_f32_e32 v41, 1.0, v41
	v_cndmask_b32_e32 v82, v52, v53, vcc
	v_lshl_add_u64 v[52:53], s[2:3], 0, v[50:51]
	v_lshl_add_u64 v[50:51], s[6:7], 0, v[50:51]
	v_lshl_add_u64 v[84:85], s[4:5], 0, v[84:85]
	v_pk_fma_f32 v[42:43], v[42:43], v[78:79], v[74:75]
	v_lshlrev_b32_e32 v74, 16, v77
	v_and_b32_e32 v75, 0xffff0000, v77
	v_lshlrev_b32_e32 v76, 16, v81
	v_and_b32_e32 v77, 0xffff0000, v81
	v_rcp_f32_e32 v40, v40
	v_rcp_f32_e32 v41, v41
	v_add_f32_e32 v34, 1.0, v34
	v_add_f32_e32 v35, 1.0, v35
	v_lshl_add_u64 v[52:53], v[52:53], 0, v[164:165]
	v_lshl_add_u64 v[50:51], v[50:51], 0, v[164:165]
	v_pk_fma_f32 v[46:47], v[46:47], v[88:89], v[86:87]
	v_pk_fma_f32 v[44:45], v[44:45], v[76:77], v[74:75]
	v_lshl_add_u64 v[74:75], v[84:85], 0, v[154:155]
	v_rcp_f32_e32 v34, v34
	v_rcp_f32_e32 v35, v35
	v_add_f32_e32 v36, 1.0, v36
	v_add_f32_e32 v37, 1.0, v37
	global_load_dwordx4 v[62:65], v[52:53], off
	global_load_dwordx4 v[58:61], v[50:51], off
	global_load_dwordx4 v[54:57], v[52:53], off offset:64
	s_nop 0
	global_load_dwordx4 v[50:53], v[50:51], off offset:64
	global_store_dwordx4 v[74:75], v[46:49], off
	global_store_dwordx4 v[74:75], v[42:45], off offset:16
	v_rcp_f32_e32 v36, v36
	v_rcp_f32_e32 v37, v37
	v_lshlrev_b32_e32 v42, 16, v70
	v_and_b32_e32 v43, 0xffff0000, v70
	v_lshlrev_b32_e32 v44, 16, v66
	v_and_b32_e32 v45, 0xffff0000, v66
	v_pk_fma_f32 v[38:39], v[38:39], v[44:45], v[42:43]
	v_lshlrev_b32_e32 v42, 16, v71
	v_and_b32_e32 v43, 0xffff0000, v71
	v_lshlrev_b32_e32 v44, 16, v67
	v_and_b32_e32 v45, 0xffff0000, v67
	v_pk_fma_f32 v[40:41], v[40:41], v[44:45], v[42:43]
	v_lshlrev_b32_e32 v42, 16, v72
	v_and_b32_e32 v43, 0xffff0000, v72
	v_lshlrev_b32_e32 v44, 16, v68
	v_and_b32_e32 v45, 0xffff0000, v68
	v_pk_fma_f32 v[34:35], v[34:35], v[44:45], v[42:43]
	v_lshlrev_b32_e32 v42, 16, v73
	v_and_b32_e32 v43, 0xffff0000, v73
	v_lshlrev_b32_e32 v44, 16, v69
	v_and_b32_e32 v45, 0xffff0000, v69
	v_pk_fma_f32 v[36:37], v[36:37], v[44:45], v[42:43]
	global_store_dwordx4 v[74:75], v[38:41], off offset:128
	global_store_dwordx4 v[74:75], v[34:37], off offset:144
	global_load_dwordx2 v[36:37], v[146:147], off offset:640
	v_mul_f32_e32 v32, v32, v82
	v_add_u32_e32 v34, 0x50, v166
	v_ashrrev_i32_e32 v35, 31, v34
	v_lshlrev_b64 v[34:35], 11, v[34:35]
	v_mul_f32_e32 v33, v33, v82
	v_mul_f32_e32 v32, 0xbfb8aa3b, v32
	v_mul_f32_e32 v33, 0xbfb8aa3b, v33
	v_mul_f32_e32 v26, v26, v82
	v_mul_f32_e32 v27, v27, v82
	v_mul_f32_e32 v30, v30, v82
	v_mul_f32_e32 v31, v31, v82
	v_exp_f32_e32 v32, v32
	v_exp_f32_e32 v33, v33
	v_mul_f32_e32 v26, 0xbfb8aa3b, v26
	v_mul_f32_e32 v27, 0xbfb8aa3b, v27
	v_mul_f32_e32 v28, v28, v82
	v_mul_f32_e32 v29, v29, v82
	v_mul_f32_e32 v30, 0xbfb8aa3b, v30
	v_mul_f32_e32 v31, 0xbfb8aa3b, v31
	v_exp_f32_e32 v26, v26
	v_exp_f32_e32 v27, v27
	v_mul_f32_e32 v28, 0xbfb8aa3b, v28
	v_mul_f32_e32 v29, 0xbfb8aa3b, v29
	v_exp_f32_e32 v30, v30
	v_exp_f32_e32 v31, v31
	v_exp_f32_e32 v28, v28
	v_exp_f32_e32 v29, v29
	v_mul_f32_e32 v22, v22, v82
	v_mul_f32_e32 v23, v23, v82
	v_mul_f32_e32 v22, 0xbfb8aa3b, v22
	v_mul_f32_e32 v23, 0xbfb8aa3b, v23
	v_mul_f32_e32 v24, v24, v82
	v_mul_f32_e32 v25, v25, v82
	v_add_f32_e32 v32, 1.0, v32
	v_add_f32_e32 v33, 1.0, v33
	v_exp_f32_e32 v22, v22
	v_exp_f32_e32 v23, v23
	v_mul_f32_e32 v24, 0xbfb8aa3b, v24
	v_mul_f32_e32 v25, 0xbfb8aa3b, v25
	v_mul_f32_e32 v18, v18, v82
	v_mul_f32_e32 v19, v19, v82
	v_rcp_f32_e32 v32, v32
	v_rcp_f32_e32 v33, v33
	v_add_f32_e32 v26, 1.0, v26
	v_add_f32_e32 v27, 1.0, v27
	v_exp_f32_e32 v24, v24
	v_exp_f32_e32 v25, v25
	v_mul_f32_e32 v18, 0xbfb8aa3b, v18
	v_mul_f32_e32 v19, 0xbfb8aa3b, v19
	v_mul_f32_e32 v20, v20, v82
	v_mul_f32_e32 v21, v21, v82
	v_add_f32_e32 v30, 1.0, v30
	v_add_f32_e32 v31, 1.0, v31
	v_rcp_f32_e32 v26, v26
	v_rcp_f32_e32 v27, v27
	v_add_f32_e32 v28, 1.0, v28
	v_add_f32_e32 v29, 1.0, v29
	v_exp_f32_e32 v18, v18
	v_exp_f32_e32 v19, v19
	v_mul_f32_e32 v20, 0xbfb8aa3b, v20
	v_mul_f32_e32 v21, 0xbfb8aa3b, v21
	v_add_u32_e32 v68, 0x60, v162
	v_rcp_f32_e32 v30, v30
	v_rcp_f32_e32 v31, v31
	v_rcp_f32_e32 v28, v28
	v_rcp_f32_e32 v29, v29
	v_exp_f32_e32 v20, v20
	v_exp_f32_e32 v21, v21
	v_ashrrev_i32_e32 v69, 31, v68
	s_waitcnt vmcnt(8)
	v_lshlrev_b32_e32 v70, 16, v62
	v_and_b32_e32 v71, 0xffff0000, v62
	s_waitcnt vmcnt(7)
	v_lshlrev_b32_e32 v72, 16, v58
	v_and_b32_e32 v73, 0xffff0000, v58
	v_lshlrev_b32_e32 v62, 16, v63
	v_and_b32_e32 v63, 0xffff0000, v63
	v_lshlrev_b32_e32 v58, 16, v59
	v_and_b32_e32 v59, 0xffff0000, v59
	v_add_f32_e32 v22, 1.0, v22
	v_add_f32_e32 v23, 1.0, v23
	s_waitcnt vmcnt(0)
	v_ffbh_u32_e32 v38, v37
	v_min_u32_e32 v38, 32, v38
	v_lshlrev_b64 v[36:37], v38, v[36:37]
	v_min_u32_e32 v36, 1, v36
	v_or_b32_e32 v36, v37, v36
	v_cvt_f32_u32_e32 v36, v36
	v_sub_u32_e32 v37, 32, v38
	v_lshlrev_b64 v[68:69], 12, v[68:69]
	v_pk_fma_f32 v[32:33], v[32:33], v[58:59], v[62:63]
	v_ldexp_f32 v36, v36, v37
	v_fmamk_f32 v36, v36, 0x2e800000, v177
	v_cmp_gt_f32_e32 vcc, s34, v36
	v_mul_f32_e32 v37, 0x4b800000, v36
	v_lshlrev_b32_e32 v58, 16, v64
	v_cndmask_b32_e32 v36, v36, v37, vcc
	v_rsq_f32_e32 v36, v36
	v_and_b32_e32 v59, 0xffff0000, v64
	v_lshlrev_b32_e32 v62, 16, v60
	v_and_b32_e32 v63, 0xffff0000, v60
	v_mul_f32_e32 v37, 0x45800000, v36
	v_cndmask_b32_e32 v66, v36, v37, vcc
	v_lshl_add_u64 v[36:37], s[2:3], 0, v[34:35]
	v_lshl_add_u64 v[36:37], v[36:37], 0, v[164:165]
	v_lshl_add_u64 v[34:35], s[6:7], 0, v[34:35]
	global_load_dwordx4 v[42:45], v[36:37], off
	v_lshl_add_u64 v[34:35], v[34:35], 0, v[164:165]
	global_load_dwordx4 v[46:49], v[34:35], off
	global_load_dwordx4 v[38:41], v[36:37], off offset:64
	s_nop 0
	global_load_dwordx4 v[34:37], v[34:35], off offset:64
	v_mul_f32_e32 v14, v14, v66
	v_mul_f32_e32 v15, v15, v66
	v_mul_f32_e32 v14, 0xbfb8aa3b, v14
	v_mul_f32_e32 v15, 0xbfb8aa3b, v15
	v_mul_f32_e32 v16, v16, v66
	v_mul_f32_e32 v17, v17, v66
	v_rcp_f32_e32 v22, v22
	v_rcp_f32_e32 v23, v23
	v_add_f32_e32 v24, 1.0, v24
	v_add_f32_e32 v25, 1.0, v25
	v_exp_f32_e32 v14, v14
	v_exp_f32_e32 v15, v15
	v_mul_f32_e32 v16, 0xbfb8aa3b, v16
	v_mul_f32_e32 v17, 0xbfb8aa3b, v17
	v_mul_f32_e32 v10, v10, v66
	v_mul_f32_e32 v11, v11, v66
	v_lshl_add_u64 v[68:69], s[4:5], 0, v[68:69]
	v_pk_fma_f32 v[26:27], v[26:27], v[62:63], v[58:59]
	v_lshlrev_b32_e32 v58, 16, v65
	v_and_b32_e32 v59, 0xffff0000, v65
	v_lshlrev_b32_e32 v60, 16, v61
	v_and_b32_e32 v61, 0xffff0000, v61
	v_rcp_f32_e32 v24, v24
	v_rcp_f32_e32 v25, v25
	v_add_f32_e32 v18, 1.0, v18
	v_add_f32_e32 v19, 1.0, v19
	v_exp_f32_e32 v16, v16
	v_exp_f32_e32 v17, v17
	v_mul_f32_e32 v10, 0xbfb8aa3b, v10
	v_mul_f32_e32 v11, 0xbfb8aa3b, v11
	v_mul_f32_e32 v12, v12, v66
	v_mul_f32_e32 v13, v13, v66
	v_pk_fma_f32 v[30:31], v[30:31], v[72:73], v[70:71]
	v_pk_fma_f32 v[28:29], v[28:29], v[60:61], v[58:59]
	v_lshl_add_u64 v[58:59], v[68:69], 0, v[154:155]
	v_rcp_f32_e32 v18, v18
	v_rcp_f32_e32 v19, v19
	v_add_f32_e32 v20, 1.0, v20
	v_add_f32_e32 v21, 1.0, v21
	v_exp_f32_e32 v10, v10
	v_exp_f32_e32 v11, v11
	v_mul_f32_e32 v12, 0xbfb8aa3b, v12
	v_mul_f32_e32 v13, 0xbfb8aa3b, v13
	global_store_dwordx4 v[58:59], v[30:33], off
	global_store_dwordx4 v[58:59], v[26:29], off offset:16
	v_rcp_f32_e32 v20, v20
	v_rcp_f32_e32 v21, v21
	v_lshlrev_b32_e32 v26, 16, v54
	v_and_b32_e32 v27, 0xffff0000, v54
	v_lshlrev_b32_e32 v28, 16, v50
	v_and_b32_e32 v29, 0xffff0000, v50
	v_exp_f32_e32 v12, v12
	v_exp_f32_e32 v13, v13
	v_mul_f32_e32 v6, v6, v66
	v_mul_f32_e32 v7, v7, v66
	v_pk_fma_f32 v[22:23], v[22:23], v[28:29], v[26:27]
	v_lshlrev_b32_e32 v26, 16, v55
	v_and_b32_e32 v27, 0xffff0000, v55
	v_lshlrev_b32_e32 v28, 16, v51
	v_and_b32_e32 v29, 0xffff0000, v51
	v_add_f32_e32 v14, 1.0, v14
	v_add_f32_e32 v15, 1.0, v15
	v_mul_f32_e32 v6, 0xbfb8aa3b, v6
	v_mul_f32_e32 v7, 0xbfb8aa3b, v7
	v_mul_f32_e32 v8, v8, v66
	v_mul_f32_e32 v9, v9, v66
	v_pk_fma_f32 v[24:25], v[24:25], v[28:29], v[26:27]
	v_lshlrev_b32_e32 v26, 16, v56
	v_and_b32_e32 v27, 0xffff0000, v56
	v_lshlrev_b32_e32 v28, 16, v52
	v_and_b32_e32 v29, 0xffff0000, v52
	v_rcp_f32_e32 v14, v14
	v_rcp_f32_e32 v15, v15
	v_add_f32_e32 v16, 1.0, v16
	v_add_f32_e32 v17, 1.0, v17
	v_exp_f32_e32 v6, v6
	v_exp_f32_e32 v7, v7
	v_mul_f32_e32 v8, 0xbfb8aa3b, v8
	v_mul_f32_e32 v9, 0xbfb8aa3b, v9
	v_mul_f32_e32 v2, v2, v66
	v_mul_f32_e32 v3, v3, v66
	v_pk_fma_f32 v[18:19], v[18:19], v[28:29], v[26:27]
	v_lshlrev_b32_e32 v26, 16, v57
	v_and_b32_e32 v27, 0xffff0000, v57
	v_lshlrev_b32_e32 v28, 16, v53
	v_and_b32_e32 v29, 0xffff0000, v53
	v_rcp_f32_e32 v16, v16
	v_rcp_f32_e32 v17, v17
	v_add_f32_e32 v10, 1.0, v10
	v_add_f32_e32 v11, 1.0, v11
	v_exp_f32_e32 v8, v8
	v_exp_f32_e32 v9, v9
	v_mul_f32_e32 v2, 0xbfb8aa3b, v2
	v_mul_f32_e32 v3, 0xbfb8aa3b, v3
	v_mul_f32_e32 v4, v4, v66
	v_mul_f32_e32 v5, v5, v66
	v_pk_fma_f32 v[20:21], v[20:21], v[28:29], v[26:27]
	v_rcp_f32_e32 v10, v10
	v_rcp_f32_e32 v11, v11
	v_add_f32_e32 v12, 1.0, v12
	v_add_f32_e32 v13, 1.0, v13
	v_exp_f32_e32 v2, v2
	v_exp_f32_e32 v3, v3
	v_mul_f32_e32 v4, 0xbfb8aa3b, v4
	v_mul_f32_e32 v5, 0xbfb8aa3b, v5
	global_store_dwordx4 v[58:59], v[22:25], off offset:128
	global_store_dwordx4 v[58:59], v[18:21], off offset:144
	v_rcp_f32_e32 v12, v12
	s_waitcnt vmcnt(6)
	v_lshlrev_b32_e32 v22, 16, v46
	v_add_u32_e32 v18, 0x70, v162
	v_lshlrev_b32_e32 v20, 16, v42
	v_and_b32_e32 v21, 0xffff0000, v42
	v_and_b32_e32 v23, 0xffff0000, v46
	v_rcp_f32_e32 v13, v13
	v_exp_f32_e32 v4, v4
	v_exp_f32_e32 v5, v5
	v_ashrrev_i32_e32 v19, 31, v18
	v_pk_fma_f32 v[14:15], v[14:15], v[22:23], v[20:21]
	v_lshlrev_b32_e32 v20, 16, v43
	v_and_b32_e32 v21, 0xffff0000, v43
	v_lshlrev_b32_e32 v22, 16, v47
	v_and_b32_e32 v23, 0xffff0000, v47
	v_add_f32_e32 v6, 1.0, v6
	v_add_f32_e32 v7, 1.0, v7
	v_lshlrev_b64 v[18:19], 12, v[18:19]
	v_pk_fma_f32 v[16:17], v[16:17], v[22:23], v[20:21]
	v_lshlrev_b32_e32 v20, 16, v44
	v_and_b32_e32 v21, 0xffff0000, v44
	v_lshlrev_b32_e32 v22, 16, v48
	v_and_b32_e32 v23, 0xffff0000, v48
	v_rcp_f32_e32 v6, v6
	v_rcp_f32_e32 v7, v7
	v_add_f32_e32 v8, 1.0, v8
	v_add_f32_e32 v9, 1.0, v9
	v_lshl_add_u64 v[18:19], s[4:5], 0, v[18:19]
	v_pk_fma_f32 v[10:11], v[10:11], v[22:23], v[20:21]
	v_lshlrev_b32_e32 v20, 16, v45
	v_and_b32_e32 v21, 0xffff0000, v45
	v_lshlrev_b32_e32 v22, 16, v49
	v_and_b32_e32 v23, 0xffff0000, v49
	v_rcp_f32_e32 v8, v8
	v_rcp_f32_e32 v9, v9
	v_add_f32_e32 v2, 1.0, v2
	v_add_f32_e32 v3, 1.0, v3
	v_pk_fma_f32 v[12:13], v[12:13], v[22:23], v[20:21]
	v_lshl_add_u64 v[18:19], v[18:19], 0, v[154:155]
	v_rcp_f32_e32 v2, v2
	v_rcp_f32_e32 v3, v3
	v_add_f32_e32 v4, 1.0, v4
	v_add_f32_e32 v5, 1.0, v5
	global_store_dwordx4 v[18:19], v[14:17], off
	global_store_dwordx4 v[18:19], v[10:13], off offset:16
	v_rcp_f32_e32 v4, v4
	v_rcp_f32_e32 v5, v5
	s_waitcnt vmcnt(7)
	v_lshlrev_b32_e32 v10, 16, v38
	v_and_b32_e32 v11, 0xffff0000, v38
	s_waitcnt vmcnt(6)
	v_lshlrev_b32_e32 v12, 16, v34
	v_and_b32_e32 v13, 0xffff0000, v34
	v_pk_fma_f32 v[6:7], v[6:7], v[12:13], v[10:11]
	v_lshlrev_b32_e32 v10, 16, v39
	v_and_b32_e32 v11, 0xffff0000, v39
	v_lshlrev_b32_e32 v12, 16, v35
	v_and_b32_e32 v13, 0xffff0000, v35
	v_pk_fma_f32 v[8:9], v[8:9], v[12:13], v[10:11]
	v_lshlrev_b32_e32 v10, 16, v40
	v_and_b32_e32 v11, 0xffff0000, v40
	v_lshlrev_b32_e32 v12, 16, v36
	v_and_b32_e32 v13, 0xffff0000, v36
	v_pk_fma_f32 v[2:3], v[2:3], v[12:13], v[10:11]
	v_lshlrev_b32_e32 v10, 16, v41
	v_and_b32_e32 v11, 0xffff0000, v41
	v_lshlrev_b32_e32 v12, 16, v37
	v_and_b32_e32 v13, 0xffff0000, v37
	v_pk_fma_f32 v[4:5], v[4:5], v[12:13], v[10:11]
	global_store_dwordx4 v[18:19], v[6:9], off offset:128
	global_store_dwordx4 v[18:19], v[2:5], off offset:144
	s_mov_b32 s2, s100
	s_waitcnt lgkmcnt(0)
	s_add_i32 s16, s2, s16
	s_cmpk_gt_i32 s16, 0x1ff
	s_cbranch_scc1 .LBB0_207

.LBB0_211:
	v_mov_b32_e32 v133, v137
	v_mov_b32_e32 v0, v138
	v_or_b32_e32 v145, s25, v136
	v_add3_u32 v132, s21, v139, v0
	v_lshlrev_b32_e32 v0, 5, v0
	v_and_b32_e32 v0, 0x1e0, v0
	v_lshlrev_b32_e32 v144, 3, v133
	v_lshl_add_u64 v[130:131], s[4:5], 0, v[0:1]
	v_lshlrev_b32_e32 v0, 4, v133
	v_ashrrev_i32_e32 v133, 31, v132
	v_lshl_add_u64 v[134:135], v[132:133], 3, s[2:3]
	global_load_dwordx2 v[140:141], v[134:135], off
	global_load_dwordx2 v[204:205], v[134:135], off offset:128
	global_load_dwordx2 v[206:207], v[134:135], off offset:256
	global_load_dwordx2 v[208:209], v[134:135], off offset:384
	global_load_dwordx2 v[210:211], v[134:135], off offset:512
	global_load_dwordx2 v[212:213], v[134:135], off offset:640
	global_load_dwordx2 v[214:215], v[134:135], off offset:768
	global_load_dwordx2 v[216:217], v[134:135], off offset:896
	v_and_b32_e32 v0, 16, v0
	v_lshl_add_u64 v[130:131], v[130:131], 0, v[0:1]
	s_waitcnt vmcnt(0)
	v_ffbh_u32_e32 v0, v141
	v_min_u32_e32 v0, 32, v0
	v_lshlrev_b64 v[140:141], v0, v[140:141]
	v_min_u32_e32 v133, 1, v140
	v_or_b32_e32 v133, v141, v133
	v_cvt_f32_u32_e32 v133, v133
	v_sub_u32_e32 v0, 32, v0
	v_ldexp_f32 v0, v133, v0
	v_fmamk_f32 v0, v0, 0x2e800000, v177
	v_cmp_gt_f32_e32 vcc, s34, v0
	v_mul_f32_e32 v133, 0x4b800000, v0
	s_nop 0
	v_cndmask_b32_e32 v0, v0, v133, vcc
	v_rsq_f32_e32 v0, v0
	s_nop 0
	v_mul_f32_e32 v133, 0x45800000, v0
	v_cndmask_b32_e32 v140, v0, v133, vcc
	v_add_lshl_u32 v0, v145, v144, 7
	v_ashrrev_i32_e32 v133, 4, v132
	v_pk_mul_f32 v[126:127], v[126:127], v[140:141] op_sel_hi:[1,0]
	v_and_b32_e32 v0, 0xfffff800, v0
	v_pk_mul_f32 v[142:143], v[124:125], v[140:141] op_sel_hi:[1,0]
	v_pk_mul_f32 v[124:125], v[122:123], v[140:141] op_sel_hi:[1,0]
	v_cvt_pk_bf16_f32 v122, v126, v127
	v_add_u32_e32 v126, v0, v133
	v_ashrrev_i32_e32 v127, 31, v126
	v_pk_mul_f32 v[128:129], v[128:129], v[140:141] op_sel_hi:[1,0]
	v_lshlrev_b64 v[126:127], 9, v[126:127]
	v_cvt_pk_bf16_f32 v123, v128, v129
	v_cvt_pk_bf16_f32 v124, v124, v125
	v_cvt_pk_bf16_f32 v125, v142, v143
	v_lshl_add_u64 v[126:127], v[130:131], 0, v[126:127]
	v_pk_mul_f32 v[118:119], v[118:119], v[140:141] op_sel_hi:[1,0]
	v_pk_mul_f32 v[114:115], v[114:115], v[140:141] op_sel_hi:[1,0]
	global_store_dwordx4 v[126:127], v[122:125], off
	v_pk_mul_f32 v[120:121], v[120:121], v[140:141] op_sel_hi:[1,0]
	s_nop 0
	v_pk_mul_f32 v[122:123], v[116:117], v[140:141] op_sel_hi:[1,0]
	v_cvt_pk_bf16_f32 v116, v118, v119
	v_cvt_pk_bf16_f32 v118, v114, v115
	v_add_u32_e32 v114, 0x1000, v0
	v_cvt_pk_bf16_f32 v117, v120, v121
	v_add_u32_e32 v120, v114, v133
	v_ashrrev_i32_e32 v121, 31, v120
	v_lshlrev_b64 v[120:121], 9, v[120:121]
	v_cvt_pk_bf16_f32 v119, v122, v123
	v_lshl_add_u64 v[120:121], v[130:131], 0, v[120:121]
	global_store_dwordx4 v[120:121], v[116:119], off
	s_nop 1
	v_mov_b32_e32 v116, v204
	v_mov_b32_e32 v117, v205
	v_add_u32_e32 v115, 16, v132
	v_ashrrev_i32_e32 v115, 4, v115
	v_ffbh_u32_e32 v118, v117
	v_min_u32_e32 v118, 32, v118
	v_lshlrev_b64 v[116:117], v118, v[116:117]
	v_min_u32_e32 v116, 1, v116
	v_or_b32_e32 v116, v117, v116
	v_cvt_f32_u32_e32 v116, v116
	v_sub_u32_e32 v117, 32, v118
	v_ldexp_f32 v116, v116, v117
	v_fmamk_f32 v116, v116, 0x2e800000, v177
	v_cmp_gt_f32_e32 vcc, s34, v116
	v_mul_f32_e32 v117, 0x4b800000, v116
	s_nop 0
	v_cndmask_b32_e32 v116, v116, v117, vcc
	v_rsq_f32_e32 v116, v116
	s_nop 0
	v_mul_f32_e32 v117, 0x45800000, v116
	v_cndmask_b32_e32 v116, v116, v117, vcc
	v_pk_mul_f32 v[110:111], v[110:111], v[116:117] op_sel_hi:[1,0]
	v_pk_mul_f32 v[118:119], v[108:109], v[116:117] op_sel_hi:[1,0]
	v_pk_mul_f32 v[108:109], v[106:107], v[116:117] op_sel_hi:[1,0]
	v_cvt_pk_bf16_f32 v106, v110, v111
	v_add_u32_e32 v110, v0, v115
	v_ashrrev_i32_e32 v111, 31, v110
	v_pk_mul_f32 v[112:113], v[112:113], v[116:117] op_sel_hi:[1,0]
	v_lshlrev_b64 v[110:111], 9, v[110:111]
	v_cvt_pk_bf16_f32 v107, v112, v113
	v_cvt_pk_bf16_f32 v108, v108, v109
	v_cvt_pk_bf16_f32 v109, v118, v119
	v_lshl_add_u64 v[110:111], v[130:131], 0, v[110:111]
	v_pk_mul_f32 v[102:103], v[102:103], v[116:117] op_sel_hi:[1,0]
	global_store_dwordx4 v[110:111], v[106:109], off
	v_pk_mul_f32 v[104:105], v[104:105], v[116:117] op_sel_hi:[1,0]
	s_nop 0
	v_pk_mul_f32 v[106:107], v[100:101], v[116:117] op_sel_hi:[1,0]
	v_pk_mul_f32 v[100:101], v[98:99], v[116:117] op_sel_hi:[1,0]
	v_cvt_pk_bf16_f32 v98, v102, v103
	v_add_u32_e32 v102, v114, v115
	v_ashrrev_i32_e32 v103, 31, v102
	v_lshlrev_b64 v[102:103], 9, v[102:103]
	v_cvt_pk_bf16_f32 v99, v104, v105
	v_cvt_pk_bf16_f32 v100, v100, v101
	v_cvt_pk_bf16_f32 v101, v106, v107
	v_lshl_add_u64 v[102:103], v[130:131], 0, v[102:103]
	global_store_dwordx4 v[102:103], v[98:101], off
	s_nop 1
	v_mov_b32_e32 v98, v206
	v_mov_b32_e32 v99, v207
	s_nop 0
	v_add_u32_e32 v100, 32, v132
	v_ffbh_u32_e32 v101, v99
	v_min_u32_e32 v101, 32, v101
	v_lshlrev_b64 v[98:99], v101, v[98:99]
	v_min_u32_e32 v98, 1, v98
	v_or_b32_e32 v98, v99, v98
	v_cvt_f32_u32_e32 v98, v98
	v_sub_u32_e32 v99, 32, v101
	v_ldexp_f32 v98, v98, v99
	v_fmamk_f32 v98, v98, 0x2e800000, v177
	v_cmp_gt_f32_e32 vcc, s34, v98
	v_mul_f32_e32 v99, 0x4b800000, v98
	s_nop 0
	v_cndmask_b32_e32 v98, v98, v99, vcc
	v_rsq_f32_e32 v98, v98
	s_nop 0
	v_mul_f32_e32 v99, 0x45800000, v98
	v_cndmask_b32_e32 v98, v98, v99, vcc
	v_ashrrev_i32_e32 v99, 4, v100
	v_pk_mul_f32 v[94:95], v[94:95], v[98:99] op_sel_hi:[1,0]
	v_pk_mul_f32 v[100:101], v[92:93], v[98:99] op_sel_hi:[1,0]
	v_pk_mul_f32 v[92:93], v[90:91], v[98:99] op_sel_hi:[1,0]
	v_cvt_pk_bf16_f32 v90, v94, v95
	v_add_u32_e32 v94, v0, v99
	v_ashrrev_i32_e32 v95, 31, v94
	v_pk_mul_f32 v[96:97], v[96:97], v[98:99] op_sel_hi:[1,0]
	v_lshlrev_b64 v[94:95], 9, v[94:95]
	v_cvt_pk_bf16_f32 v91, v96, v97
	v_cvt_pk_bf16_f32 v92, v92, v93
	v_cvt_pk_bf16_f32 v93, v100, v101
	v_lshl_add_u64 v[94:95], v[130:131], 0, v[94:95]
	v_pk_mul_f32 v[86:87], v[86:87], v[98:99] op_sel_hi:[1,0]
	global_store_dwordx4 v[94:95], v[90:93], off
	v_pk_mul_f32 v[88:89], v[88:89], v[98:99] op_sel_hi:[1,0]
	s_nop 0
	v_pk_mul_f32 v[90:91], v[84:85], v[98:99] op_sel_hi:[1,0]
	v_pk_mul_f32 v[84:85], v[82:83], v[98:99] op_sel_hi:[1,0]
	v_cvt_pk_bf16_f32 v82, v86, v87
	v_add_u32_e32 v86, v114, v99
	v_ashrrev_i32_e32 v87, 31, v86
	v_lshlrev_b64 v[86:87], 9, v[86:87]
	v_cvt_pk_bf16_f32 v83, v88, v89
	v_cvt_pk_bf16_f32 v84, v84, v85
	v_cvt_pk_bf16_f32 v85, v90, v91
	v_lshl_add_u64 v[86:87], v[130:131], 0, v[86:87]
	global_store_dwordx4 v[86:87], v[82:85], off
	s_nop 1
	v_mov_b32_e32 v82, v208
	v_mov_b32_e32 v83, v209
	s_nop 0
	v_add_u32_e32 v84, 48, v132
	v_ffbh_u32_e32 v85, v83
	v_min_u32_e32 v85, 32, v85
	v_lshlrev_b64 v[82:83], v85, v[82:83]
	v_min_u32_e32 v82, 1, v82
	v_or_b32_e32 v82, v83, v82
	v_cvt_f32_u32_e32 v82, v82
	v_sub_u32_e32 v83, 32, v85
	v_ldexp_f32 v82, v82, v83
	v_fmamk_f32 v82, v82, 0x2e800000, v177
	v_cmp_gt_f32_e32 vcc, s34, v82
	v_mul_f32_e32 v83, 0x4b800000, v82
	s_nop 0
	v_cndmask_b32_e32 v82, v82, v83, vcc
	v_rsq_f32_e32 v82, v82
	s_nop 0
	v_mul_f32_e32 v83, 0x45800000, v82
	v_cndmask_b32_e32 v82, v82, v83, vcc
	v_ashrrev_i32_e32 v83, 4, v84
	v_pk_mul_f32 v[78:79], v[78:79], v[82:83] op_sel_hi:[1,0]
	v_pk_mul_f32 v[84:85], v[76:77], v[82:83] op_sel_hi:[1,0]
	v_pk_mul_f32 v[76:77], v[74:75], v[82:83] op_sel_hi:[1,0]
	v_cvt_pk_bf16_f32 v74, v78, v79
	v_add_u32_e32 v78, v0, v83
	v_ashrrev_i32_e32 v79, 31, v78
	v_pk_mul_f32 v[80:81], v[80:81], v[82:83] op_sel_hi:[1,0]
	v_lshlrev_b64 v[78:79], 9, v[78:79]
	v_cvt_pk_bf16_f32 v75, v80, v81
	v_cvt_pk_bf16_f32 v76, v76, v77
	v_cvt_pk_bf16_f32 v77, v84, v85
	v_lshl_add_u64 v[78:79], v[130:131], 0, v[78:79]
	v_pk_mul_f32 v[70:71], v[70:71], v[82:83] op_sel_hi:[1,0]
	global_store_dwordx4 v[78:79], v[74:77], off
	v_pk_mul_f32 v[72:73], v[72:73], v[82:83] op_sel_hi:[1,0]
	s_nop 0
	v_pk_mul_f32 v[74:75], v[68:69], v[82:83] op_sel_hi:[1,0]
	v_pk_mul_f32 v[68:69], v[66:67], v[82:83] op_sel_hi:[1,0]
	v_cvt_pk_bf16_f32 v66, v70, v71
	v_add_u32_e32 v70, v114, v83
	v_ashrrev_i32_e32 v71, 31, v70
	v_lshlrev_b64 v[70:71], 9, v[70:71]
	v_cvt_pk_bf16_f32 v67, v72, v73
	v_cvt_pk_bf16_f32 v68, v68, v69
	v_cvt_pk_bf16_f32 v69, v74, v75
	v_lshl_add_u64 v[70:71], v[130:131], 0, v[70:71]
	global_store_dwordx4 v[70:71], v[66:69], off
	s_nop 1
	v_mov_b32_e32 v66, v210
	v_mov_b32_e32 v67, v211
	s_nop 0
	v_add_u32_e32 v68, 64, v132
	v_ffbh_u32_e32 v69, v67
	v_min_u32_e32 v69, 32, v69
	v_lshlrev_b64 v[66:67], v69, v[66:67]
	v_min_u32_e32 v66, 1, v66
	v_or_b32_e32 v66, v67, v66
	v_cvt_f32_u32_e32 v66, v66
	v_sub_u32_e32 v67, 32, v69
	v_ldexp_f32 v66, v66, v67
	v_fmamk_f32 v66, v66, 0x2e800000, v177
	v_cmp_gt_f32_e32 vcc, s34, v66
	v_mul_f32_e32 v67, 0x4b800000, v66
	s_nop 0
	v_cndmask_b32_e32 v66, v66, v67, vcc
	v_rsq_f32_e32 v66, v66
	s_nop 0
	v_mul_f32_e32 v67, 0x45800000, v66
	v_cndmask_b32_e32 v66, v66, v67, vcc
	v_ashrrev_i32_e32 v67, 4, v68
	v_pk_mul_f32 v[62:63], v[62:63], v[66:67] op_sel_hi:[1,0]
	v_pk_mul_f32 v[68:69], v[60:61], v[66:67] op_sel_hi:[1,0]
	v_pk_mul_f32 v[60:61], v[58:59], v[66:67] op_sel_hi:[1,0]
	v_cvt_pk_bf16_f32 v58, v62, v63
	v_add_u32_e32 v62, v0, v67
	v_ashrrev_i32_e32 v63, 31, v62
	v_pk_mul_f32 v[64:65], v[64:65], v[66:67] op_sel_hi:[1,0]
	v_lshlrev_b64 v[62:63], 9, v[62:63]
	v_cvt_pk_bf16_f32 v59, v64, v65
	v_cvt_pk_bf16_f32 v60, v60, v61
	v_cvt_pk_bf16_f32 v61, v68, v69
	v_lshl_add_u64 v[62:63], v[130:131], 0, v[62:63]
	v_pk_mul_f32 v[54:55], v[54:55], v[66:67] op_sel_hi:[1,0]
	global_store_dwordx4 v[62:63], v[58:61], off
	v_pk_mul_f32 v[56:57], v[56:57], v[66:67] op_sel_hi:[1,0]
	s_nop 0
	v_pk_mul_f32 v[58:59], v[52:53], v[66:67] op_sel_hi:[1,0]
	v_pk_mul_f32 v[52:53], v[50:51], v[66:67] op_sel_hi:[1,0]
	v_cvt_pk_bf16_f32 v50, v54, v55
	v_add_u32_e32 v54, v114, v67
	v_ashrrev_i32_e32 v55, 31, v54
	v_lshlrev_b64 v[54:55], 9, v[54:55]
	v_cvt_pk_bf16_f32 v51, v56, v57
	v_cvt_pk_bf16_f32 v52, v52, v53
	v_cvt_pk_bf16_f32 v53, v58, v59
	v_lshl_add_u64 v[54:55], v[130:131], 0, v[54:55]
	global_store_dwordx4 v[54:55], v[50:53], off
	s_nop 1
	v_mov_b32_e32 v50, v212
	v_mov_b32_e32 v51, v213
	s_nop 0
	v_add_u32_e32 v52, 0x50, v132
	v_ffbh_u32_e32 v53, v51
	v_min_u32_e32 v53, 32, v53
	v_lshlrev_b64 v[50:51], v53, v[50:51]
	v_min_u32_e32 v50, 1, v50
	v_or_b32_e32 v50, v51, v50
	v_cvt_f32_u32_e32 v50, v50
	v_sub_u32_e32 v51, 32, v53
	v_ldexp_f32 v50, v50, v51
	v_fmamk_f32 v50, v50, 0x2e800000, v177
	v_cmp_gt_f32_e32 vcc, s34, v50
	v_mul_f32_e32 v51, 0x4b800000, v50
	s_nop 0
	v_cndmask_b32_e32 v50, v50, v51, vcc
	v_rsq_f32_e32 v50, v50
	s_nop 0
	v_mul_f32_e32 v51, 0x45800000, v50
	v_cndmask_b32_e32 v50, v50, v51, vcc
	v_ashrrev_i32_e32 v51, 4, v52
	v_pk_mul_f32 v[46:47], v[46:47], v[50:51] op_sel_hi:[1,0]
	v_pk_mul_f32 v[52:53], v[44:45], v[50:51] op_sel_hi:[1,0]
	v_pk_mul_f32 v[44:45], v[42:43], v[50:51] op_sel_hi:[1,0]
	v_cvt_pk_bf16_f32 v42, v46, v47
	v_add_u32_e32 v46, v0, v51
	v_ashrrev_i32_e32 v47, 31, v46
	v_pk_mul_f32 v[48:49], v[48:49], v[50:51] op_sel_hi:[1,0]
	v_lshlrev_b64 v[46:47], 9, v[46:47]
	v_cvt_pk_bf16_f32 v43, v48, v49
	v_cvt_pk_bf16_f32 v44, v44, v45
	v_cvt_pk_bf16_f32 v45, v52, v53
	v_lshl_add_u64 v[46:47], v[130:131], 0, v[46:47]
	v_pk_mul_f32 v[38:39], v[38:39], v[50:51] op_sel_hi:[1,0]
	global_store_dwordx4 v[46:47], v[42:45], off
	v_pk_mul_f32 v[40:41], v[40:41], v[50:51] op_sel_hi:[1,0]
	s_nop 0
	v_pk_mul_f32 v[42:43], v[36:37], v[50:51] op_sel_hi:[1,0]
	v_pk_mul_f32 v[36:37], v[34:35], v[50:51] op_sel_hi:[1,0]
	v_cvt_pk_bf16_f32 v34, v38, v39
	v_add_u32_e32 v38, v114, v51
	v_ashrrev_i32_e32 v39, 31, v38
	v_lshlrev_b64 v[38:39], 9, v[38:39]
	v_cvt_pk_bf16_f32 v35, v40, v41
	v_cvt_pk_bf16_f32 v36, v36, v37
	v_cvt_pk_bf16_f32 v37, v42, v43
	v_lshl_add_u64 v[38:39], v[130:131], 0, v[38:39]
	global_store_dwordx4 v[38:39], v[34:37], off
	s_nop 1
	v_mov_b32_e32 v34, v214
	v_mov_b32_e32 v35, v215
	s_nop 0
	v_add_u32_e32 v36, 0x60, v132
	v_ffbh_u32_e32 v37, v35
	v_min_u32_e32 v37, 32, v37
	v_lshlrev_b64 v[34:35], v37, v[34:35]
	v_min_u32_e32 v34, 1, v34
	v_or_b32_e32 v34, v35, v34
	v_cvt_f32_u32_e32 v34, v34
	v_sub_u32_e32 v35, 32, v37
	v_ldexp_f32 v34, v34, v35
	v_fmamk_f32 v34, v34, 0x2e800000, v177
	v_cmp_gt_f32_e32 vcc, s34, v34
	v_mul_f32_e32 v35, 0x4b800000, v34
	s_nop 0
	v_cndmask_b32_e32 v34, v34, v35, vcc
	v_rsq_f32_e32 v34, v34
	s_nop 0
	v_mul_f32_e32 v35, 0x45800000, v34
	v_cndmask_b32_e32 v34, v34, v35, vcc
	v_ashrrev_i32_e32 v35, 4, v36
	v_pk_mul_f32 v[30:31], v[30:31], v[34:35] op_sel_hi:[1,0]
	v_pk_mul_f32 v[36:37], v[28:29], v[34:35] op_sel_hi:[1,0]
	v_pk_mul_f32 v[28:29], v[26:27], v[34:35] op_sel_hi:[1,0]
	v_cvt_pk_bf16_f32 v26, v30, v31
	v_add_u32_e32 v30, v0, v35
	v_ashrrev_i32_e32 v31, 31, v30
	v_pk_mul_f32 v[32:33], v[32:33], v[34:35] op_sel_hi:[1,0]
	v_lshlrev_b64 v[30:31], 9, v[30:31]
	v_cvt_pk_bf16_f32 v27, v32, v33
	v_cvt_pk_bf16_f32 v28, v28, v29
	v_cvt_pk_bf16_f32 v29, v36, v37
	v_lshl_add_u64 v[30:31], v[130:131], 0, v[30:31]
	v_pk_mul_f32 v[22:23], v[22:23], v[34:35] op_sel_hi:[1,0]
	global_store_dwordx4 v[30:31], v[26:29], off
	v_pk_mul_f32 v[24:25], v[24:25], v[34:35] op_sel_hi:[1,0]
	s_nop 0
	v_pk_mul_f32 v[26:27], v[20:21], v[34:35] op_sel_hi:[1,0]
	v_pk_mul_f32 v[20:21], v[18:19], v[34:35] op_sel_hi:[1,0]
	v_cvt_pk_bf16_f32 v18, v22, v23
	v_add_u32_e32 v22, v114, v35
	v_ashrrev_i32_e32 v23, 31, v22
	v_lshlrev_b64 v[22:23], 9, v[22:23]
	v_cvt_pk_bf16_f32 v19, v24, v25
	v_cvt_pk_bf16_f32 v20, v20, v21
	v_cvt_pk_bf16_f32 v21, v26, v27
	v_lshl_add_u64 v[22:23], v[130:131], 0, v[22:23]
	global_store_dwordx4 v[22:23], v[18:21], off
	s_nop 1
	v_mov_b32_e32 v18, v216
	v_mov_b32_e32 v19, v217
	s_nop 0
	v_add_u32_e32 v20, 0x70, v132
	v_ffbh_u32_e32 v21, v19
	v_min_u32_e32 v21, 32, v21
	v_lshlrev_b64 v[18:19], v21, v[18:19]
	v_min_u32_e32 v18, 1, v18
	v_or_b32_e32 v18, v19, v18
	v_cvt_f32_u32_e32 v18, v18
	v_sub_u32_e32 v19, 32, v21
	v_ldexp_f32 v18, v18, v19
	v_fmamk_f32 v18, v18, 0x2e800000, v177
	v_cmp_gt_f32_e32 vcc, s34, v18
	v_mul_f32_e32 v19, 0x4b800000, v18
	s_nop 0
	v_cndmask_b32_e32 v18, v18, v19, vcc
	v_rsq_f32_e32 v18, v18
	s_nop 0
	v_mul_f32_e32 v19, 0x45800000, v18
	v_cndmask_b32_e32 v18, v18, v19, vcc
	v_ashrrev_i32_e32 v19, 4, v20
	v_pk_mul_f32 v[14:15], v[14:15], v[18:19] op_sel_hi:[1,0]
	v_pk_mul_f32 v[20:21], v[12:13], v[18:19] op_sel_hi:[1,0]
	v_pk_mul_f32 v[12:13], v[10:11], v[18:19] op_sel_hi:[1,0]
	v_cvt_pk_bf16_f32 v10, v14, v15
	v_add_u32_e32 v14, v0, v19
	v_ashrrev_i32_e32 v15, 31, v14
	v_pk_mul_f32 v[16:17], v[16:17], v[18:19] op_sel_hi:[1,0]
	v_lshlrev_b64 v[14:15], 9, v[14:15]
	v_cvt_pk_bf16_f32 v11, v16, v17
	v_cvt_pk_bf16_f32 v12, v12, v13
	v_cvt_pk_bf16_f32 v13, v20, v21
	v_lshl_add_u64 v[14:15], v[130:131], 0, v[14:15]
	v_pk_mul_f32 v[6:7], v[6:7], v[18:19] op_sel_hi:[1,0]
	global_store_dwordx4 v[14:15], v[10:13], off
	v_pk_mul_f32 v[8:9], v[8:9], v[18:19] op_sel_hi:[1,0]
	s_nop 0
	v_pk_mul_f32 v[10:11], v[4:5], v[18:19] op_sel_hi:[1,0]
	v_pk_mul_f32 v[4:5], v[2:3], v[18:19] op_sel_hi:[1,0]
	v_cvt_pk_bf16_f32 v2, v6, v7
	v_add_u32_e32 v6, v114, v19
	v_ashrrev_i32_e32 v7, 31, v6
	v_lshlrev_b64 v[6:7], 9, v[6:7]
	v_cvt_pk_bf16_f32 v3, v8, v9
	v_cvt_pk_bf16_f32 v4, v4, v5
	v_cvt_pk_bf16_f32 v5, v10, v11
	v_lshl_add_u64 v[6:7], v[130:131], 0, v[6:7]
	global_store_dwordx4 v[6:7], v[2:5], off
	s_mov_b32 s10, s100
	s_waitcnt lgkmcnt(0)
	s_add_i32 s19, s10, s19
	s_cmpk_gt_i32 s19, 0x1ff
	s_cbranch_scc1 .LBB0_218

.LBB0_222:
	s_or_b64 exec, exec, s[2:3]
	s_mov_b32 s2, s100
	s_waitcnt lgkmcnt(0)
	s_add_i32 s18, s2, s18
	s_cmp_ge_i32 s18, s11
	s_cbranch_scc1 .LBB0_261

.LBB0_229:
	v_mov_b32_e32 v0, v152
	v_mov_b32_e32 v130, v153
	v_add_u32_e32 v142, s15, v154
	v_add3_u32 v138, s19, v155, v130
	v_ashrrev_i32_e32 v139, 31, v138
	v_lshl_add_u64 v[140:141], v[138:139], 3, s[62:63]
	global_load_dwordx2 v[130:131], v[140:141], off
	global_load_dwordx2 v[204:205], v[140:141], off offset:128
	global_load_dwordx2 v[206:207], v[140:141], off offset:256
	global_load_dwordx2 v[208:209], v[140:141], off offset:384
	global_load_dwordx2 v[210:211], v[140:141], off offset:512
	global_load_dwordx2 v[212:213], v[140:141], off offset:640
	global_load_dwordx2 v[214:215], v[140:141], off offset:768
	global_load_dwordx2 v[216:217], v[140:141], off offset:896
	s_movk_i32 s2, 0x7ff
	v_mov_b32_e32 v132, s55
	v_mov_b32_e32 v133, s13
	v_cmp_lt_i32_e32 vcc, s2, v142
	v_and_b32_e32 v136, 0xfffffc00, v142
	v_cmp_ne_u32_e64 s[42:43], s69, v136
	v_cndmask_b32_e32 v133, v132, v133, vcc
	v_mov_b32_e32 v134, s54
	v_mov_b32_e32 v135, s12
	v_ashrrev_i32_e32 v143, 31, v142
	v_cndmask_b32_e32 v156, 1.0, v187, vcc
	v_cndmask_b32_e32 v240, v134, v135, vcc
	v_mov_b32_e32 v241, v133
	v_lshlrev_b32_e32 v238, 3, v0
	v_ashrrev_i32_e32 v239, 31, v238
	v_lshl_add_u64 v[238:239], v[238:239], 2, v[240:241]
	global_load_dwordx4 v[222:225], v[238:239], off
	global_load_dwordx4 v[226:229], v[238:239], off offset:16
	global_load_dwordx4 v[230:233], v[238:239], off offset:128
	global_load_dwordx4 v[234:237], v[238:239], off offset:144
	s_waitcnt vmcnt(0)
	v_ffbh_u32_e32 v132, v131
	v_min_u32_e32 v136, 32, v132
	v_lshlrev_b64 v[130:131], v136, v[130:131]
	v_min_u32_e32 v130, 1, v130
	v_or_b32_e32 v130, v131, v130
	v_cvt_f32_u32_e32 v130, v130
	v_sub_u32_e32 v131, 32, v136
	v_cndmask_b32_e32 v132, v134, v135, vcc
	v_lshl_add_u64 v[134:135], v[142:143], 1, s[66:67]
	v_ldexp_f32 v130, v130, v131
	v_fmamk_f32 v130, v130, 0x2e800000, v177
	v_mul_f32_e32 v131, 0x4b800000, v130
	v_cmp_gt_f32_e64 s[44:45], s34, v130
	v_mov_b32_e32 v143, v1
	v_lshl_add_u64 v[136:137], v[142:143], 1, s[40:41]
	v_cndmask_b32_e64 v130, v130, v131, s[44:45]
	v_rsq_f32_e32 v131, v130
	v_lshlrev_b32_e32 v130, 3, v0
	v_mul_f32_e32 v0, 0x45800000, v131
	v_cndmask_b32_e64 v0, v131, v0, s[44:45]
	v_pk_mul_f32 v[146:147], v[128:129], v[0:1] op_sel_hi:[1,0]
	v_pk_mul_f32 v[148:149], v[126:127], v[0:1] op_sel_hi:[1,0]
	v_pk_mul_f32 v[128:129], v[124:125], v[0:1] op_sel_hi:[1,0]
	v_pk_mul_f32 v[144:145], v[122:123], v[0:1] op_sel_hi:[1,0]
	v_pk_mul_f32 v[122:123], v[120:121], v[0:1] op_sel_hi:[1,0]
	v_pk_mul_f32 v[124:125], v[118:119], v[0:1] op_sel_hi:[1,0]
	v_pk_mul_f32 v[118:119], v[116:117], v[0:1] op_sel_hi:[1,0]
	v_pk_mul_f32 v[120:121], v[114:115], v[0:1] op_sel_hi:[1,0]
	v_ashrrev_i32_e32 v131, 31, v130
	s_and_saveexec_b64 s[2:3], s[42:43]
	s_xor_b64 s[2:3], exec, s[2:3]
	s_cbranch_execz .LBB0_231
	v_mov_b32_e32 v150, v149
	v_mov_b32_e32 v151, v145
	v_mov_b32_e32 v126, v148
	v_mov_b32_e32 v127, v144
	v_pk_mul_f32 v[150:151], v[150:151], v[150:151]
	v_mov_b32_e32 v116, v146
	v_mov_b32_e32 v117, v128
	v_pk_fma_f32 v[126:127], v[126:127], v[126:127], v[150:151]
	v_mov_b32_e32 v114, v147
	v_mov_b32_e32 v115, v129
	v_pk_fma_f32 v[116:117], v[116:117], v[116:117], v[126:127]
	v_mov_b32_e32 v158, v121
	v_mov_b32_e32 v159, v125
	v_pk_fma_f32 v[114:115], v[114:115], v[114:115], v[116:117]
	v_mov_b32_e32 v150, v120
	v_mov_b32_e32 v151, v124
	v_pk_mul_f32 v[158:159], v[158:159], v[158:159]
	v_mov_b32_e32 v126, v118
	v_mov_b32_e32 v127, v122
	v_pk_fma_f32 v[150:151], v[150:151], v[150:151], v[158:159]
	v_add_f32_e32 v0, v114, v115
	v_and_b32_e32 v115, 64, v179
	v_mov_b32_e32 v116, v119
	v_mov_b32_e32 v117, v123
	v_pk_fma_f32 v[126:127], v[126:127], v[126:127], v[150:151]
	v_xor_b32_e32 v114, 16, v179
	v_add_u32_e32 v115, 64, v115
	v_pk_fma_f32 v[116:117], v[116:117], v[116:117], v[126:127]
	v_cmp_lt_i32_e64 s[44:45], v114, v115
	v_add_f32_e32 v0, v117, v0
	v_add_f32_e32 v0, v116, v0
	v_cndmask_b32_e64 v114, v179, v114, s[44:45]
	v_lshlrev_b32_e32 v114, 2, v114
	ds_bpermute_b32 v114, v114, v0
	v_lshl_add_u64 v[150:151], v[130:131], 2, v[132:133]
	s_waitcnt lgkmcnt(0)
	v_add_f32_e32 v0, v0, v114
	v_xor_b32_e32 v114, 32, v179
	v_cmp_lt_i32_e64 s[44:45], v114, v115
	s_nop 1
	v_cndmask_b32_e64 v114, v179, v114, s[44:45]
	v_lshlrev_b32_e32 v114, 2, v114
	ds_bpermute_b32 v114, v114, v0
	s_waitcnt lgkmcnt(0)
	v_add_f32_e32 v0, v0, v114
	v_fmamk_f32 v0, v0, 0x3c800000, v177
	v_cmp_gt_f32_e64 s[44:45], s34, v0
	v_mul_f32_e32 v114, 0x4b800000, v0
	s_nop 0
	v_cndmask_b32_e64 v0, v0, v114, s[44:45]
	v_rsq_f32_e32 v0, v0
	s_nop 0
	v_mul_f32_e32 v114, 0x45800000, v0
	v_cndmask_b32_e64 v0, v0, v114, s[44:45]
	v_lshlrev_b64 v[114:115], 11, v[138:139]
	v_lshl_add_u64 v[116:117], v[136:137], 0, v[114:115]
	v_lshl_add_u64 v[116:117], v[116:117], 0, s[82:83]
	v_lshl_add_u64 v[114:115], v[134:135], 0, v[114:115]
	v_cndmask_b32_e32 v127, v115, v117, vcc
	v_cndmask_b32_e32 v126, v114, v116, vcc
	s_nop 1
	v_mov_b32_e32 v114, v226
	v_mov_b32_e32 v115, v227
	v_mov_b32_e32 v116, v228
	v_mov_b32_e32 v117, v229
	s_nop 1
	v_mov_b32_e32 v158, v222
	v_mov_b32_e32 v159, v223
	v_mov_b32_e32 v160, v224
	v_mov_b32_e32 v161, v225
	v_mul_f32_e32 v0, v156, v0
	v_pk_mul_f32 v[148:149], v[148:149], v[0:1] op_sel_hi:[1,0]
	v_pk_mul_f32 v[146:147], v[146:147], v[0:1] op_sel_hi:[1,0]
	v_pk_mul_f32 v[144:145], v[144:145], v[0:1] op_sel_hi:[1,0]
	v_pk_mul_f32 v[128:129], v[128:129], v[0:1] op_sel_hi:[1,0]
	v_pk_mul_f32 v[124:125], v[124:125], v[0:1] op_sel_hi:[1,0]
	v_pk_mul_f32 v[122:123], v[122:123], v[0:1] op_sel_hi:[1,0]
	v_pk_mul_f32 v[120:121], v[120:121], v[0:1] op_sel_hi:[1,0]
	v_pk_mul_f32 v[118:119], v[118:119], v[0:1] op_sel_hi:[1,0]
	v_pk_mul_f32 v[128:129], v[116:117], v[128:129]
	v_pk_mul_f32 v[146:147], v[160:161], v[146:147]
	v_pk_mul_f32 v[148:149], v[158:159], v[148:149]
	v_pk_mul_f32 v[116:117], v[114:115], v[144:145]
	v_cvt_pk_bf16_f32 v114, v148, v149
	v_cvt_pk_bf16_f32 v115, v146, v147
	v_cvt_pk_bf16_f32 v116, v116, v117
	v_cvt_pk_bf16_f32 v117, v128, v129
	v_lshl_add_u64 v[144:145], v[130:131], 1, v[126:127]
	global_store_dwordx4 v[144:145], v[114:117], off
	s_nop 1
	v_mov_b32_e32 v114, v234
	v_mov_b32_e32 v115, v235
	v_mov_b32_e32 v116, v236
	v_mov_b32_e32 v117, v237
	s_nop 0
	s_nop 1
	v_mov_b32_e32 v126, v230
	v_mov_b32_e32 v127, v231
	v_mov_b32_e32 v128, v232
	v_mov_b32_e32 v129, v233
	v_pk_mul_f32 v[118:119], v[116:117], v[118:119]
	v_pk_mul_f32 v[122:123], v[128:129], v[122:123]
	v_pk_mul_f32 v[124:125], v[126:127], v[124:125]
	v_pk_mul_f32 v[116:117], v[114:115], v[120:121]
	v_cvt_pk_bf16_f32 v114, v124, v125
	v_cvt_pk_bf16_f32 v115, v122, v123
	v_cvt_pk_bf16_f32 v116, v116, v117
	v_cvt_pk_bf16_f32 v117, v118, v119
	global_store_dwordx4 v[144:145], v[114:117], off offset:64

.LBB0_233:
	s_or_b64 exec, exec, s[2:3]
	s_nop 1
	v_mov_b32_e32 v114, v204
	v_mov_b32_e32 v115, v205
	v_add_u32_e32 v120, 16, v138
	v_ashrrev_i32_e32 v121, 31, v120
	v_ffbh_u32_e32 v0, v115
	v_min_u32_e32 v0, 32, v0
	v_lshlrev_b64 v[114:115], v0, v[114:115]
	v_min_u32_e32 v114, 1, v114
	v_or_b32_e32 v114, v115, v114
	v_cvt_f32_u32_e32 v114, v114
	v_sub_u32_e32 v0, 32, v0
	v_ldexp_f32 v0, v114, v0
	v_fmamk_f32 v0, v0, 0x2e800000, v177
	v_mul_f32_e32 v114, 0x4b800000, v0
	v_cmp_gt_f32_e64 s[44:45], s34, v0
	s_nop 1
	v_cndmask_b32_e64 v0, v0, v114, s[44:45]
	v_rsq_f32_e32 v0, v0
	s_nop 0
	v_mul_f32_e32 v114, 0x45800000, v0
	v_cndmask_b32_e64 v0, v0, v114, s[44:45]
	v_pk_mul_f32 v[116:117], v[112:113], v[0:1] op_sel_hi:[1,0]
	v_pk_mul_f32 v[118:119], v[110:111], v[0:1] op_sel_hi:[1,0]
	v_pk_mul_f32 v[112:113], v[108:109], v[0:1] op_sel_hi:[1,0]
	v_pk_mul_f32 v[114:115], v[106:107], v[0:1] op_sel_hi:[1,0]
	v_pk_mul_f32 v[106:107], v[104:105], v[0:1] op_sel_hi:[1,0]
	v_pk_mul_f32 v[108:109], v[102:103], v[0:1] op_sel_hi:[1,0]
	v_pk_mul_f32 v[102:103], v[100:101], v[0:1] op_sel_hi:[1,0]
	v_pk_mul_f32 v[104:105], v[98:99], v[0:1] op_sel_hi:[1,0]
	s_and_saveexec_b64 s[2:3], s[42:43]
	s_xor_b64 s[2:3], exec, s[2:3]
	s_cbranch_execz .LBB0_235
	v_mov_b32_e32 v122, v119
	v_mov_b32_e32 v123, v115
	v_mov_b32_e32 v110, v118
	v_mov_b32_e32 v111, v114
	v_pk_mul_f32 v[122:123], v[122:123], v[122:123]
	v_mov_b32_e32 v100, v116
	v_mov_b32_e32 v101, v112
	v_pk_fma_f32 v[110:111], v[110:111], v[110:111], v[122:123]
	v_mov_b32_e32 v98, v117
	v_mov_b32_e32 v99, v113
	v_pk_fma_f32 v[100:101], v[100:101], v[100:101], v[110:111]
	v_mov_b32_e32 v124, v105
	v_mov_b32_e32 v125, v109
	v_pk_fma_f32 v[98:99], v[98:99], v[98:99], v[100:101]
	v_mov_b32_e32 v122, v104
	v_mov_b32_e32 v123, v108
	v_pk_mul_f32 v[124:125], v[124:125], v[124:125]
	v_mov_b32_e32 v110, v102
	v_mov_b32_e32 v111, v106
	v_pk_fma_f32 v[122:123], v[122:123], v[122:123], v[124:125]
	v_add_f32_e32 v0, v98, v99
	v_and_b32_e32 v99, 64, v179
	v_mov_b32_e32 v100, v103
	v_mov_b32_e32 v101, v107
	v_pk_fma_f32 v[110:111], v[110:111], v[110:111], v[122:123]
	v_xor_b32_e32 v98, 16, v179
	v_add_u32_e32 v99, 64, v99
	v_pk_fma_f32 v[100:101], v[100:101], v[100:101], v[110:111]
	v_cmp_lt_i32_e64 s[44:45], v98, v99
	v_add_f32_e32 v0, v101, v0
	v_add_f32_e32 v0, v100, v0
	v_cndmask_b32_e64 v98, v179, v98, s[44:45]
	v_lshlrev_b32_e32 v98, 2, v98
	ds_bpermute_b32 v98, v98, v0
	s_waitcnt lgkmcnt(0)
	v_add_f32_e32 v0, v0, v98
	v_xor_b32_e32 v98, 32, v179
	v_cmp_lt_i32_e64 s[44:45], v98, v99
	s_nop 1
	v_cndmask_b32_e64 v98, v179, v98, s[44:45]
	v_lshlrev_b32_e32 v98, 2, v98
	ds_bpermute_b32 v98, v98, v0
	s_waitcnt lgkmcnt(0)
	v_add_f32_e32 v0, v0, v98
	v_fmamk_f32 v0, v0, 0x3c800000, v177
	v_cmp_gt_f32_e64 s[44:45], s34, v0
	v_mul_f32_e32 v98, 0x4b800000, v0
	s_nop 0
	v_cndmask_b32_e64 v0, v0, v98, s[44:45]
	v_rsq_f32_e32 v0, v0
	s_nop 0
	v_mul_f32_e32 v98, 0x45800000, v0
	v_cndmask_b32_e64 v0, v0, v98, s[44:45]
	v_lshlrev_b64 v[98:99], 11, v[120:121]
	v_lshl_add_u64 v[100:101], v[136:137], 0, v[98:99]
	v_lshl_add_u64 v[100:101], v[100:101], 0, s[82:83]
	v_lshl_add_u64 v[98:99], v[134:135], 0, v[98:99]
	v_lshl_add_u64 v[120:121], v[130:131], 2, v[132:133]
	v_cndmask_b32_e32 v111, v99, v101, vcc
	v_cndmask_b32_e32 v110, v98, v100, vcc
	s_nop 1
	v_mov_b32_e32 v98, v226
	v_mov_b32_e32 v99, v227
	v_mov_b32_e32 v100, v228
	v_mov_b32_e32 v101, v229
	s_nop 1
	v_mov_b32_e32 v122, v222
	v_mov_b32_e32 v123, v223
	v_mov_b32_e32 v124, v224
	v_mov_b32_e32 v125, v225
	v_mul_f32_e32 v0, v156, v0
	v_pk_mul_f32 v[118:119], v[118:119], v[0:1] op_sel_hi:[1,0]
	v_pk_mul_f32 v[116:117], v[116:117], v[0:1] op_sel_hi:[1,0]
	v_pk_mul_f32 v[114:115], v[114:115], v[0:1] op_sel_hi:[1,0]
	v_pk_mul_f32 v[112:113], v[112:113], v[0:1] op_sel_hi:[1,0]
	v_pk_mul_f32 v[108:109], v[108:109], v[0:1] op_sel_hi:[1,0]
	v_pk_mul_f32 v[106:107], v[106:107], v[0:1] op_sel_hi:[1,0]
	v_pk_mul_f32 v[104:105], v[104:105], v[0:1] op_sel_hi:[1,0]
	v_pk_mul_f32 v[102:103], v[102:103], v[0:1] op_sel_hi:[1,0]
	v_pk_mul_f32 v[112:113], v[100:101], v[112:113]
	v_pk_mul_f32 v[116:117], v[124:125], v[116:117]
	v_pk_mul_f32 v[118:119], v[122:123], v[118:119]
	v_pk_mul_f32 v[100:101], v[98:99], v[114:115]
	v_cvt_pk_bf16_f32 v98, v118, v119
	v_cvt_pk_bf16_f32 v99, v116, v117
	v_cvt_pk_bf16_f32 v100, v100, v101
	v_cvt_pk_bf16_f32 v101, v112, v113
	v_lshl_add_u64 v[114:115], v[130:131], 1, v[110:111]
	global_store_dwordx4 v[114:115], v[98:101], off
	s_nop 1
	v_mov_b32_e32 v98, v234
	v_mov_b32_e32 v99, v235
	v_mov_b32_e32 v100, v236
	v_mov_b32_e32 v101, v237
	s_nop 0
	s_nop 1
	v_mov_b32_e32 v110, v230
	v_mov_b32_e32 v111, v231
	v_mov_b32_e32 v112, v232
	v_mov_b32_e32 v113, v233
	v_pk_mul_f32 v[102:103], v[100:101], v[102:103]
	v_pk_mul_f32 v[106:107], v[112:113], v[106:107]
	v_pk_mul_f32 v[108:109], v[110:111], v[108:109]
	v_pk_mul_f32 v[100:101], v[98:99], v[104:105]
	v_cvt_pk_bf16_f32 v98, v108, v109
	v_cvt_pk_bf16_f32 v99, v106, v107
	v_cvt_pk_bf16_f32 v100, v100, v101
	v_cvt_pk_bf16_f32 v101, v102, v103
	global_store_dwordx4 v[114:115], v[98:101], off offset:64

.LBB0_237:
	s_or_b64 exec, exec, s[2:3]
	s_nop 1
	v_mov_b32_e32 v98, v206
	v_mov_b32_e32 v99, v207
	v_add_u32_e32 v104, 32, v138
	v_ashrrev_i32_e32 v105, 31, v104
	v_ffbh_u32_e32 v0, v99
	v_min_u32_e32 v0, 32, v0
	v_lshlrev_b64 v[98:99], v0, v[98:99]
	v_min_u32_e32 v98, 1, v98
	v_or_b32_e32 v98, v99, v98
	v_cvt_f32_u32_e32 v98, v98
	v_sub_u32_e32 v0, 32, v0
	v_ldexp_f32 v0, v98, v0
	v_fmamk_f32 v0, v0, 0x2e800000, v177
	v_mul_f32_e32 v98, 0x4b800000, v0
	v_cmp_gt_f32_e64 s[44:45], s34, v0
	s_nop 1
	v_cndmask_b32_e64 v0, v0, v98, s[44:45]
	v_rsq_f32_e32 v0, v0
	s_nop 0
	v_mul_f32_e32 v98, 0x45800000, v0
	v_cndmask_b32_e64 v0, v0, v98, s[44:45]
	v_pk_mul_f32 v[100:101], v[96:97], v[0:1] op_sel_hi:[1,0]
	v_pk_mul_f32 v[102:103], v[94:95], v[0:1] op_sel_hi:[1,0]
	v_pk_mul_f32 v[96:97], v[92:93], v[0:1] op_sel_hi:[1,0]
	v_pk_mul_f32 v[98:99], v[90:91], v[0:1] op_sel_hi:[1,0]
	v_pk_mul_f32 v[90:91], v[88:89], v[0:1] op_sel_hi:[1,0]
	v_pk_mul_f32 v[92:93], v[86:87], v[0:1] op_sel_hi:[1,0]
	v_pk_mul_f32 v[86:87], v[84:85], v[0:1] op_sel_hi:[1,0]
	v_pk_mul_f32 v[88:89], v[82:83], v[0:1] op_sel_hi:[1,0]
	s_and_saveexec_b64 s[2:3], s[42:43]
	s_xor_b64 s[2:3], exec, s[2:3]
	s_cbranch_execz .LBB0_239
	v_mov_b32_e32 v106, v103
	v_mov_b32_e32 v107, v99
	v_mov_b32_e32 v94, v102
	v_mov_b32_e32 v95, v98
	v_pk_mul_f32 v[106:107], v[106:107], v[106:107]
	v_mov_b32_e32 v84, v100
	v_mov_b32_e32 v85, v96
	v_pk_fma_f32 v[94:95], v[94:95], v[94:95], v[106:107]
	v_mov_b32_e32 v82, v101
	v_mov_b32_e32 v83, v97
	v_pk_fma_f32 v[84:85], v[84:85], v[84:85], v[94:95]
	v_mov_b32_e32 v108, v89
	v_mov_b32_e32 v109, v93
	v_pk_fma_f32 v[82:83], v[82:83], v[82:83], v[84:85]
	v_mov_b32_e32 v106, v88
	v_mov_b32_e32 v107, v92
	v_pk_mul_f32 v[108:109], v[108:109], v[108:109]
	v_mov_b32_e32 v94, v86
	v_mov_b32_e32 v95, v90
	v_pk_fma_f32 v[106:107], v[106:107], v[106:107], v[108:109]
	v_add_f32_e32 v0, v82, v83
	v_and_b32_e32 v83, 64, v179
	v_mov_b32_e32 v84, v87
	v_mov_b32_e32 v85, v91
	v_pk_fma_f32 v[94:95], v[94:95], v[94:95], v[106:107]
	v_xor_b32_e32 v82, 16, v179
	v_add_u32_e32 v83, 64, v83
	v_pk_fma_f32 v[84:85], v[84:85], v[84:85], v[94:95]
	v_cmp_lt_i32_e64 s[44:45], v82, v83
	v_add_f32_e32 v0, v85, v0
	v_add_f32_e32 v0, v84, v0
	v_cndmask_b32_e64 v82, v179, v82, s[44:45]
	v_lshlrev_b32_e32 v82, 2, v82
	ds_bpermute_b32 v82, v82, v0
	s_waitcnt lgkmcnt(0)
	v_add_f32_e32 v0, v0, v82
	v_xor_b32_e32 v82, 32, v179
	v_cmp_lt_i32_e64 s[44:45], v82, v83
	s_nop 1
	v_cndmask_b32_e64 v82, v179, v82, s[44:45]
	v_lshlrev_b32_e32 v82, 2, v82
	ds_bpermute_b32 v82, v82, v0
	s_waitcnt lgkmcnt(0)
	v_add_f32_e32 v0, v0, v82
	v_fmamk_f32 v0, v0, 0x3c800000, v177
	v_cmp_gt_f32_e64 s[44:45], s34, v0
	v_mul_f32_e32 v82, 0x4b800000, v0
	s_nop 0
	v_cndmask_b32_e64 v0, v0, v82, s[44:45]
	v_rsq_f32_e32 v0, v0
	s_nop 0
	v_mul_f32_e32 v82, 0x45800000, v0
	v_cndmask_b32_e64 v0, v0, v82, s[44:45]
	v_lshlrev_b64 v[82:83], 11, v[104:105]
	v_lshl_add_u64 v[84:85], v[136:137], 0, v[82:83]
	v_lshl_add_u64 v[84:85], v[84:85], 0, s[82:83]
	v_lshl_add_u64 v[82:83], v[134:135], 0, v[82:83]
	v_lshl_add_u64 v[104:105], v[130:131], 2, v[132:133]
	v_cndmask_b32_e32 v95, v83, v85, vcc
	v_cndmask_b32_e32 v94, v82, v84, vcc
	s_nop 1
	v_mov_b32_e32 v82, v226
	v_mov_b32_e32 v83, v227
	v_mov_b32_e32 v84, v228
	v_mov_b32_e32 v85, v229
	s_nop 1
	v_mov_b32_e32 v106, v222
	v_mov_b32_e32 v107, v223
	v_mov_b32_e32 v108, v224
	v_mov_b32_e32 v109, v225
	v_mul_f32_e32 v0, v156, v0
	v_pk_mul_f32 v[102:103], v[102:103], v[0:1] op_sel_hi:[1,0]
	v_pk_mul_f32 v[100:101], v[100:101], v[0:1] op_sel_hi:[1,0]
	v_pk_mul_f32 v[98:99], v[98:99], v[0:1] op_sel_hi:[1,0]
	v_pk_mul_f32 v[96:97], v[96:97], v[0:1] op_sel_hi:[1,0]
	v_pk_mul_f32 v[92:93], v[92:93], v[0:1] op_sel_hi:[1,0]
	v_pk_mul_f32 v[90:91], v[90:91], v[0:1] op_sel_hi:[1,0]
	v_pk_mul_f32 v[88:89], v[88:89], v[0:1] op_sel_hi:[1,0]
	v_pk_mul_f32 v[86:87], v[86:87], v[0:1] op_sel_hi:[1,0]
	v_pk_mul_f32 v[96:97], v[84:85], v[96:97]
	v_pk_mul_f32 v[100:101], v[108:109], v[100:101]
	v_pk_mul_f32 v[102:103], v[106:107], v[102:103]
	v_pk_mul_f32 v[84:85], v[82:83], v[98:99]
	v_cvt_pk_bf16_f32 v82, v102, v103
	v_cvt_pk_bf16_f32 v83, v100, v101
	v_cvt_pk_bf16_f32 v84, v84, v85
	v_cvt_pk_bf16_f32 v85, v96, v97
	v_lshl_add_u64 v[98:99], v[130:131], 1, v[94:95]
	global_store_dwordx4 v[98:99], v[82:85], off
	s_nop 1
	v_mov_b32_e32 v82, v234
	v_mov_b32_e32 v83, v235
	v_mov_b32_e32 v84, v236
	v_mov_b32_e32 v85, v237
	s_nop 0
	s_nop 1
	v_mov_b32_e32 v94, v230
	v_mov_b32_e32 v95, v231
	v_mov_b32_e32 v96, v232
	v_mov_b32_e32 v97, v233
	v_pk_mul_f32 v[86:87], v[84:85], v[86:87]
	v_pk_mul_f32 v[90:91], v[96:97], v[90:91]
	v_pk_mul_f32 v[92:93], v[94:95], v[92:93]
	v_pk_mul_f32 v[84:85], v[82:83], v[88:89]
	v_cvt_pk_bf16_f32 v82, v92, v93
	v_cvt_pk_bf16_f32 v83, v90, v91
	v_cvt_pk_bf16_f32 v84, v84, v85
	v_cvt_pk_bf16_f32 v85, v86, v87
	global_store_dwordx4 v[98:99], v[82:85], off offset:64

.LBB0_241:
	s_or_b64 exec, exec, s[2:3]
	s_nop 1
	v_mov_b32_e32 v82, v208
	v_mov_b32_e32 v83, v209
	v_add_u32_e32 v88, 48, v138
	v_ashrrev_i32_e32 v89, 31, v88
	v_ffbh_u32_e32 v0, v83
	v_min_u32_e32 v0, 32, v0
	v_lshlrev_b64 v[82:83], v0, v[82:83]
	v_min_u32_e32 v82, 1, v82
	v_or_b32_e32 v82, v83, v82
	v_cvt_f32_u32_e32 v82, v82
	v_sub_u32_e32 v0, 32, v0
	v_ldexp_f32 v0, v82, v0
	v_fmamk_f32 v0, v0, 0x2e800000, v177
	v_mul_f32_e32 v82, 0x4b800000, v0
	v_cmp_gt_f32_e64 s[44:45], s34, v0
	s_nop 1
	v_cndmask_b32_e64 v0, v0, v82, s[44:45]
	v_rsq_f32_e32 v0, v0
	s_nop 0
	v_mul_f32_e32 v82, 0x45800000, v0
	v_cndmask_b32_e64 v0, v0, v82, s[44:45]
	v_pk_mul_f32 v[84:85], v[80:81], v[0:1] op_sel_hi:[1,0]
	v_pk_mul_f32 v[86:87], v[78:79], v[0:1] op_sel_hi:[1,0]
	v_pk_mul_f32 v[80:81], v[76:77], v[0:1] op_sel_hi:[1,0]
	v_pk_mul_f32 v[82:83], v[74:75], v[0:1] op_sel_hi:[1,0]
	v_pk_mul_f32 v[74:75], v[72:73], v[0:1] op_sel_hi:[1,0]
	v_pk_mul_f32 v[76:77], v[70:71], v[0:1] op_sel_hi:[1,0]
	v_pk_mul_f32 v[70:71], v[68:69], v[0:1] op_sel_hi:[1,0]
	v_pk_mul_f32 v[72:73], v[66:67], v[0:1] op_sel_hi:[1,0]
	s_and_saveexec_b64 s[2:3], s[42:43]
	s_xor_b64 s[2:3], exec, s[2:3]
	s_cbranch_execz .LBB0_243
	v_mov_b32_e32 v90, v87
	v_mov_b32_e32 v91, v83
	v_mov_b32_e32 v78, v86
	v_mov_b32_e32 v79, v82
	v_pk_mul_f32 v[90:91], v[90:91], v[90:91]
	v_mov_b32_e32 v68, v84
	v_mov_b32_e32 v69, v80
	v_pk_fma_f32 v[78:79], v[78:79], v[78:79], v[90:91]
	v_mov_b32_e32 v66, v85
	v_mov_b32_e32 v67, v81
	v_pk_fma_f32 v[68:69], v[68:69], v[68:69], v[78:79]
	v_mov_b32_e32 v92, v73
	v_mov_b32_e32 v93, v77
	v_pk_fma_f32 v[66:67], v[66:67], v[66:67], v[68:69]
	v_mov_b32_e32 v90, v72
	v_mov_b32_e32 v91, v76
	v_pk_mul_f32 v[92:93], v[92:93], v[92:93]
	v_mov_b32_e32 v78, v70
	v_mov_b32_e32 v79, v74
	v_pk_fma_f32 v[90:91], v[90:91], v[90:91], v[92:93]
	v_add_f32_e32 v0, v66, v67
	v_and_b32_e32 v67, 64, v179
	v_mov_b32_e32 v68, v71
	v_mov_b32_e32 v69, v75
	v_pk_fma_f32 v[78:79], v[78:79], v[78:79], v[90:91]
	v_xor_b32_e32 v66, 16, v179
	v_add_u32_e32 v67, 64, v67
	v_pk_fma_f32 v[68:69], v[68:69], v[68:69], v[78:79]
	v_cmp_lt_i32_e64 s[44:45], v66, v67
	v_add_f32_e32 v0, v69, v0
	v_add_f32_e32 v0, v68, v0
	v_cndmask_b32_e64 v66, v179, v66, s[44:45]
	v_lshlrev_b32_e32 v66, 2, v66
	ds_bpermute_b32 v66, v66, v0
	s_waitcnt lgkmcnt(0)
	v_add_f32_e32 v0, v0, v66
	v_xor_b32_e32 v66, 32, v179
	v_cmp_lt_i32_e64 s[44:45], v66, v67
	s_nop 1
	v_cndmask_b32_e64 v66, v179, v66, s[44:45]
	v_lshlrev_b32_e32 v66, 2, v66
	ds_bpermute_b32 v66, v66, v0
	s_waitcnt lgkmcnt(0)
	v_add_f32_e32 v0, v0, v66
	v_fmamk_f32 v0, v0, 0x3c800000, v177
	v_cmp_gt_f32_e64 s[44:45], s34, v0
	v_mul_f32_e32 v66, 0x4b800000, v0
	s_nop 0
	v_cndmask_b32_e64 v0, v0, v66, s[44:45]
	v_rsq_f32_e32 v0, v0
	s_nop 0
	v_mul_f32_e32 v66, 0x45800000, v0
	v_cndmask_b32_e64 v0, v0, v66, s[44:45]
	v_lshlrev_b64 v[66:67], 11, v[88:89]
	v_lshl_add_u64 v[68:69], v[136:137], 0, v[66:67]
	v_lshl_add_u64 v[68:69], v[68:69], 0, s[82:83]
	v_lshl_add_u64 v[66:67], v[134:135], 0, v[66:67]
	v_lshl_add_u64 v[88:89], v[130:131], 2, v[132:133]
	v_cndmask_b32_e32 v79, v67, v69, vcc
	v_cndmask_b32_e32 v78, v66, v68, vcc
	s_nop 1
	v_mov_b32_e32 v66, v226
	v_mov_b32_e32 v67, v227
	v_mov_b32_e32 v68, v228
	v_mov_b32_e32 v69, v229
	s_nop 1
	v_mov_b32_e32 v90, v222
	v_mov_b32_e32 v91, v223
	v_mov_b32_e32 v92, v224
	v_mov_b32_e32 v93, v225
	v_mul_f32_e32 v0, v156, v0
	v_pk_mul_f32 v[86:87], v[86:87], v[0:1] op_sel_hi:[1,0]
	v_pk_mul_f32 v[84:85], v[84:85], v[0:1] op_sel_hi:[1,0]
	v_pk_mul_f32 v[82:83], v[82:83], v[0:1] op_sel_hi:[1,0]
	v_pk_mul_f32 v[80:81], v[80:81], v[0:1] op_sel_hi:[1,0]
	v_pk_mul_f32 v[76:77], v[76:77], v[0:1] op_sel_hi:[1,0]
	v_pk_mul_f32 v[74:75], v[74:75], v[0:1] op_sel_hi:[1,0]
	v_pk_mul_f32 v[72:73], v[72:73], v[0:1] op_sel_hi:[1,0]
	v_pk_mul_f32 v[70:71], v[70:71], v[0:1] op_sel_hi:[1,0]
	v_pk_mul_f32 v[80:81], v[68:69], v[80:81]
	v_pk_mul_f32 v[84:85], v[92:93], v[84:85]
	v_pk_mul_f32 v[86:87], v[90:91], v[86:87]
	v_pk_mul_f32 v[68:69], v[66:67], v[82:83]
	v_cvt_pk_bf16_f32 v66, v86, v87
	v_cvt_pk_bf16_f32 v67, v84, v85
	v_cvt_pk_bf16_f32 v68, v68, v69
	v_cvt_pk_bf16_f32 v69, v80, v81
	v_lshl_add_u64 v[82:83], v[130:131], 1, v[78:79]
	global_store_dwordx4 v[82:83], v[66:69], off
	s_nop 1
	v_mov_b32_e32 v66, v234
	v_mov_b32_e32 v67, v235
	v_mov_b32_e32 v68, v236
	v_mov_b32_e32 v69, v237
	s_nop 0
	s_nop 1
	v_mov_b32_e32 v78, v230
	v_mov_b32_e32 v79, v231
	v_mov_b32_e32 v80, v232
	v_mov_b32_e32 v81, v233
	v_pk_mul_f32 v[70:71], v[68:69], v[70:71]
	v_pk_mul_f32 v[74:75], v[80:81], v[74:75]
	v_pk_mul_f32 v[76:77], v[78:79], v[76:77]
	v_pk_mul_f32 v[68:69], v[66:67], v[72:73]
	v_cvt_pk_bf16_f32 v66, v76, v77
	v_cvt_pk_bf16_f32 v67, v74, v75
	v_cvt_pk_bf16_f32 v68, v68, v69
	v_cvt_pk_bf16_f32 v69, v70, v71
	global_store_dwordx4 v[82:83], v[66:69], off offset:64

.LBB0_245:
	s_or_b64 exec, exec, s[2:3]
	s_nop 1
	v_mov_b32_e32 v66, v210
	v_mov_b32_e32 v67, v211
	v_add_u32_e32 v72, 64, v138
	v_ashrrev_i32_e32 v73, 31, v72
	v_ffbh_u32_e32 v0, v67
	v_min_u32_e32 v0, 32, v0
	v_lshlrev_b64 v[66:67], v0, v[66:67]
	v_min_u32_e32 v66, 1, v66
	v_or_b32_e32 v66, v67, v66
	v_cvt_f32_u32_e32 v66, v66
	v_sub_u32_e32 v0, 32, v0
	v_ldexp_f32 v0, v66, v0
	v_fmamk_f32 v0, v0, 0x2e800000, v177
	v_mul_f32_e32 v66, 0x4b800000, v0
	v_cmp_gt_f32_e64 s[44:45], s34, v0
	s_nop 1
	v_cndmask_b32_e64 v0, v0, v66, s[44:45]
	v_rsq_f32_e32 v0, v0
	s_nop 0
	v_mul_f32_e32 v66, 0x45800000, v0
	v_cndmask_b32_e64 v0, v0, v66, s[44:45]
	v_pk_mul_f32 v[68:69], v[64:65], v[0:1] op_sel_hi:[1,0]
	v_pk_mul_f32 v[70:71], v[62:63], v[0:1] op_sel_hi:[1,0]
	v_pk_mul_f32 v[64:65], v[60:61], v[0:1] op_sel_hi:[1,0]
	v_pk_mul_f32 v[66:67], v[58:59], v[0:1] op_sel_hi:[1,0]
	v_pk_mul_f32 v[58:59], v[56:57], v[0:1] op_sel_hi:[1,0]
	v_pk_mul_f32 v[60:61], v[54:55], v[0:1] op_sel_hi:[1,0]
	v_pk_mul_f32 v[54:55], v[52:53], v[0:1] op_sel_hi:[1,0]
	v_pk_mul_f32 v[56:57], v[50:51], v[0:1] op_sel_hi:[1,0]
	s_and_saveexec_b64 s[2:3], s[42:43]
	s_xor_b64 s[2:3], exec, s[2:3]
	s_cbranch_execz .LBB0_247
	v_mov_b32_e32 v74, v71
	v_mov_b32_e32 v75, v67
	v_mov_b32_e32 v62, v70
	v_mov_b32_e32 v63, v66
	v_pk_mul_f32 v[74:75], v[74:75], v[74:75]
	v_mov_b32_e32 v52, v68
	v_mov_b32_e32 v53, v64
	v_pk_fma_f32 v[62:63], v[62:63], v[62:63], v[74:75]
	v_mov_b32_e32 v50, v69
	v_mov_b32_e32 v51, v65
	v_pk_fma_f32 v[52:53], v[52:53], v[52:53], v[62:63]
	v_mov_b32_e32 v76, v57
	v_mov_b32_e32 v77, v61
	v_pk_fma_f32 v[50:51], v[50:51], v[50:51], v[52:53]
	v_mov_b32_e32 v74, v56
	v_mov_b32_e32 v75, v60
	v_pk_mul_f32 v[76:77], v[76:77], v[76:77]
	v_mov_b32_e32 v62, v54
	v_mov_b32_e32 v63, v58
	v_pk_fma_f32 v[74:75], v[74:75], v[74:75], v[76:77]
	v_add_f32_e32 v0, v50, v51
	v_and_b32_e32 v51, 64, v179
	v_mov_b32_e32 v52, v55
	v_mov_b32_e32 v53, v59
	v_pk_fma_f32 v[62:63], v[62:63], v[62:63], v[74:75]
	v_xor_b32_e32 v50, 16, v179
	v_add_u32_e32 v51, 64, v51
	v_pk_fma_f32 v[52:53], v[52:53], v[52:53], v[62:63]
	v_cmp_lt_i32_e64 s[44:45], v50, v51
	v_add_f32_e32 v0, v53, v0
	v_add_f32_e32 v0, v52, v0
	v_cndmask_b32_e64 v50, v179, v50, s[44:45]
	v_lshlrev_b32_e32 v50, 2, v50
	ds_bpermute_b32 v50, v50, v0
	s_waitcnt lgkmcnt(0)
	v_add_f32_e32 v0, v0, v50
	v_xor_b32_e32 v50, 32, v179
	v_cmp_lt_i32_e64 s[44:45], v50, v51
	s_nop 1
	v_cndmask_b32_e64 v50, v179, v50, s[44:45]
	v_lshlrev_b32_e32 v50, 2, v50
	ds_bpermute_b32 v50, v50, v0
	s_waitcnt lgkmcnt(0)
	v_add_f32_e32 v0, v0, v50
	v_fmamk_f32 v0, v0, 0x3c800000, v177
	v_cmp_gt_f32_e64 s[44:45], s34, v0
	v_mul_f32_e32 v50, 0x4b800000, v0
	s_nop 0
	v_cndmask_b32_e64 v0, v0, v50, s[44:45]
	v_rsq_f32_e32 v0, v0
	s_nop 0
	v_mul_f32_e32 v50, 0x45800000, v0
	v_cndmask_b32_e64 v0, v0, v50, s[44:45]
	v_lshlrev_b64 v[50:51], 11, v[72:73]
	v_lshl_add_u64 v[52:53], v[136:137], 0, v[50:51]
	v_lshl_add_u64 v[52:53], v[52:53], 0, s[82:83]
	v_lshl_add_u64 v[50:51], v[134:135], 0, v[50:51]
	v_lshl_add_u64 v[72:73], v[130:131], 2, v[132:133]
	v_cndmask_b32_e32 v63, v51, v53, vcc
	v_cndmask_b32_e32 v62, v50, v52, vcc
	s_nop 1
	v_mov_b32_e32 v50, v226
	v_mov_b32_e32 v51, v227
	v_mov_b32_e32 v52, v228
	v_mov_b32_e32 v53, v229
	s_nop 1
	v_mov_b32_e32 v74, v222
	v_mov_b32_e32 v75, v223
	v_mov_b32_e32 v76, v224
	v_mov_b32_e32 v77, v225
	v_mul_f32_e32 v0, v156, v0
	v_pk_mul_f32 v[70:71], v[70:71], v[0:1] op_sel_hi:[1,0]
	v_pk_mul_f32 v[68:69], v[68:69], v[0:1] op_sel_hi:[1,0]
	v_pk_mul_f32 v[66:67], v[66:67], v[0:1] op_sel_hi:[1,0]
	v_pk_mul_f32 v[64:65], v[64:65], v[0:1] op_sel_hi:[1,0]
	v_pk_mul_f32 v[60:61], v[60:61], v[0:1] op_sel_hi:[1,0]
	v_pk_mul_f32 v[58:59], v[58:59], v[0:1] op_sel_hi:[1,0]
	v_pk_mul_f32 v[56:57], v[56:57], v[0:1] op_sel_hi:[1,0]
	v_pk_mul_f32 v[54:55], v[54:55], v[0:1] op_sel_hi:[1,0]
	v_pk_mul_f32 v[64:65], v[52:53], v[64:65]
	v_pk_mul_f32 v[68:69], v[76:77], v[68:69]
	v_pk_mul_f32 v[70:71], v[74:75], v[70:71]
	v_pk_mul_f32 v[52:53], v[50:51], v[66:67]
	v_cvt_pk_bf16_f32 v50, v70, v71
	v_cvt_pk_bf16_f32 v51, v68, v69
	v_cvt_pk_bf16_f32 v52, v52, v53
	v_cvt_pk_bf16_f32 v53, v64, v65
	v_lshl_add_u64 v[66:67], v[130:131], 1, v[62:63]
	global_store_dwordx4 v[66:67], v[50:53], off
	s_nop 1
	v_mov_b32_e32 v50, v234
	v_mov_b32_e32 v51, v235
	v_mov_b32_e32 v52, v236
	v_mov_b32_e32 v53, v237
	s_nop 0
	s_nop 1
	v_mov_b32_e32 v62, v230
	v_mov_b32_e32 v63, v231
	v_mov_b32_e32 v64, v232
	v_mov_b32_e32 v65, v233
	v_pk_mul_f32 v[54:55], v[52:53], v[54:55]
	v_pk_mul_f32 v[58:59], v[64:65], v[58:59]
	v_pk_mul_f32 v[60:61], v[62:63], v[60:61]
	v_pk_mul_f32 v[52:53], v[50:51], v[56:57]
	v_cvt_pk_bf16_f32 v50, v60, v61
	v_cvt_pk_bf16_f32 v51, v58, v59
	v_cvt_pk_bf16_f32 v52, v52, v53
	v_cvt_pk_bf16_f32 v53, v54, v55
	global_store_dwordx4 v[66:67], v[50:53], off offset:64

.LBB0_249:
	s_or_b64 exec, exec, s[2:3]
	s_nop 1
	v_mov_b32_e32 v50, v212
	v_mov_b32_e32 v51, v213
	v_add_u32_e32 v56, 0x50, v138
	v_ashrrev_i32_e32 v57, 31, v56
	v_ffbh_u32_e32 v0, v51
	v_min_u32_e32 v0, 32, v0
	v_lshlrev_b64 v[50:51], v0, v[50:51]
	v_min_u32_e32 v50, 1, v50
	v_or_b32_e32 v50, v51, v50
	v_cvt_f32_u32_e32 v50, v50
	v_sub_u32_e32 v0, 32, v0
	v_ldexp_f32 v0, v50, v0
	v_fmamk_f32 v0, v0, 0x2e800000, v177
	v_mul_f32_e32 v50, 0x4b800000, v0
	v_cmp_gt_f32_e64 s[44:45], s34, v0
	s_nop 1
	v_cndmask_b32_e64 v0, v0, v50, s[44:45]
	v_rsq_f32_e32 v0, v0
	s_nop 0
	v_mul_f32_e32 v50, 0x45800000, v0
	v_cndmask_b32_e64 v0, v0, v50, s[44:45]
	v_pk_mul_f32 v[52:53], v[48:49], v[0:1] op_sel_hi:[1,0]
	v_pk_mul_f32 v[54:55], v[46:47], v[0:1] op_sel_hi:[1,0]
	v_pk_mul_f32 v[48:49], v[44:45], v[0:1] op_sel_hi:[1,0]
	v_pk_mul_f32 v[50:51], v[42:43], v[0:1] op_sel_hi:[1,0]
	v_pk_mul_f32 v[42:43], v[40:41], v[0:1] op_sel_hi:[1,0]
	v_pk_mul_f32 v[44:45], v[38:39], v[0:1] op_sel_hi:[1,0]
	v_pk_mul_f32 v[38:39], v[36:37], v[0:1] op_sel_hi:[1,0]
	v_pk_mul_f32 v[40:41], v[34:35], v[0:1] op_sel_hi:[1,0]
	s_and_saveexec_b64 s[2:3], s[42:43]
	s_xor_b64 s[2:3], exec, s[2:3]
	s_cbranch_execz .LBB0_251
	v_mov_b32_e32 v58, v55
	v_mov_b32_e32 v59, v51
	v_mov_b32_e32 v46, v54
	v_mov_b32_e32 v47, v50
	v_pk_mul_f32 v[58:59], v[58:59], v[58:59]
	v_mov_b32_e32 v36, v52
	v_mov_b32_e32 v37, v48
	v_pk_fma_f32 v[46:47], v[46:47], v[46:47], v[58:59]
	v_mov_b32_e32 v34, v53
	v_mov_b32_e32 v35, v49
	v_pk_fma_f32 v[36:37], v[36:37], v[36:37], v[46:47]
	v_mov_b32_e32 v60, v41
	v_mov_b32_e32 v61, v45
	v_pk_fma_f32 v[34:35], v[34:35], v[34:35], v[36:37]
	v_mov_b32_e32 v58, v40
	v_mov_b32_e32 v59, v44
	v_pk_mul_f32 v[60:61], v[60:61], v[60:61]
	v_mov_b32_e32 v46, v38
	v_mov_b32_e32 v47, v42
	v_pk_fma_f32 v[58:59], v[58:59], v[58:59], v[60:61]
	v_add_f32_e32 v0, v34, v35
	v_and_b32_e32 v35, 64, v179
	v_mov_b32_e32 v36, v39
	v_mov_b32_e32 v37, v43
	v_pk_fma_f32 v[46:47], v[46:47], v[46:47], v[58:59]
	v_xor_b32_e32 v34, 16, v179
	v_add_u32_e32 v35, 64, v35
	v_pk_fma_f32 v[36:37], v[36:37], v[36:37], v[46:47]
	v_cmp_lt_i32_e64 s[44:45], v34, v35
	v_add_f32_e32 v0, v37, v0
	v_add_f32_e32 v0, v36, v0
	v_cndmask_b32_e64 v34, v179, v34, s[44:45]
	v_lshlrev_b32_e32 v34, 2, v34
	ds_bpermute_b32 v34, v34, v0
	s_waitcnt lgkmcnt(0)
	v_add_f32_e32 v0, v0, v34
	v_xor_b32_e32 v34, 32, v179
	v_cmp_lt_i32_e64 s[44:45], v34, v35
	s_nop 1
	v_cndmask_b32_e64 v34, v179, v34, s[44:45]
	v_lshlrev_b32_e32 v34, 2, v34
	ds_bpermute_b32 v34, v34, v0
	s_waitcnt lgkmcnt(0)
	v_add_f32_e32 v0, v0, v34
	v_fmamk_f32 v0, v0, 0x3c800000, v177
	v_cmp_gt_f32_e64 s[44:45], s34, v0
	v_mul_f32_e32 v34, 0x4b800000, v0
	s_nop 0
	v_cndmask_b32_e64 v0, v0, v34, s[44:45]
	v_rsq_f32_e32 v0, v0
	s_nop 0
	v_mul_f32_e32 v34, 0x45800000, v0
	v_cndmask_b32_e64 v0, v0, v34, s[44:45]
	v_lshlrev_b64 v[34:35], 11, v[56:57]
	v_lshl_add_u64 v[36:37], v[136:137], 0, v[34:35]
	v_lshl_add_u64 v[36:37], v[36:37], 0, s[82:83]
	v_lshl_add_u64 v[34:35], v[134:135], 0, v[34:35]
	v_lshl_add_u64 v[56:57], v[130:131], 2, v[132:133]
	v_cndmask_b32_e32 v47, v35, v37, vcc
	v_cndmask_b32_e32 v46, v34, v36, vcc
	s_nop 1
	v_mov_b32_e32 v34, v226
	v_mov_b32_e32 v35, v227
	v_mov_b32_e32 v36, v228
	v_mov_b32_e32 v37, v229
	s_nop 1
	v_mov_b32_e32 v58, v222
	v_mov_b32_e32 v59, v223
	v_mov_b32_e32 v60, v224
	v_mov_b32_e32 v61, v225
	v_mul_f32_e32 v0, v156, v0
	v_pk_mul_f32 v[54:55], v[54:55], v[0:1] op_sel_hi:[1,0]
	v_pk_mul_f32 v[52:53], v[52:53], v[0:1] op_sel_hi:[1,0]
	v_pk_mul_f32 v[50:51], v[50:51], v[0:1] op_sel_hi:[1,0]
	v_pk_mul_f32 v[48:49], v[48:49], v[0:1] op_sel_hi:[1,0]
	v_pk_mul_f32 v[44:45], v[44:45], v[0:1] op_sel_hi:[1,0]
	v_pk_mul_f32 v[42:43], v[42:43], v[0:1] op_sel_hi:[1,0]
	v_pk_mul_f32 v[40:41], v[40:41], v[0:1] op_sel_hi:[1,0]
	v_pk_mul_f32 v[38:39], v[38:39], v[0:1] op_sel_hi:[1,0]
	v_pk_mul_f32 v[48:49], v[36:37], v[48:49]
	v_pk_mul_f32 v[52:53], v[60:61], v[52:53]
	v_pk_mul_f32 v[54:55], v[58:59], v[54:55]
	v_pk_mul_f32 v[36:37], v[34:35], v[50:51]
	v_cvt_pk_bf16_f32 v34, v54, v55
	v_cvt_pk_bf16_f32 v35, v52, v53
	v_cvt_pk_bf16_f32 v36, v36, v37
	v_cvt_pk_bf16_f32 v37, v48, v49
	v_lshl_add_u64 v[50:51], v[130:131], 1, v[46:47]
	global_store_dwordx4 v[50:51], v[34:37], off
	s_nop 1
	v_mov_b32_e32 v34, v234
	v_mov_b32_e32 v35, v235
	v_mov_b32_e32 v36, v236
	v_mov_b32_e32 v37, v237
	s_nop 0
	s_nop 1
	v_mov_b32_e32 v46, v230
	v_mov_b32_e32 v47, v231
	v_mov_b32_e32 v48, v232
	v_mov_b32_e32 v49, v233
	v_pk_mul_f32 v[38:39], v[36:37], v[38:39]
	v_pk_mul_f32 v[42:43], v[48:49], v[42:43]
	v_pk_mul_f32 v[44:45], v[46:47], v[44:45]
	v_pk_mul_f32 v[36:37], v[34:35], v[40:41]
	v_cvt_pk_bf16_f32 v34, v44, v45
	v_cvt_pk_bf16_f32 v35, v42, v43
	v_cvt_pk_bf16_f32 v36, v36, v37
	v_cvt_pk_bf16_f32 v37, v38, v39
	global_store_dwordx4 v[50:51], v[34:37], off offset:64

.LBB0_253:
	s_or_b64 exec, exec, s[2:3]
	s_nop 1
	v_mov_b32_e32 v34, v214
	v_mov_b32_e32 v35, v215
	v_add_u32_e32 v40, 0x60, v138
	v_ashrrev_i32_e32 v41, 31, v40
	v_ffbh_u32_e32 v0, v35
	v_min_u32_e32 v0, 32, v0
	v_lshlrev_b64 v[34:35], v0, v[34:35]
	v_min_u32_e32 v34, 1, v34
	v_or_b32_e32 v34, v35, v34
	v_cvt_f32_u32_e32 v34, v34
	v_sub_u32_e32 v0, 32, v0
	v_ldexp_f32 v0, v34, v0
	v_fmamk_f32 v0, v0, 0x2e800000, v177
	v_mul_f32_e32 v34, 0x4b800000, v0
	v_cmp_gt_f32_e64 s[44:45], s34, v0
	s_nop 1
	v_cndmask_b32_e64 v0, v0, v34, s[44:45]
	v_rsq_f32_e32 v0, v0
	s_nop 0
	v_mul_f32_e32 v34, 0x45800000, v0
	v_cndmask_b32_e64 v0, v0, v34, s[44:45]
	v_pk_mul_f32 v[36:37], v[32:33], v[0:1] op_sel_hi:[1,0]
	v_pk_mul_f32 v[38:39], v[30:31], v[0:1] op_sel_hi:[1,0]
	v_pk_mul_f32 v[32:33], v[28:29], v[0:1] op_sel_hi:[1,0]
	v_pk_mul_f32 v[34:35], v[26:27], v[0:1] op_sel_hi:[1,0]
	v_pk_mul_f32 v[26:27], v[24:25], v[0:1] op_sel_hi:[1,0]
	v_pk_mul_f32 v[28:29], v[22:23], v[0:1] op_sel_hi:[1,0]
	v_pk_mul_f32 v[22:23], v[20:21], v[0:1] op_sel_hi:[1,0]
	v_pk_mul_f32 v[24:25], v[18:19], v[0:1] op_sel_hi:[1,0]
	s_and_saveexec_b64 s[2:3], s[42:43]
	s_xor_b64 s[2:3], exec, s[2:3]
	s_cbranch_execz .LBB0_255
	v_mov_b32_e32 v42, v39
	v_mov_b32_e32 v43, v35
	v_mov_b32_e32 v30, v38
	v_mov_b32_e32 v31, v34
	v_pk_mul_f32 v[42:43], v[42:43], v[42:43]
	v_mov_b32_e32 v20, v36
	v_mov_b32_e32 v21, v32
	v_pk_fma_f32 v[30:31], v[30:31], v[30:31], v[42:43]
	v_mov_b32_e32 v18, v37
	v_mov_b32_e32 v19, v33
	v_pk_fma_f32 v[20:21], v[20:21], v[20:21], v[30:31]
	v_mov_b32_e32 v44, v25
	v_mov_b32_e32 v45, v29
	v_pk_fma_f32 v[18:19], v[18:19], v[18:19], v[20:21]
	v_mov_b32_e32 v42, v24
	v_mov_b32_e32 v43, v28
	v_pk_mul_f32 v[44:45], v[44:45], v[44:45]
	v_mov_b32_e32 v30, v22
	v_mov_b32_e32 v31, v26
	v_pk_fma_f32 v[42:43], v[42:43], v[42:43], v[44:45]
	v_add_f32_e32 v0, v18, v19
	v_and_b32_e32 v19, 64, v179
	v_mov_b32_e32 v20, v23
	v_mov_b32_e32 v21, v27
	v_pk_fma_f32 v[30:31], v[30:31], v[30:31], v[42:43]
	v_xor_b32_e32 v18, 16, v179
	v_add_u32_e32 v19, 64, v19
	v_pk_fma_f32 v[20:21], v[20:21], v[20:21], v[30:31]
	v_cmp_lt_i32_e64 s[44:45], v18, v19
	v_add_f32_e32 v0, v21, v0
	v_add_f32_e32 v0, v20, v0
	v_cndmask_b32_e64 v18, v179, v18, s[44:45]
	v_lshlrev_b32_e32 v18, 2, v18
	ds_bpermute_b32 v18, v18, v0
	s_waitcnt lgkmcnt(0)
	v_add_f32_e32 v0, v0, v18
	v_xor_b32_e32 v18, 32, v179
	v_cmp_lt_i32_e64 s[44:45], v18, v19
	s_nop 1
	v_cndmask_b32_e64 v18, v179, v18, s[44:45]
	v_lshlrev_b32_e32 v18, 2, v18
	ds_bpermute_b32 v18, v18, v0
	s_waitcnt lgkmcnt(0)
	v_add_f32_e32 v0, v0, v18
	v_fmamk_f32 v0, v0, 0x3c800000, v177
	v_cmp_gt_f32_e64 s[44:45], s34, v0
	v_mul_f32_e32 v18, 0x4b800000, v0
	s_nop 0
	v_cndmask_b32_e64 v0, v0, v18, s[44:45]
	v_rsq_f32_e32 v0, v0
	s_nop 0
	v_mul_f32_e32 v18, 0x45800000, v0
	v_cndmask_b32_e64 v0, v0, v18, s[44:45]
	v_lshlrev_b64 v[18:19], 11, v[40:41]
	v_lshl_add_u64 v[20:21], v[136:137], 0, v[18:19]
	v_lshl_add_u64 v[20:21], v[20:21], 0, s[82:83]
	v_lshl_add_u64 v[18:19], v[134:135], 0, v[18:19]
	v_lshl_add_u64 v[40:41], v[130:131], 2, v[132:133]
	v_cndmask_b32_e32 v31, v19, v21, vcc
	v_cndmask_b32_e32 v30, v18, v20, vcc
	s_nop 1
	v_mov_b32_e32 v18, v226
	v_mov_b32_e32 v19, v227
	v_mov_b32_e32 v20, v228
	v_mov_b32_e32 v21, v229
	s_nop 1
	v_mov_b32_e32 v42, v222
	v_mov_b32_e32 v43, v223
	v_mov_b32_e32 v44, v224
	v_mov_b32_e32 v45, v225
	v_mul_f32_e32 v0, v156, v0
	v_pk_mul_f32 v[38:39], v[38:39], v[0:1] op_sel_hi:[1,0]
	v_pk_mul_f32 v[36:37], v[36:37], v[0:1] op_sel_hi:[1,0]
	v_pk_mul_f32 v[34:35], v[34:35], v[0:1] op_sel_hi:[1,0]
	v_pk_mul_f32 v[32:33], v[32:33], v[0:1] op_sel_hi:[1,0]
	v_pk_mul_f32 v[28:29], v[28:29], v[0:1] op_sel_hi:[1,0]
	v_pk_mul_f32 v[26:27], v[26:27], v[0:1] op_sel_hi:[1,0]
	v_pk_mul_f32 v[24:25], v[24:25], v[0:1] op_sel_hi:[1,0]
	v_pk_mul_f32 v[22:23], v[22:23], v[0:1] op_sel_hi:[1,0]
	v_pk_mul_f32 v[32:33], v[20:21], v[32:33]
	v_pk_mul_f32 v[36:37], v[44:45], v[36:37]
	v_pk_mul_f32 v[38:39], v[42:43], v[38:39]
	v_pk_mul_f32 v[20:21], v[18:19], v[34:35]
	v_cvt_pk_bf16_f32 v18, v38, v39
	v_cvt_pk_bf16_f32 v19, v36, v37
	v_cvt_pk_bf16_f32 v20, v20, v21
	v_cvt_pk_bf16_f32 v21, v32, v33
	v_lshl_add_u64 v[34:35], v[130:131], 1, v[30:31]
	global_store_dwordx4 v[34:35], v[18:21], off
	s_nop 1
	v_mov_b32_e32 v18, v234
	v_mov_b32_e32 v19, v235
	v_mov_b32_e32 v20, v236
	v_mov_b32_e32 v21, v237
	s_nop 0
	s_nop 1
	v_mov_b32_e32 v30, v230
	v_mov_b32_e32 v31, v231
	v_mov_b32_e32 v32, v232
	v_mov_b32_e32 v33, v233
	v_pk_mul_f32 v[22:23], v[20:21], v[22:23]
	v_pk_mul_f32 v[26:27], v[32:33], v[26:27]
	v_pk_mul_f32 v[28:29], v[30:31], v[28:29]
	v_pk_mul_f32 v[20:21], v[18:19], v[24:25]
	v_cvt_pk_bf16_f32 v18, v28, v29
	v_cvt_pk_bf16_f32 v19, v26, v27
	v_cvt_pk_bf16_f32 v20, v20, v21
	v_cvt_pk_bf16_f32 v21, v22, v23
	global_store_dwordx4 v[34:35], v[18:21], off offset:64

.LBB0_257:
	s_or_b64 exec, exec, s[2:3]
	s_nop 1
	v_mov_b32_e32 v18, v216
	v_mov_b32_e32 v19, v217
	v_add_u32_e32 v24, 0x70, v138
	v_ashrrev_i32_e32 v25, 31, v24
	v_ffbh_u32_e32 v0, v19
	v_min_u32_e32 v0, 32, v0
	v_lshlrev_b64 v[18:19], v0, v[18:19]
	v_min_u32_e32 v18, 1, v18
	v_or_b32_e32 v18, v19, v18
	v_cvt_f32_u32_e32 v18, v18
	v_sub_u32_e32 v0, 32, v0
	v_ldexp_f32 v0, v18, v0
	v_fmamk_f32 v0, v0, 0x2e800000, v177
	v_cmp_gt_f32_e64 s[44:45], s34, v0
	v_mul_f32_e32 v18, 0x4b800000, v0
	s_nop 0
	v_cndmask_b32_e64 v0, v0, v18, s[44:45]
	v_rsq_f32_e32 v0, v0
	s_nop 0
	v_mul_f32_e32 v18, 0x45800000, v0
	v_cndmask_b32_e64 v0, v0, v18, s[44:45]
	v_pk_mul_f32 v[20:21], v[16:17], v[0:1] op_sel_hi:[1,0]
	v_pk_mul_f32 v[22:23], v[14:15], v[0:1] op_sel_hi:[1,0]
	v_pk_mul_f32 v[16:17], v[12:13], v[0:1] op_sel_hi:[1,0]
	v_pk_mul_f32 v[18:19], v[10:11], v[0:1] op_sel_hi:[1,0]
	v_pk_mul_f32 v[10:11], v[8:9], v[0:1] op_sel_hi:[1,0]
	v_pk_mul_f32 v[12:13], v[6:7], v[0:1] op_sel_hi:[1,0]
	v_pk_mul_f32 v[6:7], v[4:5], v[0:1] op_sel_hi:[1,0]
	v_pk_mul_f32 v[8:9], v[2:3], v[0:1] op_sel_hi:[1,0]
	s_and_saveexec_b64 s[2:3], s[42:43]
	s_xor_b64 s[2:3], exec, s[2:3]
	s_cbranch_execz .LBB0_259
	v_mov_b32_e32 v26, v23
	v_mov_b32_e32 v27, v19
	v_mov_b32_e32 v14, v22
	v_mov_b32_e32 v15, v18
	v_pk_mul_f32 v[26:27], v[26:27], v[26:27]
	v_mov_b32_e32 v4, v20
	v_mov_b32_e32 v5, v16
	v_pk_fma_f32 v[14:15], v[14:15], v[14:15], v[26:27]
	v_mov_b32_e32 v2, v21
	v_mov_b32_e32 v3, v17
	v_pk_fma_f32 v[4:5], v[4:5], v[4:5], v[14:15]
	v_mov_b32_e32 v28, v9
	v_mov_b32_e32 v29, v13
	v_pk_fma_f32 v[2:3], v[2:3], v[2:3], v[4:5]
	v_mov_b32_e32 v26, v8
	v_mov_b32_e32 v27, v12
	v_pk_mul_f32 v[28:29], v[28:29], v[28:29]
	v_mov_b32_e32 v14, v6
	v_mov_b32_e32 v15, v10
	v_pk_fma_f32 v[26:27], v[26:27], v[26:27], v[28:29]
	v_add_f32_e32 v0, v2, v3
	v_and_b32_e32 v3, 64, v179
	v_mov_b32_e32 v4, v7
	v_mov_b32_e32 v5, v11
	v_pk_fma_f32 v[14:15], v[14:15], v[14:15], v[26:27]
	v_xor_b32_e32 v2, 16, v179
	v_add_u32_e32 v3, 64, v3
	v_pk_fma_f32 v[4:5], v[4:5], v[4:5], v[14:15]
	v_cmp_lt_i32_e64 s[42:43], v2, v3
	v_add_f32_e32 v0, v5, v0
	v_add_f32_e32 v0, v4, v0
	v_cndmask_b32_e64 v2, v179, v2, s[42:43]
	v_lshlrev_b32_e32 v2, 2, v2
	ds_bpermute_b32 v2, v2, v0
	s_waitcnt lgkmcnt(0)
	v_add_f32_e32 v0, v0, v2
	v_xor_b32_e32 v2, 32, v179
	v_cmp_lt_i32_e64 s[42:43], v2, v3
	s_nop 1
	v_cndmask_b32_e64 v2, v179, v2, s[42:43]
	v_lshlrev_b32_e32 v2, 2, v2
	ds_bpermute_b32 v2, v2, v0
	s_waitcnt lgkmcnt(0)
	v_add_f32_e32 v0, v0, v2
	v_fmamk_f32 v0, v0, 0x3c800000, v177
	v_cmp_gt_f32_e64 s[42:43], s34, v0
	v_mul_f32_e32 v2, 0x4b800000, v0
	s_nop 0
	v_cndmask_b32_e64 v0, v0, v2, s[42:43]
	v_rsq_f32_e32 v0, v0
	s_nop 0
	v_mul_f32_e32 v2, 0x45800000, v0
	v_cndmask_b32_e64 v0, v0, v2, s[42:43]
	v_lshlrev_b64 v[2:3], 11, v[24:25]
	v_lshl_add_u64 v[4:5], v[136:137], 0, v[2:3]
	v_lshl_add_u64 v[4:5], v[4:5], 0, s[82:83]
	v_lshl_add_u64 v[2:3], v[134:135], 0, v[2:3]
	v_lshl_add_u64 v[24:25], v[130:131], 2, v[132:133]
	v_cndmask_b32_e32 v15, v3, v5, vcc
	v_cndmask_b32_e32 v14, v2, v4, vcc
	s_nop 1
	v_mov_b32_e32 v2, v226
	v_mov_b32_e32 v3, v227
	v_mov_b32_e32 v4, v228
	v_mov_b32_e32 v5, v229
	s_nop 1
	v_mov_b32_e32 v26, v222
	v_mov_b32_e32 v27, v223
	v_mov_b32_e32 v28, v224
	v_mov_b32_e32 v29, v225
	v_mul_f32_e32 v0, v156, v0
	v_pk_mul_f32 v[22:23], v[22:23], v[0:1] op_sel_hi:[1,0]
	v_pk_mul_f32 v[20:21], v[20:21], v[0:1] op_sel_hi:[1,0]
	v_pk_mul_f32 v[18:19], v[18:19], v[0:1] op_sel_hi:[1,0]
	v_pk_mul_f32 v[16:17], v[16:17], v[0:1] op_sel_hi:[1,0]
	v_pk_mul_f32 v[12:13], v[12:13], v[0:1] op_sel_hi:[1,0]
	v_pk_mul_f32 v[10:11], v[10:11], v[0:1] op_sel_hi:[1,0]
	v_pk_mul_f32 v[8:9], v[8:9], v[0:1] op_sel_hi:[1,0]
	v_pk_mul_f32 v[6:7], v[6:7], v[0:1] op_sel_hi:[1,0]
	v_pk_mul_f32 v[16:17], v[4:5], v[16:17]
	v_pk_mul_f32 v[20:21], v[28:29], v[20:21]
	v_pk_mul_f32 v[22:23], v[26:27], v[22:23]
	v_pk_mul_f32 v[4:5], v[2:3], v[18:19]
	v_cvt_pk_bf16_f32 v2, v22, v23
	v_cvt_pk_bf16_f32 v3, v20, v21
	v_cvt_pk_bf16_f32 v4, v4, v5
	v_cvt_pk_bf16_f32 v5, v16, v17
	v_lshl_add_u64 v[18:19], v[130:131], 1, v[14:15]
	global_store_dwordx4 v[18:19], v[2:5], off
	s_nop 1
	v_mov_b32_e32 v2, v234
	v_mov_b32_e32 v3, v235
	v_mov_b32_e32 v4, v236
	v_mov_b32_e32 v5, v237
	s_nop 0
	s_nop 1
	v_mov_b32_e32 v14, v230
	v_mov_b32_e32 v15, v231
	v_mov_b32_e32 v16, v232
	v_mov_b32_e32 v17, v233
	v_pk_mul_f32 v[6:7], v[4:5], v[6:7]
	v_pk_mul_f32 v[10:11], v[16:17], v[10:11]
	v_pk_mul_f32 v[12:13], v[14:15], v[12:13]
	v_pk_mul_f32 v[4:5], v[2:3], v[8:9]
	v_cvt_pk_bf16_f32 v2, v12, v13
	v_cvt_pk_bf16_f32 v3, v10, v11
	v_cvt_pk_bf16_f32 v4, v4, v5
	v_cvt_pk_bf16_f32 v5, v6, v7
	global_store_dwordx4 v[18:19], v[2:5], off offset:64

.LBB0_279:
	s_mov_b32 s10, s100
	v_and_b32_e32 v25, 63, v0
	s_waitcnt vmcnt(5)
	v_mul_f32_e32 v4, v10, v15
	v_ashrrev_i32_e32 v10, 3, v0
	v_lshlrev_b32_e32 v0, 3, v0
	s_add_u32 s6, s46, 0x2700000
	v_and_b32_e32 v0, 56, v0
	s_movk_i32 s8, 0x104
	v_mul_f32_e32 v2, v6, v8
	s_waitcnt vmcnt(4)
	v_mul_f32_e32 v5, v16, v14
	s_waitcnt vmcnt(3)
	v_mul_f32_e32 v6, v17, v19
	s_addc_u32 s7, s47, 0
	v_lshl_add_u32 v14, v25, 2, 0
	v_lshl_add_u32 v15, v10, 2, 0
	v_mul_u32_u24_e32 v16, 0x104, v0
	v_mul_lo_u32 v17, v12, s8
	s_waitcnt lgkmcnt(0)
	s_lshl_b32 s11, s10, 6
	v_mul_f32_e32 v3, v9, v7
	s_waitcnt vmcnt(2)
	v_mul_f32_e32 v7, v20, v18
	s_waitcnt vmcnt(1)
	v_mul_f32_e32 v8, v22, v23
	s_waitcnt vmcnt(0)
	v_mul_f32_e32 v9, v24, v21
	v_or_b32_e32 v11, v11, v13
	v_add_u32_e32 v12, s11, v12
	v_add_u32_e32 v13, v14, v17
	v_add_u32_e32 v14, v15, v16
	v_lshlrev_b32_e32 v0, 1, v0
	v_readlane_b32 s12, v250, 45
	s_mov_b32 s15, s14
	s_branch .LBB0_282

.LBB0_304:
	s_or_b64 exec, exec, s[18:19]
	s_mov_b32 s18, s100
	s_waitcnt lgkmcnt(0)
	s_add_i32 s15, s18, s15
	s_cmpk_lt_i32 s15, 0x200
	s_cbranch_scc0 .LBB0_327

.LBB0_327:
	s_lshl_b64 s[2:3], s[6:7], 3
	v_readlane_b32 s4, v251, 0
	v_readlane_b32 s5, v251, 1
	s_add_u32 s4, s4, s2
	s_addc_u32 s5, s5, s3
	s_add_i32 s8, s50, 1
	s_and_b64 s[2:3], s[0:1], exec
	s_cselect_b32 s88, 0, s8
	s_cmp_eq_u32 s88, 0
	s_cselect_b64 s[40:41], -1, 0
	s_cmp_lg_u32 s88, 0
	s_cbranch_scc1 .LBB0_337
	v_mov_b32_e32 v0, v176
	v_readlane_b32 s8, v251, 23
	s_add_u32 s2, s66, 0x2a20000
	s_addc_u32 s3, s67, 0
	v_add_u32_e32 v2, s8, v0
	s_mov_b32 s8, 0x60000
	v_cmp_gt_i32_e32 vcc, s8, v2
	s_and_saveexec_b64 s[8:9], vcc
	s_cbranch_execz .LBB0_331
	s_mov_b32 s10, s100
	s_waitcnt lgkmcnt(0)
	s_lshl_b32 s12, s10, 9
	s_mov_b64 s[10:11], 0

.LBB0_331:
	s_or_b64 exec, exec, s[8:9]
	v_ashrrev_i32_e32 v2, 6, v0
	v_readlane_b32 s8, v251, 24
	s_nop 1
	v_add_u32_e32 v2, s8, v2
	s_mov_b32 s8, 0x8000
	v_cmp_gt_i32_e32 vcc, s8, v2
	s_and_saveexec_b64 s[8:9], vcc
	s_cbranch_execz .LBB0_336
	s_load_dwordx2 s[10:11], s[4:5], 0x0
	v_and_b32_e32 v3, 63, v0
	v_lshlrev_b32_e32 v0, 5, v3
	v_cmp_eq_u32_e32 vcc, 0, v3
	s_mov_b32 s12, s100
	s_waitcnt lgkmcnt(0)
	v_lshl_add_u64 v[4:5], s[10:11], 0, v[0:1]
	v_lshlrev_b32_e32 v0, 4, v3
	v_lshl_add_u64 v[6:7], s[66:67], 0, v[0:1]
	v_and_b32_e32 v0, 64, v179
	v_add_u32_e32 v12, 64, v0
	v_xor_b32_e32 v0, 32, v179
	v_cmp_lt_i32_e64 s[42:43], v0, v12
	v_xor_b32_e32 v3, 16, v179
	s_mov_b64 s[10:11], 0x3e00000
	v_cndmask_b32_e64 v0, v179, v0, s[42:43]
	v_cmp_lt_i32_e64 s[42:43], v3, v12
	v_lshl_add_u64 v[6:7], v[6:7], 0, s[10:11]
	s_lshl_b32 s15, s12, 3
	v_cndmask_b32_e64 v3, v179, v3, s[42:43]
	v_lshlrev_b32_e32 v8, 2, v3
	v_xor_b32_e32 v3, 8, v179
	v_cmp_lt_i32_e64 s[42:43], v3, v12
	v_lshlrev_b32_e32 v0, 2, v0
	s_mov_b64 s[10:11], 0
	v_cndmask_b32_e64 v3, v179, v3, s[42:43]
	v_lshlrev_b32_e32 v9, 2, v3
	v_xor_b32_e32 v3, 4, v179
	v_cmp_lt_i32_e64 s[42:43], v3, v12
	s_nop 1
	v_cndmask_b32_e64 v3, v179, v3, s[42:43]
	v_lshlrev_b32_e32 v10, 2, v3
	v_xor_b32_e32 v3, 2, v179
	v_cmp_lt_i32_e64 s[42:43], v3, v12
	s_nop 1
	v_cndmask_b32_e64 v3, v179, v3, s[42:43]
	v_lshlrev_b32_e32 v11, 2, v3
	v_xor_b32_e32 v3, 1, v179
	v_cmp_lt_i32_e64 s[42:43], v3, v12
	s_nop 1
	v_cndmask_b32_e64 v3, v179, v3, s[42:43]
	v_lshlrev_b32_e32 v12, 2, v3
	s_branch .LBB0_334

.LBB0_337:
	v_mov_b32_e32 v6, v176
	v_readlane_b32 s2, v251, 25
	v_writelane_b32 v250, s92, 59
	v_readlane_b32 s3, v251, 26
	v_ashrrev_i32_e32 v7, 31, v6
	v_writelane_b32 v250, s93, 60
	s_mov_b32 s92, s27
	s_mov_b64 s[26:27], s[0:1]
	v_lshl_add_u64 v[2:3], s[2:3], 0, v[6:7]
	s_mov_b64 s[0:1], 0x100000
	s_ashr_i32 s89, s88, 31
	v_cmp_gt_u64_e32 vcc, s[0:1], v[2:3]
	s_and_saveexec_b64 s[2:3], vcc
	s_cbranch_execz .LBB0_349
	s_mov_b32 s86, s100
	v_mov_b32_e32 v5, s87
	s_waitcnt lgkmcnt(0)
	s_lshl_b64 s[8:9], s[86:87], 9
	v_lshl_add_u64 v[8:9], v[2:3], 0, s[8:9]
	v_cmp_gt_u64_e64 s[42:43], s[0:1], v[8:9]
	v_cmp_lt_u64_e32 vcc, s[0:1], v[8:9]
	s_nop 0
	v_cndmask_b32_e64 v4, 0, 1, s[42:43]
	v_cndmask_b32_e32 v0, 0, v9, vcc
	v_cndmask_b32_e32 v10, v188, v8, vcc
	v_lshl_add_u64 v[8:9], v[8:9], 0, v[4:5]
	v_sub_co_u32_e32 v10, vcc, v10, v8
	v_mov_b32_e32 v8, v1
	s_nop 0
	v_subb_co_u32_e32 v11, vcc, v0, v9, vcc
	v_or_b32_e32 v9, s9, v11
	v_cmp_ne_u64_e32 vcc, 0, v[8:9]
	s_and_saveexec_b64 s[10:11], vcc
	s_xor_b64 s[10:11], exec, s[10:11]
	s_cbranch_execz .LBB0_340
	v_cvt_f32_u32_e32 v0, s8
	v_cvt_f32_u32_e32 v8, s9
	s_sub_u32 s15, 0, s8
	s_subb_u32 s16, 0, s9
	v_fmac_f32_e32 v0, 0x4f800000, v8
	v_rcp_f32_e32 v0, v0
	s_nop 0
	v_mul_f32_e32 v0, 0x5f7ffffc, v0
	v_mul_f32_e32 v8, 0x2f800000, v0
	v_trunc_f32_e32 v8, v8
	v_fmac_f32_e32 v0, 0xcf800000, v8
	v_cvt_u32_f32_e32 v8, v8
	v_cvt_u32_f32_e32 v0, v0
	v_readfirstlane_b32 s17, v8
	v_readfirstlane_b32 s12, v0
	s_mul_i32 s13, s15, s17
	s_mul_hi_u32 s19, s15, s12
	s_mul_i32 s18, s16, s12
	s_add_i32 s13, s19, s13
	s_mul_i32 s20, s15, s12
	s_add_i32 s13, s13, s18
	s_mul_i32 s19, s12, s13
	s_mul_hi_u32 s21, s12, s20
	s_mul_hi_u32 s18, s12, s13
	s_add_u32 s19, s21, s19
	s_addc_u32 s18, 0, s18
	s_mul_hi_u32 s22, s17, s20
	s_mul_i32 s20, s17, s20
	s_add_u32 s19, s19, s20
	s_mul_hi_u32 s21, s17, s13
	s_addc_u32 s18, s18, s22
	s_addc_u32 s19, s21, 0
	s_mul_i32 s13, s17, s13
	s_add_u32 s13, s18, s13
	s_addc_u32 s18, 0, s19
	s_add_u32 s19, s12, s13
	s_cselect_b64 s[12:13], -1, 0
	s_cmp_lg_u64 s[12:13], 0
	s_addc_u32 s17, s17, s18
	s_mul_i32 s12, s15, s17
	s_mul_hi_u32 s13, s15, s19
	s_add_i32 s12, s13, s12
	s_mul_i32 s16, s16, s19
	s_add_i32 s12, s12, s16
	s_mul_i32 s15, s15, s19
	s_mul_hi_u32 s16, s17, s15
	s_mul_i32 s18, s17, s15
	s_mul_i32 s21, s19, s12
	s_mul_hi_u32 s15, s19, s15
	s_mul_hi_u32 s20, s19, s12
	s_add_u32 s15, s15, s21
	s_addc_u32 s20, 0, s20
	s_add_u32 s15, s15, s18
	s_mul_hi_u32 s13, s17, s12
	s_addc_u32 s15, s20, s16
	s_addc_u32 s13, s13, 0
	s_mul_i32 s12, s17, s12
	s_add_u32 s12, s15, s12
	s_addc_u32 s15, 0, s13
	s_add_u32 s16, s19, s12
	s_cselect_b64 s[12:13], -1, 0
	s_cmp_lg_u64 s[12:13], 0
	s_addc_u32 s15, s17, s15
	v_mad_u64_u32 v[8:9], s[12:13], v10, s15, 0
	v_mul_hi_u32 v0, v10, s16
	v_lshl_add_u64 v[8:9], v[0:1], 0, v[8:9]
	v_mad_u64_u32 v[14:15], s[12:13], v11, s16, 0
	v_add_co_u32_e32 v0, vcc, v8, v14
	v_mad_u64_u32 v[12:13], s[12:13], v11, s15, 0
	s_nop 0
	v_addc_co_u32_e32 v0, vcc, v9, v15, vcc
	s_nop 1
	v_addc_co_u32_e32 v13, vcc, 0, v13, vcc
	v_lshl_add_u64 v[8:9], v[0:1], 0, v[12:13]
	v_mul_lo_u32 v0, s9, v8
	v_mul_lo_u32 v14, s8, v9
	v_mad_u64_u32 v[12:13], s[12:13], s8, v8, 0
	v_add3_u32 v0, v13, v14, v0
	v_sub_u32_e32 v13, v11, v0
	v_mov_b32_e32 v14, s9
	v_sub_co_u32_e32 v10, vcc, v10, v12
	s_nop 1
	v_subb_co_u32_e64 v12, s[44:45], v13, v14, vcc
	v_subrev_co_u32_e64 v13, s[44:45], s8, v10
	v_subb_co_u32_e32 v0, vcc, v11, v0, vcc
	s_nop 0
	v_subbrev_co_u32_e64 v12, s[44:45], 0, v12, s[44:45]
	v_cmp_le_u32_e64 s[44:45], s9, v12
	v_cmp_le_u32_e32 vcc, s9, v0
	s_nop 0
	v_cndmask_b32_e64 v14, 0, -1, s[44:45]
	v_cmp_le_u32_e64 s[44:45], s8, v13
	v_cndmask_b32_e64 v11, 0, -1, vcc
	v_cmp_le_u32_e32 vcc, s8, v10
	v_cndmask_b32_e64 v13, 0, -1, s[44:45]
	v_cmp_eq_u32_e64 s[44:45], s9, v12
	v_cndmask_b32_e64 v10, 0, -1, vcc
	v_cmp_eq_u32_e32 vcc, s9, v0
	v_cndmask_b32_e64 v16, v14, v13, s[44:45]
	v_lshl_add_u64 v[12:13], v[8:9], 0, 2
	v_lshl_add_u64 v[14:15], v[8:9], 0, 1
	v_cmp_ne_u32_e64 s[44:45], 0, v16
	v_cndmask_b32_e32 v0, v11, v10, vcc
	v_cmp_ne_u32_e32 vcc, 0, v0
	v_cndmask_b32_e64 v13, v15, v13, s[44:45]
	v_cndmask_b32_e64 v0, v14, v12, s[44:45]
	v_cndmask_b32_e32 v9, v9, v13, vcc
	v_cndmask_b32_e32 v8, v8, v0, vcc

.LBB0_361:
	v_writelane_b32 v250, s76, 61
	s_mov_b64 s[82:83], s[72:73]
	s_mov_b64 s[72:73], s[94:95]
	s_mov_b32 s1, s84
	s_mov_b32 s0, s81
	s_mov_b32 s95, s70
	s_andn2_b64 vcc, exec, s[2:3]
	v_writelane_b32 v250, s77, 62
	s_cbranch_vccnz .LBB0_519
	v_readlane_b32 s2, v251, 29
	v_readlane_b32 s3, v251, 30
	v_mov_b32_e32 v28, v176
	s_andn2_b64 vcc, exec, s[2:3]
	s_cbranch_vccnz .LBB0_519
	s_lshl_b64 s[2:3], s[88:89], 16
	s_waitcnt lgkmcnt(0)
	s_load_dwordx8 s[16:23], s[4:5], 0x38
	s_add_u32 s2, s66, s2
	s_addc_u32 s3, s67, s3
	s_add_u32 s6, s2, 0x2d80000
	s_addc_u32 s7, s3, 0
	s_lshl_b64 s[2:3], s[88:89], 18
	s_waitcnt lgkmcnt(0)
	s_add_u32 s96, s16, s2
	s_addc_u32 s97, s17, s3
	s_add_u32 s8, s18, s2
	s_addc_u32 s9, s19, s3
	s_add_u32 s10, s20, s2
	s_addc_u32 s11, s21, s3
	s_add_u32 s12, s22, s2
	s_movk_i32 s2, 0x100
	v_ashrrev_i32_e32 v0, 4, v28
	v_cmp_gt_i32_e64 s[44:45], s2, v28
	v_and_b32_e32 v2, 15, v28
	v_mul_lo_u32 v30, v0, s38
	v_or_b32_e32 v4, -16, v28
	s_movk_i32 s2, 0x1810
	v_or_b32_e32 v38, v30, v2
	v_add3_u32 v80, v4, v30, s2
	s_mov_b32 s2, 0x7ffe9710
	s_mov_b32 s15, s100
	v_cmp_gt_i32_e64 s[46:47], s2, v38
	s_mov_b32 s2, 0x7ffeaf20
	s_addc_u32 s13, s23, s3
	v_add_u32_e32 v78, 0x3000, v38
	v_cmp_gt_i32_e64 s[48:49], s2, v80
	s_mov_b32 s2, 0x7ffec730
	s_add_u32 s65, s66, 0x600000
	v_add_u32_e32 v77, 0x4800, v38
	v_cmp_gt_i32_e64 s[52:53], s2, v78
	s_mov_b32 s2, 0x7ffedf40
	s_addc_u32 s93, s67, 0
	v_add_u32_e32 v42, 0xe0, v38
	v_add_u32_e32 v44, 0x15000, v38
	v_cmp_gt_i32_e64 s[56:57], s2, v77
	s_mov_b32 s2, 0x7fffe7f0
	s_add_u32 s80, s66, 0xa00000
	v_and_b32_e32 v75, 63, v28
	v_add_u32_e32 v40, 0x16800, v38
	v_or_b32_e32 v6, 0xffffffe0, v2
	v_or_b32_e32 v8, 32, v2
	v_or_b32_e32 v10, 0xffffffd0, v2
	v_or_b32_e32 v12, 48, v2
	v_or_b32_e32 v26, 48, v38
	v_or_b32_e32 v19, 32, v38
	v_or_b32_e32 v79, 16, v38
	v_add_u32_e32 v15, 0x150f0, v38
	v_add_u32_e32 v21, 0x138f0, v38
	v_add_u32_e32 v27, 0x120f0, v38
	v_cmp_gt_i32_e64 s[60:61], s2, v44
	v_add_u32_e32 v46, 0x16810, v38
	v_cmp_gt_i32_e64 s[62:63], s2, v42
	v_add_u32_e32 v48, 0x18f0, v38
	v_readlane_b32 s2, v250, 52
	s_addc_u32 s81, s67, 0
	v_cmp_gt_i32_e64 s[42:43], 64, v28
	v_lshl_add_u32 v74, v28, 2, 0
	v_lshl_add_u32 v76, v75, 2, 0
	v_ashrrev_i32_e32 v41, 31, v40
	v_mov_b32_e32 v3, v0
	v_mov_b32_e32 v14, v0
	v_mov_b32_e32 v5, v0
	v_mov_b32_e32 v7, v2
	v_mov_b32_e32 v16, v2
	v_mov_b32_e32 v9, v2
	v_mov_b32_e32 v11, v4
	v_mov_b32_e32 v18, v4
	v_mov_b32_e32 v13, v4
	v_cmp_ge_i32_e64 s[50:51], v15, v79
	v_mov_b32_e32 v15, v6
	v_mov_b32_e32 v20, v6
	v_mov_b32_e32 v17, v6
	v_cmp_ge_i32_e64 s[54:55], v21, v19
	v_mov_b32_e32 v19, v8
	v_mov_b32_e32 v22, v8
	v_mov_b32_e32 v21, v8
	v_mov_b32_e32 v23, v10
	v_mov_b32_e32 v24, v10
	v_mov_b32_e32 v25, v10
	v_cmp_ge_i32_e64 s[58:59], v27, v26
	v_mov_b32_e32 v27, v12
	v_mov_b32_e32 v26, v12
	v_mov_b32_e32 v29, v12
	v_ashrrev_i32_e32 v45, 31, v44
	v_ashrrev_i32_e32 v47, 31, v46
	v_ashrrev_i32_e32 v43, 31, v42
	v_ashrrev_i32_e32 v49, 31, v48
	v_ashrrev_i32_e32 v39, 31, v30
	v_add_u32_e32 v81, s2, v2
	s_waitcnt lgkmcnt(0)
	s_lshl_b32 s76, s15, 10
	v_lshl_add_u32 v82, v0, 6, s2
	v_add_u32_e32 v83, 0x6000, v38
	v_add_u32_e32 v84, 0x7800, v38
	v_add_u32_e32 v85, 0x9000, v38
	v_add_u32_e32 v86, 0xa800, v38
	v_add_u32_e32 v87, 0xc000, v38
	v_add_u32_e32 v88, 0xd800, v38
	v_add_u32_e32 v89, 0xf000, v38
	v_add_u32_e32 v90, 0x10800, v38
	v_add_u32_e32 v91, 0x12000, v38
	v_add_u32_e32 v92, 0x13800, v38
	s_mov_b32 s2, s14

.LBB0_589:
	v_mul_f32_e32 v16, 0x4f7ffffe, v16
	v_cvt_u32_f32_e32 v16, v16
	v_lshlrev_b32_e32 v0, 1, v10
	s_mov_b32 s97, s100
	v_and_b32_e32 v0, 24, v0
	v_lshrrev_b32_e32 v11, 2, v15
	v_lshrrev_b32_e32 v12, 3, v15
	v_lshlrev_b32_e32 v13, 6, v10
	v_and_or_b32 v11, v11, 4, v0
	v_and_b32_e32 v12, 4, v12
	v_and_b32_e32 v13, 0x400, v13
	v_and_or_b32 v0, v15, 3, v0
	s_waitcnt lgkmcnt(0)
	s_cmp_lg_u64 s[44:45], 0
	s_movk_i32 s20, 0x104
	v_or3_b32 v12, v12, v13, v0
	s_cselect_b64 s[62:63], -1, 0
	v_ashrrev_i32_e32 v13, 3, v15
	v_lshlrev_b32_e32 v0, 3, v15
	v_mul_lo_u32 v15, v14, s20
	s_sub_i32 s20, 0, s93
	v_readfirstlane_b32 s21, v16
	s_mul_i32 s20, s20, s21
	v_and_b32_e32 v0, 56, v0
	s_mul_hi_u32 s20, s21, s20
	v_lshl_add_u32 v17, v10, 2, 0
	v_lshl_add_u32 v18, v13, 2, 0
	v_mul_u32_u24_e32 v19, 0x104, v0
	s_add_i32 s70, s21, s20
	s_lshl_b32 s20, s93, 6
	s_lshl_b32 s85, s97, 6
	s_sub_i32 s84, 0, s20
	v_add_u32_e32 v14, s85, v14
	v_add_u32_e32 v15, v17, v15
	v_add_u32_e32 v16, v18, v19
	v_lshlrev_b32_e32 v0, 1, v0
	v_readlane_b32 s29, v250, 45
	s_mov_b32 s69, s14
	s_branch .LBB0_592

.LBB0_629:
	s_or_b64 exec, exec, s[10:11]
	s_mov_b32 s10, s100
	s_waitcnt lgkmcnt(0)
	s_add_i32 s21, s10, s21
	s_cmpk_lt_i32 s21, 0x200
	s_cbranch_scc0 .LBB0_652

	.amdhsa_kernel _Z9yoco_mega6Params
		.amdhsa_group_segment_fixed_size 0
		.amdhsa_private_segment_fixed_size 0
		.amdhsa_kernarg_size 560
		.amdhsa_user_sgpr_count 2
		.amdhsa_user_sgpr_dispatch_ptr 0
		.amdhsa_user_sgpr_queue_ptr 0
		.amdhsa_user_sgpr_kernarg_segment_ptr 1
		.amdhsa_user_sgpr_dispatch_id 0
		.amdhsa_user_sgpr_kernarg_preload_length 0
		.amdhsa_user_sgpr_kernarg_preload_offset 0
		.amdhsa_user_sgpr_private_segment_size 0
		.amdhsa_uses_dynamic_stack 0
		.amdhsa_enable_private_segment 0
		.amdhsa_system_sgpr_workgroup_id_x 1
		.amdhsa_system_sgpr_workgroup_id_y 0
		.amdhsa_system_sgpr_workgroup_id_z 0
		.amdhsa_system_sgpr_workgroup_info 0
		.amdhsa_system_vgpr_workitem_id 2
		.amdhsa_next_free_vgpr 252
		.amdhsa_next_free_sgpr 102
		.amdhsa_accum_offset 252
		.amdhsa_reserve_vcc 1
		.amdhsa_float_round_mode_32 0
		.amdhsa_float_round_mode_16_64 0
		.amdhsa_float_denorm_mode_32 3
		.amdhsa_float_denorm_mode_16_64 3
		.amdhsa_dx10_clamp 1
		.amdhsa_ieee_mode 1
		.amdhsa_fp16_overflow 0
		.amdhsa_tg_split 0
		.amdhsa_exception_fp_ieee_invalid_op 0
		.amdhsa_exception_fp_denorm_src 0
		.amdhsa_exception_fp_ieee_div_zero 0
		.amdhsa_exception_fp_ieee_overflow 0
		.amdhsa_exception_fp_ieee_underflow 0
		.amdhsa_exception_fp_ieee_inexact 0
		.amdhsa_exception_int_div_zero 0
	.end_amdhsa_kernel

amdhsa.kernels:
  - .agpr_count:     0
    .args:
      - .offset:         0
        .size:           304
        .value_kind:     by_value
      - .offset:         304
        .size:           4
        .value_kind:     hidden_block_count_x
      - .offset:         308
        .size:           4
        .value_kind:     hidden_block_count_y
      - .offset:         312
        .size:           4
        .value_kind:     hidden_block_count_z
      - .offset:         316
        .size:           2
        .value_kind:     hidden_group_size_x
      - .offset:         318
        .size:           2
        .value_kind:     hidden_group_size_y
      - .offset:         320
        .size:           2
        .value_kind:     hidden_group_size_z
      - .offset:         322
        .size:           2
        .value_kind:     hidden_remainder_x
      - .offset:         324
        .size:           2
        .value_kind:     hidden_remainder_y
      - .offset:         326
        .size:           2
        .value_kind:     hidden_remainder_z
      - .offset:         344
        .size:           8
        .value_kind:     hidden_global_offset_x
      - .offset:         352
        .size:           8
        .value_kind:     hidden_global_offset_y
      - .offset:         360
        .size:           8
        .value_kind:     hidden_global_offset_z
      - .offset:         368
        .size:           2
        .value_kind:     hidden_grid_dims
      - .offset:         392
        .size:           8
        .value_kind:     hidden_multigrid_sync_arg
      - .offset:         424
        .size:           4
        .value_kind:     hidden_dynamic_lds_size
    .group_segment_fixed_size: 0
    .kernarg_segment_align: 8
    .kernarg_segment_size: 560
    .language:       OpenCL C
    .language_version:
      - 2
      - 0
    .max_flat_workgroup_size: 512
    .name:           _Z9yoco_mega6Params
    .private_segment_fixed_size: 0
    .sgpr_count:     108
    .sgpr_spill_count: 127
    .symbol:         _Z9yoco_mega6Params.kd
    .uniform_work_group_size: 1
    .uses_dynamic_stack: false
    .vgpr_count:     252
    .vgpr_spill_count: 0
    .wavefront_size: 64
